# v64 + vmcnt(8) and lgkmcnt(0) of each K-loop load segment merged into one s_waitcnt
# speedup vs baseline: 1.0002x; 1.0002x over previous
; #define PG8_STAGE(bufoff, gbase, voff) do { _Pragma("unroll") for (int _i = 0; _i < 2; ++_i) \
;         __builtin_amdgcn_global_load_lds((const unsigned*)((const char*)(gbase) + (voff)[_i]), (PG8_LAS unsigned*)(lds + (bufoff) + ldsw + _i * 8192), 16, 0, 0); } while (0)
; #define PG8_LDA(dst, b, h) do { _Pragma("unroll") for (int m = 0; m < 4; ++m) _Pragma("unroll") for (int k = 0; k < 2; ++k) dst[m][k] = *(const PG8_LAS bf16x8*)(lds + PG8_SA(b, h) + aoff + m * 2048 + k * 1024); } while (0)
; #define PG8_LDB(dst, b, h) do { _Pragma("unroll") for (int n = 0; n < 2; ++n) _Pragma("unroll") for (int k = 0; k < 2; ++k) dst[n][k] = *(const PG8_LAS bf16x8*)(lds + PG8_SB(b, h) + boff + n * 2048 + k * 1024); } while (0)
; #define PG8_MMA(ai, bj, At, Bt) do { __builtin_amdgcn_s_setprio(1); _Pragma("unroll") for (int m = 0; m < 4; ++m) _Pragma("unroll") for (int n = 0; n < 2; ++n) _Pragma("unroll") for (int k = 0; k < 2; ++k) \
;         acc[ai][bj][m][n] = __builtin_amdgcn_mfma_f32_16x16x32_bf16(Bt[n][k], At[m][k], acc[ai][bj][m][n], 0, 0, 0); __builtin_amdgcn_s_setprio(0); } while (0)
; #define PG8_WAIT_V(n) asm volatile("s_waitcnt vmcnt(" #n ")" ::: "memory")
; #define PG8_WAIT_L(n) asm volatile("s_waitcnt lgkmcnt(" #n ")" ::: "memory")
; template <class Epi, class Sched, bool ALIGN_EPI = false, bool SP2 = false>
; __device__ __forceinline__ void gemm_phase(PG8_LAS unsigned char* lds, const Gemm g, const Sched& S, const Epi& E, const int wv) {
;     ...
;             const bool last = (t == nt - 2);
;             const char* a1 = cA + (size_t)(t + 1) * kstep;
;             const char* a2 = last ? nA : cA + (size_t)(t + 2) * kstep; const char* b2 = last ? nB : cB + (size_t)(t + 2) * kstep;
;             const char* a3 = a2 + kstep; const char* b3 = b2 + kstep;
;             if (last && has_next) S.a_ready(nxt);
;             if constexpr (SP2) {
;             PG8_LDB(B0, 0, 0); PG8_LDB(B1, 0, 1); PG8_SCHED; PG8_LDA(At, 0, 0); PG8_STAGE(PG8_SA(1, 1), a1 + hstepA, voffA);
;             PG8_WAIT_V(8); PG8_WAIT_L(0); PG8_BAR; PG8_MMA(0, 0, At, B0); PG8_MMA(0, 1, At, B1); PG8_BAR; PG8_SCHED;
;             PG8_LDA(At, 0, 1); PG8_STAGE(PG8_SB(0, 0), b2, voffB); PG8_STAGE(PG8_SB(0, 1), b2 + hstepB, voffB); PG8_STAGE(PG8_SA(0, 0), a2, voffA);
;             PG8_WAIT_V(8); PG8_WAIT_L(0); PG8_BAR; PG8_MMA(1, 0, At, B0); PG8_MMA(1, 1, At, B1); PG8_BAR; PG8_SCHED;
.LBB0_176:
	s_add_i32 s67, s14, 2
	s_add_u32 s68, s12, 0xfff80080
	s_addc_u32 s15, s13, -1
	s_cmp_eq_u32 s61, s14
	s_cselect_b32 s15, s11, s15
	s_cselect_b32 s14, s35, s68
	s_cselect_b32 s69, s45, s43
	s_cselect_b32 s68, s44, s42
	ds_read_b128 v[66:69], v171
	ds_read_b128 v[74:77], v171 offset:1024
	ds_read_b128 v[82:85], v171 offset:2048
	ds_read_b128 v[86:89], v171 offset:3072
	ds_read_b128 v[154:157], v173
	ds_read_b128 v[158:161], v173 offset:1024
	ds_read_b128 v[174:177], v173 offset:2048
	ds_read_b128 v[178:181], v173 offset:3072
	s_add_i32 m0, s54, 0xc000
	ds_read_b128 v[202:205], v200
	ds_read_b128 v[206:209], v200 offset:1024
	ds_read_b128 v[210:213], v200 offset:2048
	ds_read_b128 v[214:217], v200 offset:3072
	ds_read_b128 v[228:231], v200 offset:4096
	ds_read_b128 v[232:235], v200 offset:5120
	ds_read_b128 v[236:239], v200 offset:6144
	ds_read_b128 v[240:243], v200 offset:7168
	global_load_lds_dwordx4 v170, s[12:13]
	s_add_i32 m0, s54, 0xe000
	s_nop 0
	global_load_lds_dwordx4 v172, s[12:13]
	s_waitcnt vmcnt(8) lgkmcnt(0)
	s_barrier
	v_mfma_f32_16x16x32_bf16 v[150:153], v[66:69], v[202:205], v[150:153]
	v_mfma_f32_16x16x32_bf16 v[146:149], v[82:85], v[202:205], v[146:149]
	v_mfma_f32_16x16x32_bf16 v[134:137], v[66:69], v[210:213], v[134:137]
	v_mfma_f32_16x16x32_bf16 v[130:133], v[82:85], v[210:213], v[130:133]
	v_mfma_f32_16x16x32_bf16 v[118:121], v[66:69], v[228:231], v[118:121]
	v_mfma_f32_16x16x32_bf16 v[114:117], v[82:85], v[228:231], v[114:117]
	v_mfma_f32_16x16x32_bf16 v[102:105], v[66:69], v[236:239], v[102:105]
	v_mfma_f32_16x16x32_bf16 v[98:101], v[82:85], v[236:239], v[98:101]
	v_mfma_f32_16x16x32_bf16 v[150:153], v[74:77], v[206:209], v[150:153]
	v_mfma_f32_16x16x32_bf16 v[146:149], v[86:89], v[206:209], v[146:149]
	v_mfma_f32_16x16x32_bf16 v[134:137], v[74:77], v[214:217], v[134:137]
	v_mfma_f32_16x16x32_bf16 v[130:133], v[86:89], v[214:217], v[130:133]
	v_mfma_f32_16x16x32_bf16 v[118:121], v[74:77], v[232:235], v[118:121]
	v_mfma_f32_16x16x32_bf16 v[114:117], v[86:89], v[232:235], v[114:117]
	v_mfma_f32_16x16x32_bf16 v[102:105], v[74:77], v[240:243], v[102:105]
	v_mfma_f32_16x16x32_bf16 v[98:101], v[86:89], v[240:243], v[98:101]
	v_mfma_f32_16x16x32_bf16 v[142:145], v[154:157], v[202:205], v[142:145]
	v_mfma_f32_16x16x32_bf16 v[138:141], v[174:177], v[202:205], v[138:141]
	v_mfma_f32_16x16x32_bf16 v[126:129], v[154:157], v[210:213], v[126:129]
	v_mfma_f32_16x16x32_bf16 v[122:125], v[174:177], v[210:213], v[122:125]
	v_mfma_f32_16x16x32_bf16 v[110:113], v[154:157], v[228:231], v[110:113]
	v_mfma_f32_16x16x32_bf16 v[106:109], v[174:177], v[228:231], v[106:109]
	v_mfma_f32_16x16x32_bf16 v[94:97], v[154:157], v[236:239], v[94:97]
	v_mfma_f32_16x16x32_bf16 v[90:93], v[174:177], v[236:239], v[90:93]
	v_mfma_f32_16x16x32_bf16 v[142:145], v[158:161], v[206:209], v[142:145]
	v_mfma_f32_16x16x32_bf16 v[138:141], v[178:181], v[206:209], v[138:141]
	v_mfma_f32_16x16x32_bf16 v[126:129], v[158:161], v[214:217], v[126:129]
	v_mfma_f32_16x16x32_bf16 v[122:125], v[178:181], v[214:217], v[122:125]
	v_mfma_f32_16x16x32_bf16 v[110:113], v[158:161], v[232:235], v[110:113]
	v_mfma_f32_16x16x32_bf16 v[106:109], v[178:181], v[232:235], v[106:109]
	v_mfma_f32_16x16x32_bf16 v[94:97], v[158:161], v[240:243], v[94:97]
	v_mfma_f32_16x16x32_bf16 v[90:93], v[178:181], v[240:243], v[90:93]
	s_barrier
	s_add_i32 s70, s53, 0x10000
	v_lshl_add_u64 v[218:219], s[68:69], 0, v[0:1]
	s_mov_b32 m0, s70
	ds_read_b128 v[202:205], v200 offset:16384
	ds_read_b128 v[206:209], v200 offset:17408
	ds_read_b128 v[210:213], v200 offset:18432
	ds_read_b128 v[214:217], v200 offset:19456
	ds_read_b128 v[228:231], v200 offset:20480
	ds_read_b128 v[232:235], v200 offset:21504
	ds_read_b128 v[236:239], v200 offset:22528
	ds_read_b128 v[240:243], v200 offset:23552
	global_load_lds_dwordx4 v[218:219], off
	s_add_i32 m0, s70, 0x2000
	v_lshl_add_u64 v[244:245], s[68:69], 0, v[166:167]
	s_add_u32 s68, s68, s24
	s_addc_u32 s69, s69, s25
	s_add_i32 s70, s53, 0x14000
	global_load_lds_dwordx4 v[244:245], off
	s_mov_b32 m0, s70
	global_load_lds_dwordx4 v0, s[68:69]
	s_add_i32 m0, s70, 0x2000
	v_lshl_add_u64 v[250:251], s[14:15], 0, v[162:163]
	global_load_lds_dwordx4 v166, s[68:69]
	s_mov_b32 m0, s54
	v_lshl_add_u64 v[252:253], s[14:15], 0, v[164:165]
	global_load_lds_dwordx4 v[250:251], off
	s_mov_b32 m0, s55
	s_nop 0
	global_load_lds_dwordx4 v[252:253], off
	s_waitcnt vmcnt(8) lgkmcnt(0)
	s_barrier
	v_mfma_f32_16x16x32_bf16 v[78:81], v[66:69], v[202:205], v[78:81]
	v_mfma_f32_16x16x32_bf16 v[70:73], v[82:85], v[202:205], v[70:73]
	v_mfma_f32_16x16x32_bf16 v[46:49], v[66:69], v[210:213], v[46:49]
	v_mfma_f32_16x16x32_bf16 v[42:45], v[82:85], v[210:213], v[42:45]
	v_mfma_f32_16x16x32_bf16 v[30:33], v[66:69], v[228:231], v[30:33]
	v_mfma_f32_16x16x32_bf16 v[26:29], v[82:85], v[228:231], v[26:29]
	v_mfma_f32_16x16x32_bf16 v[14:17], v[66:69], v[236:239], v[14:17]
	v_mfma_f32_16x16x32_bf16 v[10:13], v[82:85], v[236:239], v[10:13]
	v_mfma_f32_16x16x32_bf16 v[78:81], v[74:77], v[206:209], v[78:81]
	v_mfma_f32_16x16x32_bf16 v[70:73], v[86:89], v[206:209], v[70:73]
	v_mfma_f32_16x16x32_bf16 v[46:49], v[74:77], v[214:217], v[46:49]
	v_mfma_f32_16x16x32_bf16 v[42:45], v[86:89], v[214:217], v[42:45]
	v_mfma_f32_16x16x32_bf16 v[30:33], v[74:77], v[232:235], v[30:33]
	v_mfma_f32_16x16x32_bf16 v[26:29], v[86:89], v[232:235], v[26:29]
	v_mfma_f32_16x16x32_bf16 v[14:17], v[74:77], v[240:243], v[14:17]
	v_mfma_f32_16x16x32_bf16 v[10:13], v[86:89], v[240:243], v[10:13]
	v_mfma_f32_16x16x32_bf16 v[60:63], v[154:157], v[202:205], v[62:65]
	v_mfma_f32_16x16x32_bf16 v[54:57], v[174:177], v[202:205], v[54:57]
	v_mfma_f32_16x16x32_bf16 v[38:41], v[154:157], v[210:213], v[38:41]
	v_mfma_f32_16x16x32_bf16 v[34:37], v[174:177], v[210:213], v[34:37]
	v_mfma_f32_16x16x32_bf16 v[22:25], v[154:157], v[228:231], v[22:25]
	v_mfma_f32_16x16x32_bf16 v[18:21], v[174:177], v[228:231], v[18:21]
	v_mfma_f32_16x16x32_bf16 v[6:9], v[154:157], v[236:239], v[6:9]
	v_mfma_f32_16x16x32_bf16 v[2:5], v[174:177], v[236:239], v[2:5]
	v_mfma_f32_16x16x32_bf16 v[60:63], v[158:161], v[206:209], v[60:63]
	v_mfma_f32_16x16x32_bf16 v[54:57], v[178:181], v[206:209], v[54:57]
	v_mfma_f32_16x16x32_bf16 v[38:41], v[158:161], v[214:217], v[38:41]
	v_mfma_f32_16x16x32_bf16 v[34:37], v[178:181], v[214:217], v[34:37]
	v_mfma_f32_16x16x32_bf16 v[22:25], v[158:161], v[232:235], v[22:25]
	v_mfma_f32_16x16x32_bf16 v[18:21], v[178:181], v[232:235], v[18:21]
	v_mfma_f32_16x16x32_bf16 v[6:9], v[158:161], v[240:243], v[6:9]
	v_mfma_f32_16x16x32_bf16 v[2:5], v[178:181], v[240:243], v[2:5]
	s_barrier
; #define PG8_STAGE(bufoff, gbase, voff) do { _Pragma("unroll") for (int _i = 0; _i < 2; ++_i) \
;         __builtin_amdgcn_global_load_lds((const unsigned*)((const char*)(gbase) + (voff)[_i]), (PG8_LAS unsigned*)(lds + (bufoff) + ldsw + _i * 8192), 16, 0, 0); } while (0)
; #define PG8_LDA(dst, b, h) do { _Pragma("unroll") for (int m = 0; m < 4; ++m) _Pragma("unroll") for (int k = 0; k < 2; ++k) dst[m][k] = *(const PG8_LAS bf16x8*)(lds + PG8_SA(b, h) + aoff + m * 2048 + k * 1024); } while (0)
; #define PG8_LDB(dst, b, h) do { _Pragma("unroll") for (int n = 0; n < 2; ++n) _Pragma("unroll") for (int k = 0; k < 2; ++k) dst[n][k] = *(const PG8_LAS bf16x8*)(lds + PG8_SB(b, h) + boff + n * 2048 + k * 1024); } while (0)
; #define PG8_MMA(ai, bj, At, Bt) do { __builtin_amdgcn_s_setprio(1); _Pragma("unroll") for (int m = 0; m < 4; ++m) _Pragma("unroll") for (int n = 0; n < 2; ++n) _Pragma("unroll") for (int k = 0; k < 2; ++k) \
;         acc[ai][bj][m][n] = __builtin_amdgcn_mfma_f32_16x16x32_bf16(Bt[n][k], At[m][k], acc[ai][bj][m][n], 0, 0, 0); __builtin_amdgcn_s_setprio(0); } while (0)
; #define PG8_WAIT_V(n) asm volatile("s_waitcnt vmcnt(" #n ")" ::: "memory")
; #define PG8_WAIT_L(n) asm volatile("s_waitcnt lgkmcnt(" #n ")" ::: "memory")
; #define PG8_BAR __builtin_amdgcn_s_barrier()
; #define PG8_SCHED __builtin_amdgcn_sched_barrier(0)
; template <class Epi, class Sched, bool ALIGN_EPI = false, bool SP2 = false>
; __device__ __forceinline__ void gemm_phase(PG8_LAS unsigned char* lds, const Gemm g, const Sched& S, const Epi& E, const int wv) {
;     ...
;             PG8_LDB(B0, 1, 0); PG8_LDB(B1, 1, 1); PG8_SCHED; PG8_LDA(At, 1, 0); PG8_STAGE(PG8_SA(0, 1), a2 + hstepA, voffA);
;             PG8_WAIT_V(8); PG8_WAIT_L(0); PG8_BAR; PG8_MMA(0, 0, At, B0); PG8_MMA(0, 1, At, B1); PG8_BAR; PG8_SCHED;
;             PG8_LDA(At, 1, 1); PG8_STAGE(PG8_SB(1, 0), b3, voffB); PG8_STAGE(PG8_SB(1, 1), b3 + hstepB, voffB); PG8_STAGE(PG8_SA(1, 0), a3, voffA);
;             PG8_WAIT_V(8); PG8_WAIT_L(0); PG8_BAR; PG8_MMA(1, 0, At, B0); PG8_MMA(1, 1, At, B1); PG8_BAR; PG8_SCHED;
	ds_read_b128 v[64:67], v201
	ds_read_b128 v[74:77], v201 offset:1024
	ds_read_b128 v[82:85], v201 offset:2048
	ds_read_b128 v[86:89], v201 offset:3072
	ds_read_b128 v[154:157], v227
	ds_read_b128 v[158:161], v227 offset:1024
	ds_read_b128 v[174:177], v227 offset:2048
	ds_read_b128 v[178:181], v227 offset:3072
	s_add_u32 s14, s14, 0x80000
	s_addc_u32 s15, s15, 0
	s_mov_b32 m0, s56
	ds_read_b128 v[202:205], v200 offset:32768
	ds_read_b128 v[206:209], v200 offset:33792
	ds_read_b128 v[210:213], v200 offset:34816
	ds_read_b128 v[214:217], v200 offset:35840
	ds_read_b128 v[228:231], v200 offset:36864
	ds_read_b128 v[232:235], v200 offset:37888
	ds_read_b128 v[236:239], v200 offset:38912
	ds_read_b128 v[240:243], v200 offset:39936
	global_load_lds_dwordx4 v162, s[14:15]
	s_mov_b32 m0, s57
	s_nop 0
	global_load_lds_dwordx4 v164, s[14:15]
	s_waitcnt vmcnt(8) lgkmcnt(0)
	s_barrier
	v_mfma_f32_16x16x32_bf16 v[150:153], v[64:67], v[202:205], v[150:153]
	v_mfma_f32_16x16x32_bf16 v[146:149], v[82:85], v[202:205], v[146:149]
	v_mfma_f32_16x16x32_bf16 v[134:137], v[64:67], v[210:213], v[134:137]
	v_mfma_f32_16x16x32_bf16 v[130:133], v[82:85], v[210:213], v[130:133]
	v_mfma_f32_16x16x32_bf16 v[118:121], v[64:67], v[228:231], v[118:121]
	v_mfma_f32_16x16x32_bf16 v[114:117], v[82:85], v[228:231], v[114:117]
	v_mfma_f32_16x16x32_bf16 v[102:105], v[64:67], v[236:239], v[102:105]
	v_mfma_f32_16x16x32_bf16 v[98:101], v[82:85], v[236:239], v[98:101]
	v_mfma_f32_16x16x32_bf16 v[150:153], v[74:77], v[206:209], v[150:153]
	v_mfma_f32_16x16x32_bf16 v[146:149], v[86:89], v[206:209], v[146:149]
	v_mfma_f32_16x16x32_bf16 v[134:137], v[74:77], v[214:217], v[134:137]
	v_mfma_f32_16x16x32_bf16 v[130:133], v[86:89], v[214:217], v[130:133]
	v_mfma_f32_16x16x32_bf16 v[118:121], v[74:77], v[232:235], v[118:121]
	v_mfma_f32_16x16x32_bf16 v[114:117], v[86:89], v[232:235], v[114:117]
	v_mfma_f32_16x16x32_bf16 v[102:105], v[74:77], v[240:243], v[102:105]
	v_mfma_f32_16x16x32_bf16 v[98:101], v[86:89], v[240:243], v[98:101]
	v_mfma_f32_16x16x32_bf16 v[142:145], v[154:157], v[202:205], v[142:145]
	v_mfma_f32_16x16x32_bf16 v[138:141], v[174:177], v[202:205], v[138:141]
	v_mfma_f32_16x16x32_bf16 v[126:129], v[154:157], v[210:213], v[126:129]
	v_mfma_f32_16x16x32_bf16 v[122:125], v[174:177], v[210:213], v[122:125]
	v_mfma_f32_16x16x32_bf16 v[110:113], v[154:157], v[228:231], v[110:113]
	v_mfma_f32_16x16x32_bf16 v[106:109], v[174:177], v[228:231], v[106:109]
	v_mfma_f32_16x16x32_bf16 v[94:97], v[154:157], v[236:239], v[94:97]
	v_mfma_f32_16x16x32_bf16 v[90:93], v[174:177], v[236:239], v[90:93]
	v_mfma_f32_16x16x32_bf16 v[142:145], v[158:161], v[206:209], v[142:145]
	v_mfma_f32_16x16x32_bf16 v[138:141], v[178:181], v[206:209], v[138:141]
	v_mfma_f32_16x16x32_bf16 v[126:129], v[158:161], v[214:217], v[126:129]
	v_mfma_f32_16x16x32_bf16 v[122:125], v[178:181], v[214:217], v[122:125]
	v_mfma_f32_16x16x32_bf16 v[110:113], v[158:161], v[232:235], v[110:113]
	v_mfma_f32_16x16x32_bf16 v[106:109], v[178:181], v[232:235], v[106:109]
	v_mfma_f32_16x16x32_bf16 v[94:97], v[158:161], v[240:243], v[94:97]
	v_mfma_f32_16x16x32_bf16 v[90:93], v[178:181], v[240:243], v[90:93]
	s_barrier
	s_add_i32 s14, s53, 0x18000
	s_add_i32 m0, s14, 0xffffff80
	ds_read_b128 v[202:205], v200 offset:49152
	ds_read_b128 v[206:209], v200 offset:50176
	ds_read_b128 v[210:213], v200 offset:51200
	ds_read_b128 v[214:217], v200 offset:52224
	ds_read_b128 v[228:231], v200 offset:53248
	ds_read_b128 v[232:235], v200 offset:54272
	ds_read_b128 v[236:239], v200 offset:55296
	ds_read_b128 v[240:243], v200 offset:56320
	global_load_lds_dwordx4 v[218:219], off offset:128
	s_add_i32 m0, s14, 0x1f80
	s_add_i32 s14, s53, 0x1c000
	global_load_lds_dwordx4 v[244:245], off offset:128
	s_add_i32 m0, s14, 0xffffff80
	s_nop 0
	global_load_lds_dwordx4 v0, s[68:69] offset:128
	s_add_i32 m0, s14, 0x1f80
	s_nop 0
	global_load_lds_dwordx4 v166, s[68:69] offset:128
	s_add_i32 m0, s58, 0xffffff80
	s_nop 0
	global_load_lds_dwordx4 v[250:251], off offset:128
	s_add_i32 m0, s59, 0xffffff80
	s_nop 0
	global_load_lds_dwordx4 v[252:253], off offset:128
	s_waitcnt vmcnt(8) lgkmcnt(0)
	s_barrier
	v_mfma_f32_16x16x32_bf16 v[78:81], v[64:67], v[202:205], v[78:81]
	v_mfma_f32_16x16x32_bf16 v[68:71], v[82:85], v[202:205], v[70:73]
	v_mfma_f32_16x16x32_bf16 v[46:49], v[64:67], v[210:213], v[46:49]
	v_mfma_f32_16x16x32_bf16 v[42:45], v[82:85], v[210:213], v[42:45]
	v_mfma_f32_16x16x32_bf16 v[30:33], v[64:67], v[228:231], v[30:33]
	v_mfma_f32_16x16x32_bf16 v[26:29], v[82:85], v[228:231], v[26:29]
	v_mfma_f32_16x16x32_bf16 v[14:17], v[64:67], v[236:239], v[14:17]
	v_mfma_f32_16x16x32_bf16 v[10:13], v[82:85], v[236:239], v[10:13]
	v_mfma_f32_16x16x32_bf16 v[78:81], v[74:77], v[206:209], v[78:81]
	v_mfma_f32_16x16x32_bf16 v[70:73], v[86:89], v[206:209], v[68:71]
	v_mfma_f32_16x16x32_bf16 v[46:49], v[74:77], v[214:217], v[46:49]
	v_mfma_f32_16x16x32_bf16 v[42:45], v[86:89], v[214:217], v[42:45]
	v_mfma_f32_16x16x32_bf16 v[30:33], v[74:77], v[232:235], v[30:33]
	v_mfma_f32_16x16x32_bf16 v[26:29], v[86:89], v[232:235], v[26:29]
	v_mfma_f32_16x16x32_bf16 v[14:17], v[74:77], v[240:243], v[14:17]
	v_mfma_f32_16x16x32_bf16 v[10:13], v[86:89], v[240:243], v[10:13]
	v_mfma_f32_16x16x32_bf16 v[60:63], v[154:157], v[202:205], v[60:63]
	v_mfma_f32_16x16x32_bf16 v[54:57], v[174:177], v[202:205], v[54:57]
	v_mfma_f32_16x16x32_bf16 v[38:41], v[154:157], v[210:213], v[38:41]
	v_mfma_f32_16x16x32_bf16 v[34:37], v[174:177], v[210:213], v[34:37]
	v_mfma_f32_16x16x32_bf16 v[22:25], v[154:157], v[228:231], v[22:25]
	v_mfma_f32_16x16x32_bf16 v[18:21], v[174:177], v[228:231], v[18:21]
	v_mfma_f32_16x16x32_bf16 v[6:9], v[154:157], v[236:239], v[6:9]
	v_mfma_f32_16x16x32_bf16 v[2:5], v[174:177], v[236:239], v[2:5]
	v_mfma_f32_16x16x32_bf16 v[62:65], v[158:161], v[206:209], v[60:63]
	v_mfma_f32_16x16x32_bf16 v[54:57], v[178:181], v[206:209], v[54:57]
	v_mfma_f32_16x16x32_bf16 v[38:41], v[158:161], v[214:217], v[38:41]
	v_mfma_f32_16x16x32_bf16 v[34:37], v[178:181], v[214:217], v[34:37]
	v_mfma_f32_16x16x32_bf16 v[22:25], v[158:161], v[232:235], v[22:25]
	v_mfma_f32_16x16x32_bf16 v[18:21], v[178:181], v[232:235], v[18:21]
	v_mfma_f32_16x16x32_bf16 v[6:9], v[158:161], v[240:243], v[6:9]
	v_mfma_f32_16x16x32_bf16 v[2:5], v[178:181], v[240:243], v[2:5]
	s_barrier
	s_add_u32 s12, s12, 0x100
	s_addc_u32 s13, s13, 0
	s_add_u32 s42, s42, 0x100
	s_addc_u32 s43, s43, 0
	s_cmp_ge_i32 s67, s60
	s_mov_b32 s14, s67
	s_cbranch_scc0 .LBB0_176
	s_movk_i32 s68, 0x4000
	s_movk_i32 s69, 0x6000
	s_mov_b32 s70, 0x18000
	s_mov_b32 s71, 0x3f317217

; #define PG8_STAGE(bufoff, gbase, voff) do { _Pragma("unroll") for (int _i = 0; _i < 2; ++_i) \
;         __builtin_amdgcn_global_load_lds((const unsigned*)((const char*)(gbase) + (voff)[_i]), (PG8_LAS unsigned*)(lds + (bufoff) + ldsw + _i * 8192), 16, 0, 0); } while (0)
; #define PG8_LDA(dst, b, h) do { _Pragma("unroll") for (int m = 0; m < 4; ++m) _Pragma("unroll") for (int k = 0; k < 2; ++k) dst[m][k] = *(const PG8_LAS bf16x8*)(lds + PG8_SA(b, h) + aoff + m * 2048 + k * 1024); } while (0)
; #define PG8_LDB(dst, b, h) do { _Pragma("unroll") for (int n = 0; n < 2; ++n) _Pragma("unroll") for (int k = 0; k < 2; ++k) dst[n][k] = *(const PG8_LAS bf16x8*)(lds + PG8_SB(b, h) + boff + n * 2048 + k * 1024); } while (0)
; #define PG8_MMA(ai, bj, At, Bt) do { __builtin_amdgcn_s_setprio(1); _Pragma("unroll") for (int m = 0; m < 4; ++m) _Pragma("unroll") for (int n = 0; n < 2; ++n) _Pragma("unroll") for (int k = 0; k < 2; ++k) \
;         acc[ai][bj][m][n] = __builtin_amdgcn_mfma_f32_16x16x32_bf16(Bt[n][k], At[m][k], acc[ai][bj][m][n], 0, 0, 0); __builtin_amdgcn_s_setprio(0); } while (0)
; #define PG8_WAIT_V(n) asm volatile("s_waitcnt vmcnt(" #n ")" ::: "memory")
; #define PG8_WAIT_L(n) asm volatile("s_waitcnt lgkmcnt(" #n ")" ::: "memory")
; template <class Epi, class Sched, bool ALIGN_EPI = false, bool SP2 = false>
; __device__ __forceinline__ void gemm_phase(PG8_LAS unsigned char* lds, const Gemm g, const Sched& S, const Epi& E, const int wv) {
;     ...
;             const bool last = (t == nt - 2);
;             const char* a1 = cA + (size_t)(t + 1) * kstep;
;             const char* a2 = last ? nA : cA + (size_t)(t + 2) * kstep; const char* b2 = last ? nB : cB + (size_t)(t + 2) * kstep;
;             const char* a3 = a2 + kstep; const char* b3 = b2 + kstep;
;             if (last && has_next) S.a_ready(nxt);
;             if constexpr (SP2) {
;             PG8_LDB(B0, 0, 0); PG8_LDB(B1, 0, 1); PG8_SCHED; PG8_LDA(At, 0, 0); PG8_STAGE(PG8_SA(1, 1), a1 + hstepA, voffA);
;             PG8_WAIT_V(8); PG8_WAIT_L(0); PG8_BAR; PG8_MMA(0, 0, At, B0); PG8_MMA(0, 1, At, B1); PG8_BAR; PG8_SCHED;
;             PG8_LDA(At, 0, 1); PG8_STAGE(PG8_SB(0, 0), b2, voffB); PG8_STAGE(PG8_SB(0, 1), b2 + hstepB, voffB); PG8_STAGE(PG8_SA(0, 0), a2, voffA);
;             PG8_WAIT_V(8); PG8_WAIT_L(0); PG8_BAR; PG8_MMA(1, 0, At, B0); PG8_MMA(1, 1, At, B1); PG8_BAR; PG8_SCHED;
.LBB0_336:
	s_add_i32 s40, s14, 2
	s_add_u32 s41, s12, 0xfff80080
	s_addc_u32 s15, s13, -1
	s_cmp_eq_u32 s62, s14
	s_cselect_b32 s15, s93, s15
	s_cselect_b32 s14, s92, s41
	s_cselect_b32 s45, s25, s17
	s_cselect_b32 s44, s24, s11
	ds_read_b128 v[26:29], v171
	ds_read_b128 v[30:33], v171 offset:1024
	ds_read_b128 v[42:45], v171 offset:2048
	ds_read_b128 v[46:49], v171 offset:3072
	ds_read_b128 v[146:149], v227
	ds_read_b128 v[150:153], v227 offset:1024
	ds_read_b128 v[154:157], v227 offset:2048
	ds_read_b128 v[158:161], v227 offset:3072
	s_add_i32 m0, s55, 0xc000
	ds_read_b128 v[172:175], v199
	ds_read_b128 v[176:179], v199 offset:1024
	ds_read_b128 v[180:183], v199 offset:2048
	ds_read_b128 v[200:203], v199 offset:3072
	ds_read_b128 v[204:207], v199 offset:4096
	ds_read_b128 v[208:211], v199 offset:5120
	ds_read_b128 v[212:215], v199 offset:6144
	ds_read_b128 v[216:219], v199 offset:7168
	global_load_lds_dwordx4 v168, s[12:13]
	s_add_i32 m0, s55, 0xe000
	s_nop 0
	global_load_lds_dwordx4 v170, s[12:13]
	s_waitcnt vmcnt(8) lgkmcnt(0)
	s_barrier
	v_mfma_f32_16x16x32_bf16 v[138:141], v[26:29], v[172:175], v[138:141]
	v_mfma_f32_16x16x32_bf16 v[142:145], v[42:45], v[172:175], v[142:145]
	v_mfma_f32_16x16x32_bf16 v[126:129], v[26:29], v[180:183], v[126:129]
	v_mfma_f32_16x16x32_bf16 v[122:125], v[42:45], v[180:183], v[122:125]
	v_mfma_f32_16x16x32_bf16 v[110:113], v[26:29], v[204:207], v[110:113]
	v_mfma_f32_16x16x32_bf16 v[106:109], v[42:45], v[204:207], v[106:109]
	v_mfma_f32_16x16x32_bf16 v[94:97], v[26:29], v[212:215], v[94:97]
	v_mfma_f32_16x16x32_bf16 v[90:93], v[42:45], v[212:215], v[90:93]
	v_mfma_f32_16x16x32_bf16 v[138:141], v[30:33], v[176:179], v[138:141]
	v_mfma_f32_16x16x32_bf16 v[142:145], v[46:49], v[176:179], v[142:145]
	v_mfma_f32_16x16x32_bf16 v[126:129], v[30:33], v[200:203], v[126:129]
	v_mfma_f32_16x16x32_bf16 v[122:125], v[46:49], v[200:203], v[122:125]
	v_mfma_f32_16x16x32_bf16 v[110:113], v[30:33], v[208:211], v[110:113]
	v_mfma_f32_16x16x32_bf16 v[106:109], v[46:49], v[208:211], v[106:109]
	v_mfma_f32_16x16x32_bf16 v[94:97], v[30:33], v[216:219], v[94:97]
	v_mfma_f32_16x16x32_bf16 v[90:93], v[46:49], v[216:219], v[90:93]
	v_mfma_f32_16x16x32_bf16 v[134:137], v[146:149], v[172:175], v[134:137]
	v_mfma_f32_16x16x32_bf16 v[130:133], v[154:157], v[172:175], v[130:133]
	v_mfma_f32_16x16x32_bf16 v[118:121], v[146:149], v[180:183], v[118:121]
	v_mfma_f32_16x16x32_bf16 v[114:117], v[154:157], v[180:183], v[114:117]
	v_mfma_f32_16x16x32_bf16 v[102:105], v[146:149], v[204:207], v[102:105]
	v_mfma_f32_16x16x32_bf16 v[98:101], v[154:157], v[204:207], v[98:101]
	v_mfma_f32_16x16x32_bf16 v[86:89], v[146:149], v[212:215], v[86:89]
	v_mfma_f32_16x16x32_bf16 v[82:85], v[154:157], v[212:215], v[82:85]
	v_mfma_f32_16x16x32_bf16 v[134:137], v[150:153], v[176:179], v[134:137]
	v_mfma_f32_16x16x32_bf16 v[130:133], v[158:161], v[176:179], v[130:133]
	v_mfma_f32_16x16x32_bf16 v[118:121], v[150:153], v[200:203], v[118:121]
	v_mfma_f32_16x16x32_bf16 v[114:117], v[158:161], v[200:203], v[114:117]
	v_mfma_f32_16x16x32_bf16 v[102:105], v[150:153], v[208:211], v[102:105]
	v_mfma_f32_16x16x32_bf16 v[98:101], v[158:161], v[208:211], v[98:101]
	v_mfma_f32_16x16x32_bf16 v[86:89], v[150:153], v[216:219], v[86:89]
	v_mfma_f32_16x16x32_bf16 v[82:85], v[158:161], v[216:219], v[82:85]
	s_barrier
	s_add_i32 s65, s54, 0x10000
	v_lshl_add_u64 v[184:185], s[44:45], 0, v[0:1]
	s_mov_b32 m0, s65
	ds_read_b128 v[172:175], v199 offset:16384
	ds_read_b128 v[176:179], v199 offset:17408
	ds_read_b128 v[180:183], v199 offset:18432
	ds_read_b128 v[200:203], v199 offset:19456
	ds_read_b128 v[204:207], v199 offset:20480
	ds_read_b128 v[208:211], v199 offset:21504
	ds_read_b128 v[212:215], v199 offset:22528
	ds_read_b128 v[216:219], v199 offset:23552
	global_load_lds_dwordx4 v[184:185], off
	s_add_i32 m0, s65, 0x2000
	v_lshl_add_u64 v[194:195], s[44:45], 0, v[162:163]
	s_add_u32 s44, s44, s28
	s_addc_u32 s45, s45, s29
	s_add_i32 s41, s54, 0x14000
	global_load_lds_dwordx4 v[194:195], off
	s_mov_b32 m0, s41
	global_load_lds_dwordx4 v0, s[44:45]
	s_add_i32 m0, s41, 0x2000
	v_lshl_add_u64 v[232:233], s[14:15], 0, v[166:167]
	global_load_lds_dwordx4 v162, s[44:45]
	s_mov_b32 m0, s55
	v_lshl_add_u64 v[234:235], s[14:15], 0, v[164:165]
	global_load_lds_dwordx4 v[232:233], off
	s_mov_b32 m0, s56
	s_nop 0
	global_load_lds_dwordx4 v[234:235], off
	s_waitcnt vmcnt(8) lgkmcnt(0)
	s_barrier
	v_mfma_f32_16x16x32_bf16 v[78:81], v[26:29], v[172:175], v[78:81]
	v_mfma_f32_16x16x32_bf16 v[74:77], v[42:45], v[172:175], v[74:77]
	v_mfma_f32_16x16x32_bf16 v[62:65], v[26:29], v[180:183], v[62:65]
	v_mfma_f32_16x16x32_bf16 v[58:61], v[42:45], v[180:183], v[58:61]
	v_mfma_f32_16x16x32_bf16 v[38:41], v[26:29], v[204:207], v[38:41]
	v_mfma_f32_16x16x32_bf16 v[34:37], v[42:45], v[204:207], v[34:37]
	v_mfma_f32_16x16x32_bf16 v[14:17], v[26:29], v[212:215], v[14:17]
	v_mfma_f32_16x16x32_bf16 v[10:13], v[42:45], v[212:215], v[10:13]
	v_mfma_f32_16x16x32_bf16 v[78:81], v[30:33], v[176:179], v[78:81]
	v_mfma_f32_16x16x32_bf16 v[74:77], v[46:49], v[176:179], v[74:77]
	v_mfma_f32_16x16x32_bf16 v[62:65], v[30:33], v[200:203], v[62:65]
	v_mfma_f32_16x16x32_bf16 v[58:61], v[46:49], v[200:203], v[58:61]
	v_mfma_f32_16x16x32_bf16 v[38:41], v[30:33], v[208:211], v[38:41]
	v_mfma_f32_16x16x32_bf16 v[34:37], v[46:49], v[208:211], v[34:37]
	v_mfma_f32_16x16x32_bf16 v[14:17], v[30:33], v[216:219], v[14:17]
	v_mfma_f32_16x16x32_bf16 v[10:13], v[46:49], v[216:219], v[10:13]
	v_mfma_f32_16x16x32_bf16 v[22:25], v[146:149], v[204:207], v[22:25]
	v_mfma_f32_16x16x32_bf16 v[18:21], v[154:157], v[204:207], v[18:21]
	v_mfma_f32_16x16x32_bf16 v[6:9], v[146:149], v[212:215], v[6:9]
	v_mfma_f32_16x16x32_bf16 v[2:5], v[154:157], v[212:215], v[2:5]
	v_mfma_f32_16x16x32_bf16 v[26:29], v[146:149], v[172:175], v[70:73]
	v_mfma_f32_16x16x32_bf16 v[30:33], v[154:157], v[172:175], v[66:69]
	v_mfma_f32_16x16x32_bf16 v[42:45], v[146:149], v[180:183], v[54:57]
	v_mfma_f32_16x16x32_bf16 v[46:49], v[154:157], v[180:183], v[50:53]
	v_mfma_f32_16x16x32_bf16 v[22:25], v[150:153], v[208:211], v[22:25]
	v_mfma_f32_16x16x32_bf16 v[18:21], v[158:161], v[208:211], v[18:21]
	v_mfma_f32_16x16x32_bf16 v[6:9], v[150:153], v[216:219], v[6:9]
	v_mfma_f32_16x16x32_bf16 v[2:5], v[158:161], v[216:219], v[2:5]
	v_mfma_f32_16x16x32_bf16 v[26:29], v[150:153], v[176:179], v[26:29]
	v_mfma_f32_16x16x32_bf16 v[30:33], v[158:161], v[176:179], v[30:33]
	v_mfma_f32_16x16x32_bf16 v[42:45], v[150:153], v[200:203], v[42:45]
	v_mfma_f32_16x16x32_bf16 v[46:49], v[158:161], v[200:203], v[46:49]
	s_barrier
; #define PG8_STAGE(bufoff, gbase, voff) do { _Pragma("unroll") for (int _i = 0; _i < 2; ++_i) \
;         __builtin_amdgcn_global_load_lds((const unsigned*)((const char*)(gbase) + (voff)[_i]), (PG8_LAS unsigned*)(lds + (bufoff) + ldsw + _i * 8192), 16, 0, 0); } while (0)
; #define PG8_LDA(dst, b, h) do { _Pragma("unroll") for (int m = 0; m < 4; ++m) _Pragma("unroll") for (int k = 0; k < 2; ++k) dst[m][k] = *(const PG8_LAS bf16x8*)(lds + PG8_SA(b, h) + aoff + m * 2048 + k * 1024); } while (0)
; #define PG8_LDB(dst, b, h) do { _Pragma("unroll") for (int n = 0; n < 2; ++n) _Pragma("unroll") for (int k = 0; k < 2; ++k) dst[n][k] = *(const PG8_LAS bf16x8*)(lds + PG8_SB(b, h) + boff + n * 2048 + k * 1024); } while (0)
; #define PG8_MMA(ai, bj, At, Bt) do { __builtin_amdgcn_s_setprio(1); _Pragma("unroll") for (int m = 0; m < 4; ++m) _Pragma("unroll") for (int n = 0; n < 2; ++n) _Pragma("unroll") for (int k = 0; k < 2; ++k) \
;         acc[ai][bj][m][n] = __builtin_amdgcn_mfma_f32_16x16x32_bf16(Bt[n][k], At[m][k], acc[ai][bj][m][n], 0, 0, 0); __builtin_amdgcn_s_setprio(0); } while (0)
; #define PG8_WAIT_V(n) asm volatile("s_waitcnt vmcnt(" #n ")" ::: "memory")
; #define PG8_WAIT_L(n) asm volatile("s_waitcnt lgkmcnt(" #n ")" ::: "memory")
; #define PG8_BAR __builtin_amdgcn_s_barrier()
; #define PG8_SCHED __builtin_amdgcn_sched_barrier(0)
; template <class Epi, class Sched, bool ALIGN_EPI = false, bool SP2 = false>
; __device__ __forceinline__ void gemm_phase(PG8_LAS unsigned char* lds, const Gemm g, const Sched& S, const Epi& E, const int wv) {
;     ...
;             PG8_LDB(B0, 1, 0); PG8_LDB(B1, 1, 1); PG8_SCHED; PG8_LDA(At, 1, 0); PG8_STAGE(PG8_SA(0, 1), a2 + hstepA, voffA);
;             PG8_WAIT_V(8); PG8_WAIT_L(0); PG8_BAR; PG8_MMA(0, 0, At, B0); PG8_MMA(0, 1, At, B1); PG8_BAR; PG8_SCHED;
;             PG8_LDA(At, 1, 1); PG8_STAGE(PG8_SB(1, 0), b3, voffB); PG8_STAGE(PG8_SB(1, 1), b3 + hstepB, voffB); PG8_STAGE(PG8_SA(1, 0), a3, voffA);
;             PG8_WAIT_V(8); PG8_WAIT_L(0); PG8_BAR; PG8_MMA(1, 0, At, B0); PG8_MMA(1, 1, At, B1); PG8_BAR; PG8_SCHED;
	ds_read_b128 v[50:53], v244
	ds_read_b128 v[54:57], v244 offset:1024
	ds_read_b128 v[66:69], v244 offset:2048
	ds_read_b128 v[70:73], v244 offset:3072
	ds_read_b128 v[146:149], v245
	ds_read_b128 v[150:153], v245 offset:1024
	ds_read_b128 v[154:157], v245 offset:2048
	ds_read_b128 v[158:161], v245 offset:3072
	s_add_u32 s14, s14, 0x80000
	s_addc_u32 s15, s15, 0
	s_mov_b32 m0, s57
	ds_read_b128 v[172:175], v199 offset:32768
	ds_read_b128 v[176:179], v199 offset:33792
	ds_read_b128 v[180:183], v199 offset:34816
	ds_read_b128 v[200:203], v199 offset:35840
	ds_read_b128 v[204:207], v199 offset:36864
	ds_read_b128 v[208:211], v199 offset:37888
	ds_read_b128 v[212:215], v199 offset:38912
	ds_read_b128 v[216:219], v199 offset:39936
	global_load_lds_dwordx4 v166, s[14:15]
	s_mov_b32 m0, s58
	s_nop 0
	global_load_lds_dwordx4 v164, s[14:15]
	s_waitcnt vmcnt(8) lgkmcnt(0)
	s_barrier
	v_mfma_f32_16x16x32_bf16 v[138:141], v[50:53], v[172:175], v[138:141]
	v_mfma_f32_16x16x32_bf16 v[142:145], v[66:69], v[172:175], v[142:145]
	v_mfma_f32_16x16x32_bf16 v[126:129], v[50:53], v[180:183], v[126:129]
	v_mfma_f32_16x16x32_bf16 v[122:125], v[66:69], v[180:183], v[122:125]
	v_mfma_f32_16x16x32_bf16 v[110:113], v[50:53], v[204:207], v[110:113]
	v_mfma_f32_16x16x32_bf16 v[106:109], v[66:69], v[204:207], v[106:109]
	v_mfma_f32_16x16x32_bf16 v[94:97], v[50:53], v[212:215], v[94:97]
	v_mfma_f32_16x16x32_bf16 v[90:93], v[66:69], v[212:215], v[90:93]
	v_mfma_f32_16x16x32_bf16 v[138:141], v[54:57], v[176:179], v[138:141]
	v_mfma_f32_16x16x32_bf16 v[142:145], v[70:73], v[176:179], v[142:145]
	v_mfma_f32_16x16x32_bf16 v[126:129], v[54:57], v[200:203], v[126:129]
	v_mfma_f32_16x16x32_bf16 v[122:125], v[70:73], v[200:203], v[122:125]
	v_mfma_f32_16x16x32_bf16 v[110:113], v[54:57], v[208:211], v[110:113]
	v_mfma_f32_16x16x32_bf16 v[106:109], v[70:73], v[208:211], v[106:109]
	v_mfma_f32_16x16x32_bf16 v[94:97], v[54:57], v[216:219], v[94:97]
	v_mfma_f32_16x16x32_bf16 v[90:93], v[70:73], v[216:219], v[90:93]
	v_mfma_f32_16x16x32_bf16 v[134:137], v[146:149], v[172:175], v[134:137]
	v_mfma_f32_16x16x32_bf16 v[130:133], v[154:157], v[172:175], v[130:133]
	v_mfma_f32_16x16x32_bf16 v[118:121], v[146:149], v[180:183], v[118:121]
	v_mfma_f32_16x16x32_bf16 v[114:117], v[154:157], v[180:183], v[114:117]
	v_mfma_f32_16x16x32_bf16 v[102:105], v[146:149], v[204:207], v[102:105]
	v_mfma_f32_16x16x32_bf16 v[98:101], v[154:157], v[204:207], v[98:101]
	v_mfma_f32_16x16x32_bf16 v[86:89], v[146:149], v[212:215], v[86:89]
	v_mfma_f32_16x16x32_bf16 v[82:85], v[154:157], v[212:215], v[82:85]
	v_mfma_f32_16x16x32_bf16 v[134:137], v[150:153], v[176:179], v[134:137]
	v_mfma_f32_16x16x32_bf16 v[130:133], v[158:161], v[176:179], v[130:133]
	v_mfma_f32_16x16x32_bf16 v[118:121], v[150:153], v[200:203], v[118:121]
	v_mfma_f32_16x16x32_bf16 v[114:117], v[158:161], v[200:203], v[114:117]
	v_mfma_f32_16x16x32_bf16 v[102:105], v[150:153], v[208:211], v[102:105]
	v_mfma_f32_16x16x32_bf16 v[98:101], v[158:161], v[208:211], v[98:101]
	v_mfma_f32_16x16x32_bf16 v[86:89], v[150:153], v[216:219], v[86:89]
	v_mfma_f32_16x16x32_bf16 v[82:85], v[158:161], v[216:219], v[82:85]
	s_barrier
	s_add_i32 s14, s54, 0x18000
	s_add_i32 m0, s14, 0xffffff80
	ds_read_b128 v[172:175], v199 offset:49152
	ds_read_b128 v[176:179], v199 offset:50176
	ds_read_b128 v[180:183], v199 offset:51200
	ds_read_b128 v[200:203], v199 offset:52224
	ds_read_b128 v[204:207], v199 offset:53248
	ds_read_b128 v[208:211], v199 offset:54272
	ds_read_b128 v[212:215], v199 offset:55296
	ds_read_b128 v[216:219], v199 offset:56320
	global_load_lds_dwordx4 v[184:185], off offset:128
	s_add_i32 m0, s14, 0x1f80
	s_add_i32 s14, s54, 0x1c000
	global_load_lds_dwordx4 v[194:195], off offset:128
	s_add_i32 m0, s14, 0xffffff80
	s_nop 0
	global_load_lds_dwordx4 v0, s[44:45] offset:128
	s_add_i32 m0, s14, 0x1f80
	s_nop 0
	global_load_lds_dwordx4 v162, s[44:45] offset:128
	s_add_i32 m0, s60, 0xffffff80
	s_nop 0
	global_load_lds_dwordx4 v[232:233], off offset:128
	s_add_i32 m0, s61, 0xffffff80
	s_nop 0
	global_load_lds_dwordx4 v[234:235], off offset:128
	s_waitcnt vmcnt(8) lgkmcnt(0)
	s_barrier
	v_mfma_f32_16x16x32_bf16 v[78:81], v[50:53], v[172:175], v[78:81]
	v_mfma_f32_16x16x32_bf16 v[74:77], v[66:69], v[172:175], v[74:77]
	v_mfma_f32_16x16x32_bf16 v[62:65], v[50:53], v[180:183], v[62:65]
	v_mfma_f32_16x16x32_bf16 v[58:61], v[66:69], v[180:183], v[58:61]
	v_mfma_f32_16x16x32_bf16 v[38:41], v[50:53], v[204:207], v[38:41]
	v_mfma_f32_16x16x32_bf16 v[34:37], v[66:69], v[204:207], v[34:37]
	v_mfma_f32_16x16x32_bf16 v[14:17], v[50:53], v[212:215], v[14:17]
	v_mfma_f32_16x16x32_bf16 v[10:13], v[66:69], v[212:215], v[10:13]
	v_mfma_f32_16x16x32_bf16 v[78:81], v[54:57], v[176:179], v[78:81]
	v_mfma_f32_16x16x32_bf16 v[74:77], v[70:73], v[176:179], v[74:77]
	v_mfma_f32_16x16x32_bf16 v[62:65], v[54:57], v[200:203], v[62:65]
	v_mfma_f32_16x16x32_bf16 v[58:61], v[70:73], v[200:203], v[58:61]
	v_mfma_f32_16x16x32_bf16 v[38:41], v[54:57], v[208:211], v[38:41]
	v_mfma_f32_16x16x32_bf16 v[34:37], v[70:73], v[208:211], v[34:37]
	v_mfma_f32_16x16x32_bf16 v[14:17], v[54:57], v[216:219], v[14:17]
	v_mfma_f32_16x16x32_bf16 v[10:13], v[70:73], v[216:219], v[10:13]
	v_mfma_f32_16x16x32_bf16 v[26:29], v[146:149], v[172:175], v[26:29]
	v_mfma_f32_16x16x32_bf16 v[70:73], v[150:153], v[176:179], v[26:29]
	v_mfma_f32_16x16x32_bf16 v[26:29], v[154:157], v[172:175], v[30:33]
	v_mfma_f32_16x16x32_bf16 v[66:69], v[158:161], v[176:179], v[26:29]
	v_mfma_f32_16x16x32_bf16 v[26:29], v[146:149], v[180:183], v[42:45]
	v_mfma_f32_16x16x32_bf16 v[54:57], v[150:153], v[200:203], v[26:29]
	v_mfma_f32_16x16x32_bf16 v[26:29], v[154:157], v[180:183], v[46:49]
	v_mfma_f32_16x16x32_bf16 v[22:25], v[146:149], v[204:207], v[22:25]
	v_mfma_f32_16x16x32_bf16 v[18:21], v[154:157], v[204:207], v[18:21]
	v_mfma_f32_16x16x32_bf16 v[6:9], v[146:149], v[212:215], v[6:9]
	v_mfma_f32_16x16x32_bf16 v[2:5], v[154:157], v[212:215], v[2:5]
	v_mfma_f32_16x16x32_bf16 v[50:53], v[158:161], v[200:203], v[26:29]
	v_mfma_f32_16x16x32_bf16 v[22:25], v[150:153], v[208:211], v[22:25]
	v_mfma_f32_16x16x32_bf16 v[18:21], v[158:161], v[208:211], v[18:21]
	v_mfma_f32_16x16x32_bf16 v[6:9], v[150:153], v[216:219], v[6:9]
	v_mfma_f32_16x16x32_bf16 v[2:5], v[158:161], v[216:219], v[2:5]
	s_barrier
	s_add_u32 s12, s12, 0x100
	s_addc_u32 s13, s13, 0
	s_add_u32 s11, s11, 0x100
	s_addc_u32 s17, s17, 0
	s_cmp_ge_i32 s40, s59
	s_mov_b32 s14, s40
	s_cbranch_scc0 .LBB0_336

; #define PG8_STAGE(bufoff, gbase, voff) do { _Pragma("unroll") for (int _i = 0; _i < 2; ++_i) \
;         __builtin_amdgcn_global_load_lds((const unsigned*)((const char*)(gbase) + (voff)[_i]), (PG8_LAS unsigned*)(lds + (bufoff) + ldsw + _i * 8192), 16, 0, 0); } while (0)
; #define PG8_LDA(dst, b, h) do { _Pragma("unroll") for (int m = 0; m < 4; ++m) _Pragma("unroll") for (int k = 0; k < 2; ++k) dst[m][k] = *(const PG8_LAS bf16x8*)(lds + PG8_SA(b, h) + aoff + m * 2048 + k * 1024); } while (0)
; #define PG8_LDB(dst, b, h) do { _Pragma("unroll") for (int n = 0; n < 2; ++n) _Pragma("unroll") for (int k = 0; k < 2; ++k) dst[n][k] = *(const PG8_LAS bf16x8*)(lds + PG8_SB(b, h) + boff + n * 2048 + k * 1024); } while (0)
; #define PG8_MMA(ai, bj, At, Bt) do { __builtin_amdgcn_s_setprio(1); _Pragma("unroll") for (int m = 0; m < 4; ++m) _Pragma("unroll") for (int n = 0; n < 2; ++n) _Pragma("unroll") for (int k = 0; k < 2; ++k) \
;         acc[ai][bj][m][n] = __builtin_amdgcn_mfma_f32_16x16x32_bf16(Bt[n][k], At[m][k], acc[ai][bj][m][n], 0, 0, 0); __builtin_amdgcn_s_setprio(0); } while (0)
; #define PG8_WAIT_V(n) asm volatile("s_waitcnt vmcnt(" #n ")" ::: "memory")
; #define PG8_WAIT_L(n) asm volatile("s_waitcnt lgkmcnt(" #n ")" ::: "memory")
; template <class Epi, class Sched, bool ALIGN_EPI = false, bool SP2 = false>
; __device__ __forceinline__ void gemm_phase(PG8_LAS unsigned char* lds, const Gemm g, const Sched& S, const Epi& E, const int wv) {
;     ...
;             const bool last = (t == nt - 2);
;             const char* a1 = cA + (size_t)(t + 1) * kstep;
;             const char* a2 = last ? nA : cA + (size_t)(t + 2) * kstep; const char* b2 = last ? nB : cB + (size_t)(t + 2) * kstep;
;             const char* a3 = a2 + kstep; const char* b3 = b2 + kstep;
;             if (last && has_next) S.a_ready(nxt);
;             if constexpr (SP2) {
;             PG8_LDB(B0, 0, 0); PG8_LDB(B1, 0, 1); PG8_SCHED; PG8_LDA(At, 0, 0); PG8_STAGE(PG8_SA(1, 1), a1 + hstepA, voffA);
;             PG8_WAIT_V(8); PG8_WAIT_L(0); PG8_BAR; PG8_MMA(0, 0, At, B0); PG8_MMA(0, 1, At, B1); PG8_BAR; PG8_SCHED;
;             PG8_LDA(At, 0, 1); PG8_STAGE(PG8_SB(0, 0), b2, voffB); PG8_STAGE(PG8_SB(0, 1), b2 + hstepB, voffB); PG8_STAGE(PG8_SA(0, 0), a2, voffA);
;             PG8_WAIT_V(8); PG8_WAIT_L(0); PG8_BAR; PG8_MMA(1, 0, At, B0); PG8_MMA(1, 1, At, B1); PG8_BAR; PG8_SCHED;
.LBB0_699:
	s_add_i32 s72, s54, 2
	s_add_u32 s73, s44, 0xfff80080
	s_addc_u32 s55, s45, -1
	s_cmp_eq_u32 s66, s54
	s_cselect_b32 s55, s31, s55
	s_cselect_b32 s54, s71, s73
	s_cselect_b32 s75, s13, s57
	s_cselect_b32 s74, s12, s56
	ds_read_b128 v[126:129], v190
	ds_read_b128 v[138:141], v190 offset:1024
	ds_read_b128 v[142:145], v190 offset:2048
	ds_read_b128 v[146:149], v190 offset:3072
	ds_read_b128 v[150:153], v191
	ds_read_b128 v[154:157], v191 offset:1024
	ds_read_b128 v[158:161], v191 offset:2048
	ds_read_b128 v[162:165], v191 offset:3072
	s_add_i32 m0, s59, 0xc000
	ds_read_b128 v[166:169], v235
	ds_read_b128 v[170:173], v235 offset:1024
	ds_read_b128 v[174:177], v235 offset:2048
	ds_read_b128 v[178:181], v235 offset:3072
	ds_read_b128 v[182:185], v235 offset:4096
	ds_read_b128 v[204:207], v235 offset:5120
	ds_read_b128 v[208:211], v235 offset:6144
	ds_read_b128 v[212:215], v235 offset:7168
	global_load_lds_dwordx4 v200, s[44:45]
	s_add_i32 m0, s59, 0xe000
	s_nop 0
	global_load_lds_dwordx4 v202, s[44:45]
	s_waitcnt vmcnt(8) lgkmcnt(0)
	s_barrier
	v_mfma_f32_16x16x32_bf16 v[134:137], v[126:129], v[166:169], v[134:137]
	v_mfma_f32_16x16x32_bf16 v[130:133], v[142:145], v[166:169], v[130:133]
	v_mfma_f32_16x16x32_bf16 v[110:113], v[126:129], v[174:177], v[110:113]
	v_mfma_f32_16x16x32_bf16 v[106:109], v[142:145], v[174:177], v[106:109]
	v_mfma_f32_16x16x32_bf16 v[94:97], v[126:129], v[182:185], v[94:97]
	v_mfma_f32_16x16x32_bf16 v[90:93], v[142:145], v[182:185], v[90:93]
	v_mfma_f32_16x16x32_bf16 v[78:81], v[126:129], v[208:211], v[78:81]
	v_mfma_f32_16x16x32_bf16 v[74:77], v[142:145], v[208:211], v[74:77]
	v_mfma_f32_16x16x32_bf16 v[134:137], v[138:141], v[170:173], v[134:137]
	v_mfma_f32_16x16x32_bf16 v[130:133], v[146:149], v[170:173], v[130:133]
	v_mfma_f32_16x16x32_bf16 v[110:113], v[138:141], v[178:181], v[110:113]
	v_mfma_f32_16x16x32_bf16 v[106:109], v[146:149], v[178:181], v[106:109]
	v_mfma_f32_16x16x32_bf16 v[94:97], v[138:141], v[204:207], v[94:97]
	v_mfma_f32_16x16x32_bf16 v[90:93], v[146:149], v[204:207], v[90:93]
	v_mfma_f32_16x16x32_bf16 v[78:81], v[138:141], v[212:215], v[78:81]
	v_mfma_f32_16x16x32_bf16 v[74:77], v[146:149], v[212:215], v[74:77]
	v_mfma_f32_16x16x32_bf16 v[122:125], v[150:153], v[166:169], v[122:125]
	v_mfma_f32_16x16x32_bf16 v[116:119], v[158:161], v[166:169], v[118:121]
	v_mfma_f32_16x16x32_bf16 v[102:105], v[150:153], v[174:177], v[102:105]
	v_mfma_f32_16x16x32_bf16 v[98:101], v[158:161], v[174:177], v[98:101]
	v_mfma_f32_16x16x32_bf16 v[86:89], v[150:153], v[182:185], v[86:89]
	v_mfma_f32_16x16x32_bf16 v[82:85], v[158:161], v[182:185], v[82:85]
	v_mfma_f32_16x16x32_bf16 v[70:73], v[150:153], v[208:211], v[70:73]
	v_mfma_f32_16x16x32_bf16 v[66:69], v[158:161], v[208:211], v[66:69]
	v_mfma_f32_16x16x32_bf16 v[122:125], v[154:157], v[170:173], v[122:125]
	v_mfma_f32_16x16x32_bf16 v[116:119], v[162:165], v[170:173], v[116:119]
	v_mfma_f32_16x16x32_bf16 v[102:105], v[154:157], v[178:181], v[102:105]
	v_mfma_f32_16x16x32_bf16 v[98:101], v[162:165], v[178:181], v[98:101]
	v_mfma_f32_16x16x32_bf16 v[86:89], v[154:157], v[204:207], v[86:89]
	v_mfma_f32_16x16x32_bf16 v[82:85], v[162:165], v[204:207], v[82:85]
	v_mfma_f32_16x16x32_bf16 v[70:73], v[154:157], v[212:215], v[70:73]
	v_mfma_f32_16x16x32_bf16 v[66:69], v[162:165], v[212:215], v[66:69]
	s_barrier
	s_add_i32 s76, s53, 0x10000
	v_lshl_add_u64 v[216:217], s[74:75], 0, v[0:1]
	s_mov_b32 m0, s76
	ds_read_b128 v[166:169], v235 offset:16384
	ds_read_b128 v[170:173], v235 offset:17408
	ds_read_b128 v[174:177], v235 offset:18432
	ds_read_b128 v[178:181], v235 offset:19456
	ds_read_b128 v[182:185], v235 offset:20480
	ds_read_b128 v[204:207], v235 offset:21504
	ds_read_b128 v[208:211], v235 offset:22528
	ds_read_b128 v[212:215], v235 offset:23552
	global_load_lds_dwordx4 v[216:217], off
	s_add_i32 m0, s76, 0x2000
	v_lshl_add_u64 v[218:219], s[74:75], 0, v[198:199]
	s_add_u32 s74, s74, s34
	s_addc_u32 s75, s75, s35
	s_add_i32 s73, s53, 0x14000
	global_load_lds_dwordx4 v[218:219], off
	s_mov_b32 m0, s73
	global_load_lds_dwordx4 v0, s[74:75]
	s_add_i32 m0, s73, 0x2000
	v_lshl_add_u64 v[240:241], s[54:55], 0, v[194:195]
	global_load_lds_dwordx4 v198, s[74:75]
	s_mov_b32 m0, s59
	v_lshl_add_u64 v[242:243], s[54:55], 0, v[196:197]
	global_load_lds_dwordx4 v[240:241], off
	s_mov_b32 m0, s60
	s_nop 0
	global_load_lds_dwordx4 v[242:243], off
	s_waitcnt vmcnt(8) lgkmcnt(0)
	s_barrier
	v_mfma_f32_16x16x32_bf16 v[62:65], v[126:129], v[166:169], v[62:65]
	v_mfma_f32_16x16x32_bf16 v[58:61], v[142:145], v[166:169], v[58:61]
	v_mfma_f32_16x16x32_bf16 v[46:49], v[126:129], v[174:177], v[46:49]
	v_mfma_f32_16x16x32_bf16 v[42:45], v[142:145], v[174:177], v[42:45]
	v_mfma_f32_16x16x32_bf16 v[30:33], v[126:129], v[182:185], v[30:33]
	v_mfma_f32_16x16x32_bf16 v[26:29], v[142:145], v[182:185], v[26:29]
	v_mfma_f32_16x16x32_bf16 v[14:17], v[126:129], v[208:211], v[14:17]
	v_mfma_f32_16x16x32_bf16 v[10:13], v[142:145], v[208:211], v[10:13]
	v_mfma_f32_16x16x32_bf16 v[62:65], v[138:141], v[170:173], v[62:65]
	v_mfma_f32_16x16x32_bf16 v[58:61], v[146:149], v[170:173], v[58:61]
	v_mfma_f32_16x16x32_bf16 v[46:49], v[138:141], v[178:181], v[46:49]
	v_mfma_f32_16x16x32_bf16 v[42:45], v[146:149], v[178:181], v[42:45]
	v_mfma_f32_16x16x32_bf16 v[30:33], v[138:141], v[204:207], v[30:33]
	v_mfma_f32_16x16x32_bf16 v[26:29], v[146:149], v[204:207], v[26:29]
	v_mfma_f32_16x16x32_bf16 v[14:17], v[138:141], v[212:215], v[14:17]
	v_mfma_f32_16x16x32_bf16 v[10:13], v[146:149], v[212:215], v[10:13]
	v_mfma_f32_16x16x32_bf16 v[54:57], v[150:153], v[166:169], v[54:57]
	v_mfma_f32_16x16x32_bf16 v[50:53], v[158:161], v[166:169], v[50:53]
	v_mfma_f32_16x16x32_bf16 v[38:41], v[150:153], v[174:177], v[38:41]
	v_mfma_f32_16x16x32_bf16 v[34:37], v[158:161], v[174:177], v[34:37]
	v_mfma_f32_16x16x32_bf16 v[22:25], v[150:153], v[182:185], v[22:25]
	v_mfma_f32_16x16x32_bf16 v[18:21], v[158:161], v[182:185], v[18:21]
	v_mfma_f32_16x16x32_bf16 v[6:9], v[150:153], v[208:211], v[6:9]
	v_mfma_f32_16x16x32_bf16 v[2:5], v[158:161], v[208:211], v[2:5]
	v_mfma_f32_16x16x32_bf16 v[54:57], v[154:157], v[170:173], v[54:57]
	v_mfma_f32_16x16x32_bf16 v[50:53], v[162:165], v[170:173], v[50:53]
	v_mfma_f32_16x16x32_bf16 v[38:41], v[154:157], v[178:181], v[38:41]
	v_mfma_f32_16x16x32_bf16 v[34:37], v[162:165], v[178:181], v[34:37]
	v_mfma_f32_16x16x32_bf16 v[22:25], v[154:157], v[204:207], v[22:25]
	v_mfma_f32_16x16x32_bf16 v[18:21], v[162:165], v[204:207], v[18:21]
	v_mfma_f32_16x16x32_bf16 v[6:9], v[154:157], v[212:215], v[6:9]
	v_mfma_f32_16x16x32_bf16 v[2:5], v[162:165], v[212:215], v[2:5]
	s_barrier
; #define PG8_STAGE(bufoff, gbase, voff) do { _Pragma("unroll") for (int _i = 0; _i < 2; ++_i) \
;         __builtin_amdgcn_global_load_lds((const unsigned*)((const char*)(gbase) + (voff)[_i]), (PG8_LAS unsigned*)(lds + (bufoff) + ldsw + _i * 8192), 16, 0, 0); } while (0)
; #define PG8_LDA(dst, b, h) do { _Pragma("unroll") for (int m = 0; m < 4; ++m) _Pragma("unroll") for (int k = 0; k < 2; ++k) dst[m][k] = *(const PG8_LAS bf16x8*)(lds + PG8_SA(b, h) + aoff + m * 2048 + k * 1024); } while (0)
; #define PG8_LDB(dst, b, h) do { _Pragma("unroll") for (int n = 0; n < 2; ++n) _Pragma("unroll") for (int k = 0; k < 2; ++k) dst[n][k] = *(const PG8_LAS bf16x8*)(lds + PG8_SB(b, h) + boff + n * 2048 + k * 1024); } while (0)
; #define PG8_MMA(ai, bj, At, Bt) do { __builtin_amdgcn_s_setprio(1); _Pragma("unroll") for (int m = 0; m < 4; ++m) _Pragma("unroll") for (int n = 0; n < 2; ++n) _Pragma("unroll") for (int k = 0; k < 2; ++k) \
;         acc[ai][bj][m][n] = __builtin_amdgcn_mfma_f32_16x16x32_bf16(Bt[n][k], At[m][k], acc[ai][bj][m][n], 0, 0, 0); __builtin_amdgcn_s_setprio(0); } while (0)
; #define PG8_WAIT_V(n) asm volatile("s_waitcnt vmcnt(" #n ")" ::: "memory")
; #define PG8_WAIT_L(n) asm volatile("s_waitcnt lgkmcnt(" #n ")" ::: "memory")
; #define PG8_BAR __builtin_amdgcn_s_barrier()
; #define PG8_SCHED __builtin_amdgcn_sched_barrier(0)
; template <class Epi, class Sched, bool ALIGN_EPI = false, bool SP2 = false>
; __device__ __forceinline__ void gemm_phase(PG8_LAS unsigned char* lds, const Gemm g, const Sched& S, const Epi& E, const int wv) {
;     ...
;             PG8_LDB(B0, 1, 0); PG8_LDB(B1, 1, 1); PG8_SCHED; PG8_LDA(At, 1, 0); PG8_STAGE(PG8_SA(0, 1), a2 + hstepA, voffA);
;             PG8_WAIT_V(8); PG8_WAIT_L(0); PG8_BAR; PG8_MMA(0, 0, At, B0); PG8_MMA(0, 1, At, B1); PG8_BAR; PG8_SCHED;
;             PG8_LDA(At, 1, 1); PG8_STAGE(PG8_SB(1, 0), b3, voffB); PG8_STAGE(PG8_SB(1, 1), b3 + hstepB, voffB); PG8_STAGE(PG8_SA(1, 0), a3, voffA);
;             PG8_WAIT_V(8); PG8_WAIT_L(0); PG8_BAR; PG8_MMA(1, 0, At, B0); PG8_MMA(1, 1, At, B1); PG8_BAR; PG8_SCHED;
	ds_read_b128 v[126:129], v192
	ds_read_b128 v[138:141], v192 offset:1024
	ds_read_b128 v[142:145], v192 offset:2048
	ds_read_b128 v[146:149], v192 offset:3072
	ds_read_b128 v[150:153], v193
	ds_read_b128 v[154:157], v193 offset:1024
	ds_read_b128 v[158:161], v193 offset:2048
	ds_read_b128 v[162:165], v193 offset:3072
	s_add_u32 s54, s54, 0x80000
	s_addc_u32 s55, s55, 0
	s_mov_b32 m0, s61
	ds_read_b128 v[166:169], v235 offset:32768
	ds_read_b128 v[170:173], v235 offset:33792
	ds_read_b128 v[174:177], v235 offset:34816
	ds_read_b128 v[178:181], v235 offset:35840
	ds_read_b128 v[182:185], v235 offset:36864
	ds_read_b128 v[204:207], v235 offset:37888
	ds_read_b128 v[208:211], v235 offset:38912
	ds_read_b128 v[212:215], v235 offset:39936
	global_load_lds_dwordx4 v194, s[54:55]
	s_mov_b32 m0, s62
	s_nop 0
	global_load_lds_dwordx4 v196, s[54:55]
	s_waitcnt vmcnt(8) lgkmcnt(0)
	s_barrier
	v_mfma_f32_16x16x32_bf16 v[134:137], v[126:129], v[166:169], v[134:137]
	v_mfma_f32_16x16x32_bf16 v[130:133], v[142:145], v[166:169], v[130:133]
	v_mfma_f32_16x16x32_bf16 v[110:113], v[126:129], v[174:177], v[110:113]
	v_mfma_f32_16x16x32_bf16 v[106:109], v[142:145], v[174:177], v[106:109]
	v_mfma_f32_16x16x32_bf16 v[94:97], v[126:129], v[182:185], v[94:97]
	v_mfma_f32_16x16x32_bf16 v[90:93], v[142:145], v[182:185], v[90:93]
	v_mfma_f32_16x16x32_bf16 v[78:81], v[126:129], v[208:211], v[78:81]
	v_mfma_f32_16x16x32_bf16 v[74:77], v[142:145], v[208:211], v[74:77]
	v_mfma_f32_16x16x32_bf16 v[134:137], v[138:141], v[170:173], v[134:137]
	v_mfma_f32_16x16x32_bf16 v[130:133], v[146:149], v[170:173], v[130:133]
	v_mfma_f32_16x16x32_bf16 v[110:113], v[138:141], v[178:181], v[110:113]
	v_mfma_f32_16x16x32_bf16 v[106:109], v[146:149], v[178:181], v[106:109]
	v_mfma_f32_16x16x32_bf16 v[94:97], v[138:141], v[204:207], v[94:97]
	v_mfma_f32_16x16x32_bf16 v[90:93], v[146:149], v[204:207], v[90:93]
	v_mfma_f32_16x16x32_bf16 v[78:81], v[138:141], v[212:215], v[78:81]
	v_mfma_f32_16x16x32_bf16 v[74:77], v[146:149], v[212:215], v[74:77]
	v_mfma_f32_16x16x32_bf16 v[120:123], v[150:153], v[166:169], v[122:125]
	v_mfma_f32_16x16x32_bf16 v[116:119], v[158:161], v[166:169], v[116:119]
	v_mfma_f32_16x16x32_bf16 v[102:105], v[150:153], v[174:177], v[102:105]
	v_mfma_f32_16x16x32_bf16 v[98:101], v[158:161], v[174:177], v[98:101]
	v_mfma_f32_16x16x32_bf16 v[86:89], v[150:153], v[182:185], v[86:89]
	v_mfma_f32_16x16x32_bf16 v[82:85], v[158:161], v[182:185], v[82:85]
	v_mfma_f32_16x16x32_bf16 v[70:73], v[150:153], v[208:211], v[70:73]
	v_mfma_f32_16x16x32_bf16 v[66:69], v[158:161], v[208:211], v[66:69]
	v_mfma_f32_16x16x32_bf16 v[122:125], v[154:157], v[170:173], v[120:123]
	v_mfma_f32_16x16x32_bf16 v[118:121], v[162:165], v[170:173], v[116:119]
	v_mfma_f32_16x16x32_bf16 v[102:105], v[154:157], v[178:181], v[102:105]
	v_mfma_f32_16x16x32_bf16 v[98:101], v[162:165], v[178:181], v[98:101]
	v_mfma_f32_16x16x32_bf16 v[86:89], v[154:157], v[204:207], v[86:89]
	v_mfma_f32_16x16x32_bf16 v[82:85], v[162:165], v[204:207], v[82:85]
	v_mfma_f32_16x16x32_bf16 v[70:73], v[154:157], v[212:215], v[70:73]
	v_mfma_f32_16x16x32_bf16 v[66:69], v[162:165], v[212:215], v[66:69]
	s_barrier
	s_add_i32 s54, s53, 0x18000
	s_add_i32 m0, s54, 0xffffff80
	ds_read_b128 v[166:169], v235 offset:49152
	ds_read_b128 v[170:173], v235 offset:50176
	ds_read_b128 v[174:177], v235 offset:51200
	ds_read_b128 v[178:181], v235 offset:52224
	ds_read_b128 v[182:185], v235 offset:53248
	ds_read_b128 v[204:207], v235 offset:54272
	ds_read_b128 v[208:211], v235 offset:55296
	ds_read_b128 v[212:215], v235 offset:56320
	global_load_lds_dwordx4 v[216:217], off offset:128
	s_add_i32 m0, s54, 0x1f80
	s_add_i32 s54, s53, 0x1c000
	global_load_lds_dwordx4 v[218:219], off offset:128
	s_add_i32 m0, s54, 0xffffff80
	s_nop 0
	global_load_lds_dwordx4 v0, s[74:75] offset:128
	s_add_i32 m0, s54, 0x1f80
	s_nop 0
	global_load_lds_dwordx4 v198, s[74:75] offset:128
	s_add_i32 m0, s64, 0xffffff80
	s_nop 0
	global_load_lds_dwordx4 v[240:241], off offset:128
	s_add_i32 m0, s65, 0xffffff80
	s_nop 0
	global_load_lds_dwordx4 v[242:243], off offset:128
	s_waitcnt vmcnt(8) lgkmcnt(0)
	s_barrier
	v_mfma_f32_16x16x32_bf16 v[62:65], v[126:129], v[166:169], v[62:65]
	v_mfma_f32_16x16x32_bf16 v[58:61], v[142:145], v[166:169], v[58:61]
	v_mfma_f32_16x16x32_bf16 v[46:49], v[126:129], v[174:177], v[46:49]
	v_mfma_f32_16x16x32_bf16 v[42:45], v[142:145], v[174:177], v[42:45]
	v_mfma_f32_16x16x32_bf16 v[30:33], v[126:129], v[182:185], v[30:33]
	v_mfma_f32_16x16x32_bf16 v[26:29], v[142:145], v[182:185], v[26:29]
	v_mfma_f32_16x16x32_bf16 v[14:17], v[126:129], v[208:211], v[14:17]
	v_mfma_f32_16x16x32_bf16 v[10:13], v[142:145], v[208:211], v[10:13]
	v_mfma_f32_16x16x32_bf16 v[62:65], v[138:141], v[170:173], v[62:65]
	v_mfma_f32_16x16x32_bf16 v[58:61], v[146:149], v[170:173], v[58:61]
	v_mfma_f32_16x16x32_bf16 v[46:49], v[138:141], v[178:181], v[46:49]
	v_mfma_f32_16x16x32_bf16 v[42:45], v[146:149], v[178:181], v[42:45]
	v_mfma_f32_16x16x32_bf16 v[30:33], v[138:141], v[204:207], v[30:33]
	v_mfma_f32_16x16x32_bf16 v[26:29], v[146:149], v[204:207], v[26:29]
	v_mfma_f32_16x16x32_bf16 v[14:17], v[138:141], v[212:215], v[14:17]
	v_mfma_f32_16x16x32_bf16 v[10:13], v[146:149], v[212:215], v[10:13]
	v_mfma_f32_16x16x32_bf16 v[54:57], v[150:153], v[166:169], v[54:57]
	v_mfma_f32_16x16x32_bf16 v[50:53], v[158:161], v[166:169], v[50:53]
	v_mfma_f32_16x16x32_bf16 v[38:41], v[150:153], v[174:177], v[38:41]
	v_mfma_f32_16x16x32_bf16 v[34:37], v[158:161], v[174:177], v[34:37]
	v_mfma_f32_16x16x32_bf16 v[22:25], v[150:153], v[182:185], v[22:25]
	v_mfma_f32_16x16x32_bf16 v[18:21], v[158:161], v[182:185], v[18:21]
	v_mfma_f32_16x16x32_bf16 v[6:9], v[150:153], v[208:211], v[6:9]
	v_mfma_f32_16x16x32_bf16 v[2:5], v[158:161], v[208:211], v[2:5]
	v_mfma_f32_16x16x32_bf16 v[54:57], v[154:157], v[170:173], v[54:57]
	v_mfma_f32_16x16x32_bf16 v[50:53], v[162:165], v[170:173], v[50:53]
	v_mfma_f32_16x16x32_bf16 v[38:41], v[154:157], v[178:181], v[38:41]
	v_mfma_f32_16x16x32_bf16 v[34:37], v[162:165], v[178:181], v[34:37]
	v_mfma_f32_16x16x32_bf16 v[22:25], v[154:157], v[204:207], v[22:25]
	v_mfma_f32_16x16x32_bf16 v[18:21], v[162:165], v[204:207], v[18:21]
	v_mfma_f32_16x16x32_bf16 v[6:9], v[154:157], v[212:215], v[6:9]
	v_mfma_f32_16x16x32_bf16 v[2:5], v[162:165], v[212:215], v[2:5]
	s_barrier
	s_add_u32 s44, s44, 0x100
	s_addc_u32 s45, s45, 0
	s_add_u32 s56, s56, 0x100
	s_addc_u32 s57, s57, 0
	s_cmp_ge_i32 s72, s63
	s_mov_b32 s54, s72
	s_cbranch_scc0 .LBB0_699
	s_movk_i32 s75, 0x2000
	s_mov_b32 s72, 0x10000
	s_mov_b32 s73, 0x12000
	s_mov_b32 s74, 0x14000
	s_mov_b32 s71, 0x3f317217
	s_and_b64 vcc, exec, s[48:49]
	s_cbranch_vccz .LBB0_673

; #define PG8_STAGE(bufoff, gbase, voff) do { _Pragma("unroll") for (int _i = 0; _i < 2; ++_i) \
;         __builtin_amdgcn_global_load_lds((const unsigned*)((const char*)(gbase) + (voff)[_i]), (PG8_LAS unsigned*)(lds + (bufoff) + ldsw + _i * 8192), 16, 0, 0); } while (0)
; #define PG8_LDA(dst, b, h) do { _Pragma("unroll") for (int m = 0; m < 4; ++m) _Pragma("unroll") for (int k = 0; k < 2; ++k) dst[m][k] = *(const PG8_LAS bf16x8*)(lds + PG8_SA(b, h) + aoff + m * 2048 + k * 1024); } while (0)
; #define PG8_LDB(dst, b, h) do { _Pragma("unroll") for (int n = 0; n < 2; ++n) _Pragma("unroll") for (int k = 0; k < 2; ++k) dst[n][k] = *(const PG8_LAS bf16x8*)(lds + PG8_SB(b, h) + boff + n * 2048 + k * 1024); } while (0)
; #define PG8_MMA(ai, bj, At, Bt) do { __builtin_amdgcn_s_setprio(1); _Pragma("unroll") for (int m = 0; m < 4; ++m) _Pragma("unroll") for (int n = 0; n < 2; ++n) _Pragma("unroll") for (int k = 0; k < 2; ++k) \
;         acc[ai][bj][m][n] = __builtin_amdgcn_mfma_f32_16x16x32_bf16(Bt[n][k], At[m][k], acc[ai][bj][m][n], 0, 0, 0); __builtin_amdgcn_s_setprio(0); } while (0)
; #define PG8_WAIT_V(n) asm volatile("s_waitcnt vmcnt(" #n ")" ::: "memory")
; #define PG8_WAIT_L(n) asm volatile("s_waitcnt lgkmcnt(" #n ")" ::: "memory")
; template <class Epi, class Sched, bool ALIGN_EPI = false, bool SP2 = false>
; __device__ __forceinline__ void gemm_phase(PG8_LAS unsigned char* lds, const Gemm g, const Sched& S, const Epi& E, const int wv) {
;     ...
;             const bool last = (t == nt - 2);
;             const char* a1 = cA + (size_t)(t + 1) * kstep;
;             const char* a2 = last ? nA : cA + (size_t)(t + 2) * kstep; const char* b2 = last ? nB : cB + (size_t)(t + 2) * kstep;
;             const char* a3 = a2 + kstep; const char* b3 = b2 + kstep;
;             if (last && has_next) S.a_ready(nxt);
;             if constexpr (SP2) {
;             PG8_LDB(B0, 0, 0); PG8_LDB(B1, 0, 1); PG8_SCHED; PG8_LDA(At, 0, 0); PG8_STAGE(PG8_SA(1, 1), a1 + hstepA, voffA);
;             PG8_WAIT_V(8); PG8_WAIT_L(0); PG8_BAR; PG8_MMA(0, 0, At, B0); PG8_MMA(0, 1, At, B1); PG8_BAR; PG8_SCHED;
;             PG8_LDA(At, 0, 1); PG8_STAGE(PG8_SB(0, 0), b2, voffB); PG8_STAGE(PG8_SB(0, 1), b2 + hstepB, voffB); PG8_STAGE(PG8_SA(0, 0), a2, voffA);
;             PG8_WAIT_V(8); PG8_WAIT_L(0); PG8_BAR; PG8_MMA(1, 0, At, B0); PG8_MMA(1, 1, At, B1); PG8_BAR; PG8_SCHED;
.LBB0_809:
	s_add_i32 s52, s46, 2
	s_add_u32 s14, s48, 0x100
	s_addc_u32 s15, s49, 0
	s_cmp_eq_u32 s71, s46
	s_cselect_b32 s47, s11, s15
	s_cselect_b32 s46, s13, s14
	s_cselect_b32 s77, s87, s51
	s_cselect_b32 s76, s86, s35
	ds_read_b128 v[138:141], v192
	ds_read_b128 v[142:145], v192 offset:1024
	ds_read_b128 v[146:149], v192 offset:2048
	ds_read_b128 v[150:153], v192 offset:3072
	ds_read_b128 v[154:157], v193
	ds_read_b128 v[158:161], v193 offset:1024
	ds_read_b128 v[162:165], v193 offset:2048
	ds_read_b128 v[166:169], v193 offset:3072
	s_add_i32 m0, s63, 0xc000
	ds_read_b128 v[194:197], v211
	ds_read_b128 v[198:201], v211 offset:1024
	ds_read_b128 v[202:205], v211 offset:2048
	ds_read_b128 v[214:217], v211 offset:3072
	ds_read_b128 v[228:231], v211 offset:4096
	ds_read_b128 v[232:235], v211 offset:5120
	ds_read_b128 v[236:239], v211 offset:6144
	ds_read_b128 v[240:243], v211 offset:7168
	global_load_lds_dwordx4 v182, s[48:49]
	v_lshl_add_u64 v[190:191], s[48:49], 0, v[184:185]
	s_add_i32 m0, s63, 0xe000
	s_nop 0
	global_load_lds_dwordx4 v[190:191], off
	s_waitcnt vmcnt(8) lgkmcnt(0)
	s_barrier
	v_mfma_f32_16x16x32_bf16 v[118:121], v[138:141], v[194:197], v[118:121]
	v_mfma_f32_16x16x32_bf16 v[46:49], v[146:149], v[194:197], v[46:49]
	v_mfma_f32_16x16x32_bf16 v[110:113], v[138:141], v[202:205], v[110:113]
	v_mfma_f32_16x16x32_bf16 v[38:41], v[146:149], v[202:205], v[38:41]
	v_mfma_f32_16x16x32_bf16 v[134:137], v[138:141], v[228:231], v[134:137]
	v_mfma_f32_16x16x32_bf16 v[62:65], v[146:149], v[228:231], v[62:65]
	v_mfma_f32_16x16x32_bf16 v[130:133], v[138:141], v[236:239], v[130:133]
	v_mfma_f32_16x16x32_bf16 v[58:61], v[146:149], v[236:239], v[58:61]
	v_mfma_f32_16x16x32_bf16 v[118:121], v[142:145], v[198:201], v[118:121]
	v_mfma_f32_16x16x32_bf16 v[46:49], v[150:153], v[198:201], v[46:49]
	v_mfma_f32_16x16x32_bf16 v[110:113], v[142:145], v[214:217], v[110:113]
	v_mfma_f32_16x16x32_bf16 v[38:41], v[150:153], v[214:217], v[38:41]
	v_mfma_f32_16x16x32_bf16 v[134:137], v[142:145], v[232:235], v[134:137]
	v_mfma_f32_16x16x32_bf16 v[62:65], v[150:153], v[232:235], v[62:65]
	v_mfma_f32_16x16x32_bf16 v[130:133], v[142:145], v[240:243], v[130:133]
	v_mfma_f32_16x16x32_bf16 v[58:61], v[150:153], v[240:243], v[58:61]
	v_mfma_f32_16x16x32_bf16 v[114:117], v[154:157], v[194:197], v[114:117]
	v_mfma_f32_16x16x32_bf16 v[42:45], v[162:165], v[194:197], v[42:45]
	v_mfma_f32_16x16x32_bf16 v[106:109], v[154:157], v[202:205], v[106:109]
	v_mfma_f32_16x16x32_bf16 v[34:37], v[162:165], v[202:205], v[34:37]
	v_mfma_f32_16x16x32_bf16 v[126:129], v[154:157], v[228:231], v[126:129]
	v_mfma_f32_16x16x32_bf16 v[54:57], v[162:165], v[228:231], v[54:57]
	v_mfma_f32_16x16x32_bf16 v[122:125], v[154:157], v[236:239], v[122:125]
	v_mfma_f32_16x16x32_bf16 v[50:53], v[162:165], v[236:239], v[50:53]
	v_mfma_f32_16x16x32_bf16 v[114:117], v[158:161], v[198:201], v[114:117]
	v_mfma_f32_16x16x32_bf16 v[42:45], v[166:169], v[198:201], v[42:45]
	v_mfma_f32_16x16x32_bf16 v[106:109], v[158:161], v[214:217], v[106:109]
	v_mfma_f32_16x16x32_bf16 v[34:37], v[166:169], v[214:217], v[34:37]
	v_mfma_f32_16x16x32_bf16 v[126:129], v[158:161], v[232:235], v[126:129]
	v_mfma_f32_16x16x32_bf16 v[54:57], v[166:169], v[232:235], v[54:57]
	v_mfma_f32_16x16x32_bf16 v[122:125], v[158:161], v[240:243], v[122:125]
	v_mfma_f32_16x16x32_bf16 v[50:53], v[166:169], v[240:243], v[50:53]
	s_barrier
	s_add_i32 s48, s62, 0x10000
	s_mov_b32 m0, s48
	ds_read_b128 v[194:197], v211 offset:16384
	ds_read_b128 v[198:201], v211 offset:17408
	ds_read_b128 v[202:205], v211 offset:18432
	ds_read_b128 v[214:217], v211 offset:19456
	ds_read_b128 v[228:231], v211 offset:20480
	ds_read_b128 v[232:235], v211 offset:21504
	ds_read_b128 v[236:239], v211 offset:22528
	ds_read_b128 v[240:243], v211 offset:23552
	global_load_lds_dwordx4 v0, s[76:77]
	s_add_i32 m0, s48, 0x2000
	s_add_u32 s48, s76, s16
	s_addc_u32 s49, s77, s17
	s_add_i32 s53, s62, 0x14000
	global_load_lds_dwordx4 v174, s[76:77]
	s_mov_b32 m0, s53
	global_load_lds_dwordx4 v0, s[48:49]
	s_add_i32 m0, s53, 0x2000
	v_lshl_add_u64 v[246:247], s[46:47], 0, v[170:171]
	global_load_lds_dwordx4 v174, s[48:49]
	s_mov_b32 m0, s63
	v_lshl_add_u64 v[248:249], s[46:47], 0, v[172:173]
	global_load_lds_dwordx4 v[246:247], off
	s_mov_b32 m0, s64
	s_nop 0
	global_load_lds_dwordx4 v[248:249], off
	s_waitcnt vmcnt(8) lgkmcnt(0)
	s_barrier
	v_mfma_f32_16x16x32_bf16 v[86:89], v[138:141], v[194:197], v[86:89]
	v_mfma_f32_16x16x32_bf16 v[14:17], v[146:149], v[194:197], v[14:17]
	v_mfma_f32_16x16x32_bf16 v[70:73], v[138:141], v[202:205], v[70:73]
	v_mfma_f32_16x16x32_bf16 v[6:9], v[146:149], v[202:205], v[6:9]
	v_mfma_f32_16x16x32_bf16 v[102:105], v[138:141], v[228:231], v[102:105]
	v_mfma_f32_16x16x32_bf16 v[30:33], v[146:149], v[228:231], v[30:33]
	v_mfma_f32_16x16x32_bf16 v[98:101], v[138:141], v[236:239], v[98:101]
	v_mfma_f32_16x16x32_bf16 v[26:29], v[146:149], v[236:239], v[26:29]
	v_mfma_f32_16x16x32_bf16 v[86:89], v[142:145], v[198:201], v[86:89]
	v_mfma_f32_16x16x32_bf16 v[14:17], v[150:153], v[198:201], v[14:17]
	v_mfma_f32_16x16x32_bf16 v[70:73], v[142:145], v[214:217], v[70:73]
	v_mfma_f32_16x16x32_bf16 v[6:9], v[150:153], v[214:217], v[6:9]
	v_mfma_f32_16x16x32_bf16 v[102:105], v[142:145], v[232:235], v[102:105]
	v_mfma_f32_16x16x32_bf16 v[30:33], v[150:153], v[232:235], v[30:33]
	v_mfma_f32_16x16x32_bf16 v[98:101], v[142:145], v[240:243], v[98:101]
	v_mfma_f32_16x16x32_bf16 v[26:29], v[150:153], v[240:243], v[26:29]
	v_mfma_f32_16x16x32_bf16 v[82:85], v[154:157], v[194:197], v[82:85]
	v_mfma_f32_16x16x32_bf16 v[10:13], v[162:165], v[194:197], v[10:13]
	v_mfma_f32_16x16x32_bf16 v[66:69], v[154:157], v[202:205], v[66:69]
	v_mfma_f32_16x16x32_bf16 v[2:5], v[162:165], v[202:205], v[2:5]
	v_mfma_f32_16x16x32_bf16 v[94:97], v[154:157], v[228:231], v[94:97]
	v_mfma_f32_16x16x32_bf16 v[22:25], v[162:165], v[228:231], v[22:25]
	v_mfma_f32_16x16x32_bf16 v[90:93], v[154:157], v[236:239], v[90:93]
	v_mfma_f32_16x16x32_bf16 v[18:21], v[162:165], v[236:239], v[18:21]
	v_mfma_f32_16x16x32_bf16 v[82:85], v[158:161], v[198:201], v[82:85]
	v_mfma_f32_16x16x32_bf16 v[10:13], v[166:169], v[198:201], v[10:13]
	v_mfma_f32_16x16x32_bf16 v[66:69], v[158:161], v[214:217], v[66:69]
	v_mfma_f32_16x16x32_bf16 v[2:5], v[166:169], v[214:217], v[2:5]
	v_mfma_f32_16x16x32_bf16 v[94:97], v[158:161], v[232:235], v[94:97]
	v_mfma_f32_16x16x32_bf16 v[22:25], v[166:169], v[232:235], v[22:25]
	v_mfma_f32_16x16x32_bf16 v[90:93], v[158:161], v[240:243], v[90:93]
	v_mfma_f32_16x16x32_bf16 v[18:21], v[166:169], v[240:243], v[18:21]
	s_barrier
; #define PG8_STAGE(bufoff, gbase, voff) do { _Pragma("unroll") for (int _i = 0; _i < 2; ++_i) \
;         __builtin_amdgcn_global_load_lds((const unsigned*)((const char*)(gbase) + (voff)[_i]), (PG8_LAS unsigned*)(lds + (bufoff) + ldsw + _i * 8192), 16, 0, 0); } while (0)
; #define PG8_LDA(dst, b, h) do { _Pragma("unroll") for (int m = 0; m < 4; ++m) _Pragma("unroll") for (int k = 0; k < 2; ++k) dst[m][k] = *(const PG8_LAS bf16x8*)(lds + PG8_SA(b, h) + aoff + m * 2048 + k * 1024); } while (0)
; #define PG8_LDB(dst, b, h) do { _Pragma("unroll") for (int n = 0; n < 2; ++n) _Pragma("unroll") for (int k = 0; k < 2; ++k) dst[n][k] = *(const PG8_LAS bf16x8*)(lds + PG8_SB(b, h) + boff + n * 2048 + k * 1024); } while (0)
; #define PG8_MMA(ai, bj, At, Bt) do { __builtin_amdgcn_s_setprio(1); _Pragma("unroll") for (int m = 0; m < 4; ++m) _Pragma("unroll") for (int n = 0; n < 2; ++n) _Pragma("unroll") for (int k = 0; k < 2; ++k) \
;         acc[ai][bj][m][n] = __builtin_amdgcn_mfma_f32_16x16x32_bf16(Bt[n][k], At[m][k], acc[ai][bj][m][n], 0, 0, 0); __builtin_amdgcn_s_setprio(0); } while (0)
; #define PG8_WAIT_V(n) asm volatile("s_waitcnt vmcnt(" #n ")" ::: "memory")
; #define PG8_WAIT_L(n) asm volatile("s_waitcnt lgkmcnt(" #n ")" ::: "memory")
; #define PG8_BAR __builtin_amdgcn_s_barrier()
; #define PG8_SCHED __builtin_amdgcn_sched_barrier(0)
; template <class Epi, class Sched, bool ALIGN_EPI = false, bool SP2 = false>
; __device__ __forceinline__ void gemm_phase(PG8_LAS unsigned char* lds, const Gemm g, const Sched& S, const Epi& E, const int wv) {
;     ...
;             PG8_LDB(B0, 1, 0); PG8_LDB(B1, 1, 1); PG8_SCHED; PG8_LDA(At, 1, 0); PG8_STAGE(PG8_SA(0, 1), a2 + hstepA, voffA);
;             PG8_WAIT_V(8); PG8_WAIT_L(0); PG8_BAR; PG8_MMA(0, 0, At, B0); PG8_MMA(0, 1, At, B1); PG8_BAR; PG8_SCHED;
;             PG8_LDA(At, 1, 1); PG8_STAGE(PG8_SB(1, 0), b3, voffB); PG8_STAGE(PG8_SB(1, 1), b3 + hstepB, voffB); PG8_STAGE(PG8_SA(1, 0), a3, voffA);
;             PG8_WAIT_V(8); PG8_WAIT_L(0); PG8_BAR; PG8_MMA(1, 0, At, B0); PG8_MMA(1, 1, At, B1); PG8_BAR; PG8_SCHED;
	ds_read_b128 v[138:141], v213
	ds_read_b128 v[142:145], v213 offset:1024
	ds_read_b128 v[146:149], v213 offset:2048
	ds_read_b128 v[150:153], v213 offset:3072
	ds_read_b128 v[154:157], v227
	ds_read_b128 v[158:161], v227 offset:1024
	ds_read_b128 v[162:165], v227 offset:2048
	ds_read_b128 v[166:169], v227 offset:3072
	s_add_u32 s46, s46, 0x80000
	s_addc_u32 s47, s47, 0
	s_mov_b32 m0, s65
	ds_read_b128 v[194:197], v211 offset:32768
	ds_read_b128 v[198:201], v211 offset:33792
	ds_read_b128 v[202:205], v211 offset:34816
	ds_read_b128 v[214:217], v211 offset:35840
	ds_read_b128 v[228:231], v211 offset:36864
	ds_read_b128 v[232:235], v211 offset:37888
	ds_read_b128 v[236:239], v211 offset:38912
	ds_read_b128 v[240:243], v211 offset:39936
	global_load_lds_dwordx4 v170, s[46:47]
	s_mov_b32 m0, s66
	s_nop 0
	global_load_lds_dwordx4 v172, s[46:47]
	s_waitcnt vmcnt(8) lgkmcnt(0)
	s_barrier
	v_mfma_f32_16x16x32_bf16 v[118:121], v[138:141], v[194:197], v[118:121]
	v_mfma_f32_16x16x32_bf16 v[46:49], v[146:149], v[194:197], v[46:49]
	v_mfma_f32_16x16x32_bf16 v[110:113], v[138:141], v[202:205], v[110:113]
	v_mfma_f32_16x16x32_bf16 v[38:41], v[146:149], v[202:205], v[38:41]
	v_mfma_f32_16x16x32_bf16 v[134:137], v[138:141], v[228:231], v[134:137]
	v_mfma_f32_16x16x32_bf16 v[62:65], v[146:149], v[228:231], v[62:65]
	v_mfma_f32_16x16x32_bf16 v[130:133], v[138:141], v[236:239], v[130:133]
	v_mfma_f32_16x16x32_bf16 v[58:61], v[146:149], v[236:239], v[58:61]
	v_mfma_f32_16x16x32_bf16 v[118:121], v[142:145], v[198:201], v[118:121]
	v_mfma_f32_16x16x32_bf16 v[46:49], v[150:153], v[198:201], v[46:49]
	v_mfma_f32_16x16x32_bf16 v[110:113], v[142:145], v[214:217], v[110:113]
	v_mfma_f32_16x16x32_bf16 v[38:41], v[150:153], v[214:217], v[38:41]
	v_mfma_f32_16x16x32_bf16 v[134:137], v[142:145], v[232:235], v[134:137]
	v_mfma_f32_16x16x32_bf16 v[62:65], v[150:153], v[232:235], v[62:65]
	v_mfma_f32_16x16x32_bf16 v[130:133], v[142:145], v[240:243], v[130:133]
	v_mfma_f32_16x16x32_bf16 v[58:61], v[150:153], v[240:243], v[58:61]
	v_mfma_f32_16x16x32_bf16 v[114:117], v[154:157], v[194:197], v[114:117]
	v_mfma_f32_16x16x32_bf16 v[42:45], v[162:165], v[194:197], v[42:45]
	v_mfma_f32_16x16x32_bf16 v[106:109], v[154:157], v[202:205], v[106:109]
	v_mfma_f32_16x16x32_bf16 v[34:37], v[162:165], v[202:205], v[34:37]
	v_mfma_f32_16x16x32_bf16 v[126:129], v[154:157], v[228:231], v[126:129]
	v_mfma_f32_16x16x32_bf16 v[54:57], v[162:165], v[228:231], v[54:57]
	v_mfma_f32_16x16x32_bf16 v[122:125], v[154:157], v[236:239], v[122:125]
	v_mfma_f32_16x16x32_bf16 v[50:53], v[162:165], v[236:239], v[50:53]
	v_mfma_f32_16x16x32_bf16 v[114:117], v[158:161], v[198:201], v[114:117]
	v_mfma_f32_16x16x32_bf16 v[42:45], v[166:169], v[198:201], v[42:45]
	v_mfma_f32_16x16x32_bf16 v[106:109], v[158:161], v[214:217], v[106:109]
	v_mfma_f32_16x16x32_bf16 v[34:37], v[166:169], v[214:217], v[34:37]
	v_mfma_f32_16x16x32_bf16 v[126:129], v[158:161], v[232:235], v[126:129]
	v_mfma_f32_16x16x32_bf16 v[54:57], v[166:169], v[232:235], v[54:57]
	v_mfma_f32_16x16x32_bf16 v[122:125], v[158:161], v[240:243], v[122:125]
	v_mfma_f32_16x16x32_bf16 v[50:53], v[166:169], v[240:243], v[50:53]
	s_barrier
	s_add_i32 s46, s62, 0x18000
	s_add_i32 m0, s46, 0xffffff80
	ds_read_b128 v[194:197], v211 offset:49152
	ds_read_b128 v[198:201], v211 offset:50176
	ds_read_b128 v[202:205], v211 offset:51200
	ds_read_b128 v[214:217], v211 offset:52224
	ds_read_b128 v[228:231], v211 offset:53248
	ds_read_b128 v[232:235], v211 offset:54272
	ds_read_b128 v[236:239], v211 offset:55296
	ds_read_b128 v[240:243], v211 offset:56320
	global_load_lds_dwordx4 v0, s[76:77] offset:128
	s_add_i32 m0, s46, 0x1f80
	s_add_i32 s46, s62, 0x1c000
	global_load_lds_dwordx4 v174, s[76:77] offset:128
	s_add_i32 m0, s46, 0xffffff80
	s_nop 0
	global_load_lds_dwordx4 v0, s[48:49] offset:128
	s_add_i32 m0, s46, 0x1f80
	s_nop 0
	global_load_lds_dwordx4 v174, s[48:49] offset:128
	s_add_i32 m0, s69, 0xffffff80
	s_nop 0
	global_load_lds_dwordx4 v[246:247], off offset:128
	s_add_i32 m0, s70, 0xffffff80
	s_nop 0
	global_load_lds_dwordx4 v[248:249], off offset:128
	s_waitcnt vmcnt(8) lgkmcnt(0)
	s_barrier
	v_mfma_f32_16x16x32_bf16 v[86:89], v[138:141], v[194:197], v[86:89]
	v_mfma_f32_16x16x32_bf16 v[14:17], v[146:149], v[194:197], v[14:17]
	v_mfma_f32_16x16x32_bf16 v[70:73], v[138:141], v[202:205], v[70:73]
	v_mfma_f32_16x16x32_bf16 v[6:9], v[146:149], v[202:205], v[6:9]
	v_mfma_f32_16x16x32_bf16 v[102:105], v[138:141], v[228:231], v[102:105]
	v_mfma_f32_16x16x32_bf16 v[30:33], v[146:149], v[228:231], v[30:33]
	v_mfma_f32_16x16x32_bf16 v[98:101], v[138:141], v[236:239], v[98:101]
	v_mfma_f32_16x16x32_bf16 v[26:29], v[146:149], v[236:239], v[26:29]
	v_mfma_f32_16x16x32_bf16 v[86:89], v[142:145], v[198:201], v[86:89]
	v_mfma_f32_16x16x32_bf16 v[14:17], v[150:153], v[198:201], v[14:17]
	v_mfma_f32_16x16x32_bf16 v[70:73], v[142:145], v[214:217], v[70:73]
	v_mfma_f32_16x16x32_bf16 v[6:9], v[150:153], v[214:217], v[6:9]
	v_mfma_f32_16x16x32_bf16 v[102:105], v[142:145], v[232:235], v[102:105]
	v_mfma_f32_16x16x32_bf16 v[30:33], v[150:153], v[232:235], v[30:33]
	v_mfma_f32_16x16x32_bf16 v[98:101], v[142:145], v[240:243], v[98:101]
	v_mfma_f32_16x16x32_bf16 v[26:29], v[150:153], v[240:243], v[26:29]
	v_mfma_f32_16x16x32_bf16 v[82:85], v[154:157], v[194:197], v[82:85]
	v_mfma_f32_16x16x32_bf16 v[10:13], v[162:165], v[194:197], v[10:13]
	v_mfma_f32_16x16x32_bf16 v[66:69], v[154:157], v[202:205], v[66:69]
	v_mfma_f32_16x16x32_bf16 v[2:5], v[162:165], v[202:205], v[2:5]
	v_mfma_f32_16x16x32_bf16 v[94:97], v[154:157], v[228:231], v[94:97]
	v_mfma_f32_16x16x32_bf16 v[22:25], v[162:165], v[228:231], v[22:25]
	v_mfma_f32_16x16x32_bf16 v[90:93], v[154:157], v[236:239], v[90:93]
	v_mfma_f32_16x16x32_bf16 v[18:21], v[162:165], v[236:239], v[18:21]
	v_mfma_f32_16x16x32_bf16 v[82:85], v[158:161], v[198:201], v[82:85]
	v_mfma_f32_16x16x32_bf16 v[10:13], v[166:169], v[198:201], v[10:13]
	v_mfma_f32_16x16x32_bf16 v[66:69], v[158:161], v[214:217], v[66:69]
	v_mfma_f32_16x16x32_bf16 v[2:5], v[166:169], v[214:217], v[2:5]
	v_mfma_f32_16x16x32_bf16 v[94:97], v[158:161], v[232:235], v[94:97]
	v_mfma_f32_16x16x32_bf16 v[22:25], v[166:169], v[232:235], v[22:25]
	v_mfma_f32_16x16x32_bf16 v[90:93], v[158:161], v[240:243], v[90:93]
	v_mfma_f32_16x16x32_bf16 v[18:21], v[166:169], v[240:243], v[18:21]
	s_barrier
	s_add_u32 s35, s35, 0x100
	s_addc_u32 s51, s51, 0
	s_cmp_ge_i32 s52, s67
	s_mov_b64 s[48:49], s[14:15]
	s_mov_b32 s46, s52
	s_cbranch_scc0 .LBB0_809
	s_movk_i32 s75, 0x2000
	s_movk_i32 s76, 0x3000
	s_and_b64 vcc, exec, s[30:31]
	s_cbranch_vccz .LBB0_784

; #define PG8_STAGE(bufoff, gbase, voff) do { _Pragma("unroll") for (int _i = 0; _i < 2; ++_i) \
;         __builtin_amdgcn_global_load_lds((const unsigned*)((const char*)(gbase) + (voff)[_i]), (PG8_LAS unsigned*)(lds + (bufoff) + ldsw + _i * 8192), 16, 0, 0); } while (0)
; #define PG8_LDA(dst, b, h) do { _Pragma("unroll") for (int m = 0; m < 4; ++m) _Pragma("unroll") for (int k = 0; k < 2; ++k) dst[m][k] = *(const PG8_LAS bf16x8*)(lds + PG8_SA(b, h) + aoff + m * 2048 + k * 1024); } while (0)
; #define PG8_LDB(dst, b, h) do { _Pragma("unroll") for (int n = 0; n < 2; ++n) _Pragma("unroll") for (int k = 0; k < 2; ++k) dst[n][k] = *(const PG8_LAS bf16x8*)(lds + PG8_SB(b, h) + boff + n * 2048 + k * 1024); } while (0)
; #define PG8_MMA(ai, bj, At, Bt) do { __builtin_amdgcn_s_setprio(1); _Pragma("unroll") for (int m = 0; m < 4; ++m) _Pragma("unroll") for (int n = 0; n < 2; ++n) _Pragma("unroll") for (int k = 0; k < 2; ++k) \
;         acc[ai][bj][m][n] = __builtin_amdgcn_mfma_f32_16x16x32_bf16(Bt[n][k], At[m][k], acc[ai][bj][m][n], 0, 0, 0); __builtin_amdgcn_s_setprio(0); } while (0)
; #define PG8_WAIT_V(n) asm volatile("s_waitcnt vmcnt(" #n ")" ::: "memory")
; #define PG8_WAIT_L(n) asm volatile("s_waitcnt lgkmcnt(" #n ")" ::: "memory")
; template <class Epi, class Sched, bool ALIGN_EPI = false, bool SP2 = false>
; __device__ __forceinline__ void gemm_phase(PG8_LAS unsigned char* lds, const Gemm g, const Sched& S, const Epi& E, const int wv) {
;     ...
;             const bool last = (t == nt - 2);
;             const char* a1 = cA + (size_t)(t + 1) * kstep;
;             const char* a2 = last ? nA : cA + (size_t)(t + 2) * kstep; const char* b2 = last ? nB : cB + (size_t)(t + 2) * kstep;
;             const char* a3 = a2 + kstep; const char* b3 = b2 + kstep;
;             if (last && has_next) S.a_ready(nxt);
;             if constexpr (SP2) {
;             PG8_LDB(B0, 0, 0); PG8_LDB(B1, 0, 1); PG8_SCHED; PG8_LDA(At, 0, 0); PG8_STAGE(PG8_SA(1, 1), a1 + hstepA, voffA);
;             PG8_WAIT_V(8); PG8_WAIT_L(0); PG8_BAR; PG8_MMA(0, 0, At, B0); PG8_MMA(0, 1, At, B1); PG8_BAR; PG8_SCHED;
;             PG8_LDA(At, 0, 1); PG8_STAGE(PG8_SB(0, 0), b2, voffB); PG8_STAGE(PG8_SB(0, 1), b2 + hstepB, voffB); PG8_STAGE(PG8_SA(0, 0), a2, voffA);
;             PG8_WAIT_V(8); PG8_WAIT_L(0); PG8_BAR; PG8_MMA(1, 0, At, B0); PG8_MMA(1, 1, At, B1); PG8_BAR; PG8_SCHED;
.LBB0_990:
	s_add_i32 s67, s44, 2
	s_add_u32 s34, s30, 0x100
	s_addc_u32 s35, s31, 0
	s_cmp_eq_u32 s59, s44
	s_cselect_b32 s45, s13, s35
	s_cselect_b32 s44, s12, s34
	s_cselect_b32 s69, s15, s66
	s_cselect_b32 s68, s14, s65
	ds_read_b128 v[114:117], v197
	ds_read_b128 v[126:129], v197 offset:1024
	ds_read_b128 v[138:141], v197 offset:2048
	ds_read_b128 v[142:145], v197 offset:3072
	ds_read_b128 v[146:149], v201
	ds_read_b128 v[150:153], v201 offset:1024
	ds_read_b128 v[154:157], v201 offset:2048
	ds_read_b128 v[158:161], v201 offset:3072
	s_add_i32 m0, s52, 0xc000
	ds_read_b128 v[162:165], v235
	ds_read_b128 v[166:169], v235 offset:1024
	ds_read_b128 v[170:173], v235 offset:2048
	ds_read_b128 v[174:177], v235 offset:3072
	ds_read_b128 v[178:181], v235 offset:4096
	ds_read_b128 v[182:185], v235 offset:5120
	ds_read_b128 v[204:207], v235 offset:6144
	ds_read_b128 v[208:211], v235 offset:7168
	global_load_lds_dwordx4 v200, s[30:31]
	s_add_i32 m0, s52, 0xe000
	s_nop 0
	global_load_lds_dwordx4 v202, s[30:31]
	s_waitcnt vmcnt(8) lgkmcnt(0)
	s_barrier
	v_mfma_f32_16x16x32_bf16 v[134:137], v[114:117], v[162:165], v[134:137]
	v_mfma_f32_16x16x32_bf16 v[130:133], v[138:141], v[162:165], v[130:133]
	v_mfma_f32_16x16x32_bf16 v[110:113], v[114:117], v[170:173], v[110:113]
	v_mfma_f32_16x16x32_bf16 v[106:109], v[138:141], v[170:173], v[106:109]
	v_mfma_f32_16x16x32_bf16 v[94:97], v[114:117], v[178:181], v[94:97]
	v_mfma_f32_16x16x32_bf16 v[90:93], v[138:141], v[178:181], v[90:93]
	v_mfma_f32_16x16x32_bf16 v[78:81], v[114:117], v[204:207], v[78:81]
	v_mfma_f32_16x16x32_bf16 v[74:77], v[138:141], v[204:207], v[74:77]
	v_mfma_f32_16x16x32_bf16 v[134:137], v[126:129], v[166:169], v[134:137]
	v_mfma_f32_16x16x32_bf16 v[130:133], v[142:145], v[166:169], v[130:133]
	v_mfma_f32_16x16x32_bf16 v[110:113], v[126:129], v[174:177], v[110:113]
	v_mfma_f32_16x16x32_bf16 v[106:109], v[142:145], v[174:177], v[106:109]
	v_mfma_f32_16x16x32_bf16 v[94:97], v[126:129], v[182:185], v[94:97]
	v_mfma_f32_16x16x32_bf16 v[90:93], v[142:145], v[182:185], v[90:93]
	v_mfma_f32_16x16x32_bf16 v[78:81], v[126:129], v[208:211], v[78:81]
	v_mfma_f32_16x16x32_bf16 v[74:77], v[142:145], v[208:211], v[74:77]
	v_mfma_f32_16x16x32_bf16 v[122:125], v[146:149], v[162:165], v[122:125]
	v_mfma_f32_16x16x32_bf16 v[118:121], v[154:157], v[162:165], v[118:121]
	v_mfma_f32_16x16x32_bf16 v[102:105], v[146:149], v[170:173], v[102:105]
	v_mfma_f32_16x16x32_bf16 v[98:101], v[154:157], v[170:173], v[98:101]
	v_mfma_f32_16x16x32_bf16 v[86:89], v[146:149], v[178:181], v[86:89]
	v_mfma_f32_16x16x32_bf16 v[82:85], v[154:157], v[178:181], v[82:85]
	v_mfma_f32_16x16x32_bf16 v[70:73], v[146:149], v[204:207], v[70:73]
	v_mfma_f32_16x16x32_bf16 v[66:69], v[154:157], v[204:207], v[66:69]
	v_mfma_f32_16x16x32_bf16 v[122:125], v[150:153], v[166:169], v[122:125]
	v_mfma_f32_16x16x32_bf16 v[118:121], v[158:161], v[166:169], v[118:121]
	v_mfma_f32_16x16x32_bf16 v[102:105], v[150:153], v[174:177], v[102:105]
	v_mfma_f32_16x16x32_bf16 v[98:101], v[158:161], v[174:177], v[98:101]
	v_mfma_f32_16x16x32_bf16 v[86:89], v[150:153], v[182:185], v[86:89]
	v_mfma_f32_16x16x32_bf16 v[82:85], v[158:161], v[182:185], v[82:85]
	v_mfma_f32_16x16x32_bf16 v[70:73], v[150:153], v[208:211], v[70:73]
	v_mfma_f32_16x16x32_bf16 v[66:69], v[158:161], v[208:211], v[66:69]
	s_barrier
	s_add_i32 s30, s47, 0x10000
	v_lshl_add_u64 v[190:191], s[68:69], 0, v[0:1]
	s_mov_b32 m0, s30
	ds_read_b128 v[162:165], v235 offset:16384
	ds_read_b128 v[166:169], v235 offset:17408
	ds_read_b128 v[170:173], v235 offset:18432
	ds_read_b128 v[174:177], v235 offset:19456
	ds_read_b128 v[178:181], v235 offset:20480
	ds_read_b128 v[182:185], v235 offset:21504
	ds_read_b128 v[204:207], v235 offset:22528
	ds_read_b128 v[208:211], v235 offset:23552
	global_load_lds_dwordx4 v[190:191], off
	s_add_i32 m0, s30, 0x2000
	s_add_u32 s30, s68, s2
	v_lshl_add_u64 v[192:193], s[68:69], 0, v[198:199]
	s_addc_u32 s31, s69, s3
	s_add_i32 s68, s47, 0x14000
	global_load_lds_dwordx4 v[192:193], off
	v_lshl_add_u64 v[212:213], s[30:31], 0, v[0:1]
	s_mov_b32 m0, s68
	v_lshl_add_u64 v[214:215], s[30:31], 0, v[198:199]
	global_load_lds_dwordx4 v[212:213], off
	s_add_i32 m0, s68, 0x2000
	global_load_lds_dwordx4 v[214:215], off
	s_mov_b32 m0, s52
	global_load_lds_dwordx4 v194, s[44:45]
	s_mov_b32 m0, s53
	s_nop 0
	global_load_lds_dwordx4 v196, s[44:45]
	s_waitcnt vmcnt(8) lgkmcnt(0)
	s_barrier
	v_mfma_f32_16x16x32_bf16 v[62:65], v[114:117], v[162:165], v[62:65]
	v_mfma_f32_16x16x32_bf16 v[58:61], v[138:141], v[162:165], v[58:61]
	v_mfma_f32_16x16x32_bf16 v[46:49], v[114:117], v[170:173], v[46:49]
	v_mfma_f32_16x16x32_bf16 v[42:45], v[138:141], v[170:173], v[42:45]
	v_mfma_f32_16x16x32_bf16 v[30:33], v[114:117], v[178:181], v[30:33]
	v_mfma_f32_16x16x32_bf16 v[26:29], v[138:141], v[178:181], v[26:29]
	v_mfma_f32_16x16x32_bf16 v[14:17], v[114:117], v[204:207], v[14:17]
	v_mfma_f32_16x16x32_bf16 v[10:13], v[138:141], v[204:207], v[10:13]
	v_mfma_f32_16x16x32_bf16 v[62:65], v[126:129], v[166:169], v[62:65]
	v_mfma_f32_16x16x32_bf16 v[58:61], v[142:145], v[166:169], v[58:61]
	v_mfma_f32_16x16x32_bf16 v[46:49], v[126:129], v[174:177], v[46:49]
	v_mfma_f32_16x16x32_bf16 v[42:45], v[142:145], v[174:177], v[42:45]
	v_mfma_f32_16x16x32_bf16 v[30:33], v[126:129], v[182:185], v[30:33]
	v_mfma_f32_16x16x32_bf16 v[26:29], v[142:145], v[182:185], v[26:29]
	v_mfma_f32_16x16x32_bf16 v[14:17], v[126:129], v[208:211], v[14:17]
	v_mfma_f32_16x16x32_bf16 v[10:13], v[142:145], v[208:211], v[10:13]
	v_mfma_f32_16x16x32_bf16 v[54:57], v[146:149], v[162:165], v[54:57]
	v_mfma_f32_16x16x32_bf16 v[50:53], v[154:157], v[162:165], v[50:53]
	v_mfma_f32_16x16x32_bf16 v[38:41], v[146:149], v[170:173], v[38:41]
	v_mfma_f32_16x16x32_bf16 v[34:37], v[154:157], v[170:173], v[34:37]
	v_mfma_f32_16x16x32_bf16 v[22:25], v[146:149], v[178:181], v[22:25]
	v_mfma_f32_16x16x32_bf16 v[18:21], v[154:157], v[178:181], v[18:21]
	v_mfma_f32_16x16x32_bf16 v[6:9], v[146:149], v[204:207], v[6:9]
	v_mfma_f32_16x16x32_bf16 v[2:5], v[154:157], v[204:207], v[2:5]
	v_mfma_f32_16x16x32_bf16 v[54:57], v[150:153], v[166:169], v[54:57]
	v_mfma_f32_16x16x32_bf16 v[50:53], v[158:161], v[166:169], v[50:53]
	v_mfma_f32_16x16x32_bf16 v[38:41], v[150:153], v[174:177], v[38:41]
	v_mfma_f32_16x16x32_bf16 v[34:37], v[158:161], v[174:177], v[34:37]
	v_mfma_f32_16x16x32_bf16 v[22:25], v[150:153], v[182:185], v[22:25]
	v_mfma_f32_16x16x32_bf16 v[18:21], v[158:161], v[182:185], v[18:21]
	v_mfma_f32_16x16x32_bf16 v[6:9], v[150:153], v[208:211], v[6:9]
	v_mfma_f32_16x16x32_bf16 v[2:5], v[158:161], v[208:211], v[2:5]
	s_barrier
; #define PG8_STAGE(bufoff, gbase, voff) do { _Pragma("unroll") for (int _i = 0; _i < 2; ++_i) \
;         __builtin_amdgcn_global_load_lds((const unsigned*)((const char*)(gbase) + (voff)[_i]), (PG8_LAS unsigned*)(lds + (bufoff) + ldsw + _i * 8192), 16, 0, 0); } while (0)
; #define PG8_LDA(dst, b, h) do { _Pragma("unroll") for (int m = 0; m < 4; ++m) _Pragma("unroll") for (int k = 0; k < 2; ++k) dst[m][k] = *(const PG8_LAS bf16x8*)(lds + PG8_SA(b, h) + aoff + m * 2048 + k * 1024); } while (0)
; #define PG8_LDB(dst, b, h) do { _Pragma("unroll") for (int n = 0; n < 2; ++n) _Pragma("unroll") for (int k = 0; k < 2; ++k) dst[n][k] = *(const PG8_LAS bf16x8*)(lds + PG8_SB(b, h) + boff + n * 2048 + k * 1024); } while (0)
; #define PG8_MMA(ai, bj, At, Bt) do { __builtin_amdgcn_s_setprio(1); _Pragma("unroll") for (int m = 0; m < 4; ++m) _Pragma("unroll") for (int n = 0; n < 2; ++n) _Pragma("unroll") for (int k = 0; k < 2; ++k) \
;         acc[ai][bj][m][n] = __builtin_amdgcn_mfma_f32_16x16x32_bf16(Bt[n][k], At[m][k], acc[ai][bj][m][n], 0, 0, 0); __builtin_amdgcn_s_setprio(0); } while (0)
; #define PG8_WAIT_V(n) asm volatile("s_waitcnt vmcnt(" #n ")" ::: "memory")
; #define PG8_WAIT_L(n) asm volatile("s_waitcnt lgkmcnt(" #n ")" ::: "memory")
; #define PG8_BAR __builtin_amdgcn_s_barrier()
; #define PG8_SCHED __builtin_amdgcn_sched_barrier(0)
; template <class Epi, class Sched, bool ALIGN_EPI = false, bool SP2 = false>
; __device__ __forceinline__ void gemm_phase(PG8_LAS unsigned char* lds, const Gemm g, const Sched& S, const Epi& E, const int wv) {
;     ...
;             PG8_LDB(B0, 1, 0); PG8_LDB(B1, 1, 1); PG8_SCHED; PG8_LDA(At, 1, 0); PG8_STAGE(PG8_SA(0, 1), a2 + hstepA, voffA);
;             PG8_WAIT_V(8); PG8_WAIT_L(0); PG8_BAR; PG8_MMA(0, 0, At, B0); PG8_MMA(0, 1, At, B1); PG8_BAR; PG8_SCHED;
;             PG8_LDA(At, 1, 1); PG8_STAGE(PG8_SB(1, 0), b3, voffB); PG8_STAGE(PG8_SB(1, 1), b3 + hstepB, voffB); PG8_STAGE(PG8_SA(1, 0), a3, voffA);
;             PG8_WAIT_V(8); PG8_WAIT_L(0); PG8_BAR; PG8_MMA(1, 0, At, B0); PG8_MMA(1, 1, At, B1); PG8_BAR; PG8_SCHED;
	ds_read_b128 v[114:117], v203
	ds_read_b128 v[126:129], v203 offset:1024
	ds_read_b128 v[138:141], v203 offset:2048
	ds_read_b128 v[142:145], v203 offset:3072
	ds_read_b128 v[146:149], v216
	ds_read_b128 v[150:153], v216 offset:1024
	ds_read_b128 v[154:157], v216 offset:2048
	ds_read_b128 v[158:161], v216 offset:3072
	s_add_u32 s30, s44, 0x180000
	s_addc_u32 s31, s45, 0
	s_mov_b32 m0, s54
	ds_read_b128 v[162:165], v235 offset:32768
	ds_read_b128 v[166:169], v235 offset:33792
	ds_read_b128 v[170:173], v235 offset:34816
	ds_read_b128 v[174:177], v235 offset:35840
	ds_read_b128 v[178:181], v235 offset:36864
	ds_read_b128 v[182:185], v235 offset:37888
	ds_read_b128 v[204:207], v235 offset:38912
	ds_read_b128 v[208:211], v235 offset:39936
	global_load_lds_dwordx4 v194, s[30:31]
	s_mov_b32 m0, s55
	s_nop 0
	global_load_lds_dwordx4 v196, s[30:31]
	s_waitcnt vmcnt(8) lgkmcnt(0)
	s_barrier
	v_mfma_f32_16x16x32_bf16 v[134:137], v[114:117], v[162:165], v[134:137]
	v_mfma_f32_16x16x32_bf16 v[130:133], v[138:141], v[162:165], v[130:133]
	v_mfma_f32_16x16x32_bf16 v[110:113], v[114:117], v[170:173], v[110:113]
	v_mfma_f32_16x16x32_bf16 v[106:109], v[138:141], v[170:173], v[106:109]
	v_mfma_f32_16x16x32_bf16 v[94:97], v[114:117], v[178:181], v[94:97]
	v_mfma_f32_16x16x32_bf16 v[90:93], v[138:141], v[178:181], v[90:93]
	v_mfma_f32_16x16x32_bf16 v[78:81], v[114:117], v[204:207], v[78:81]
	v_mfma_f32_16x16x32_bf16 v[74:77], v[138:141], v[204:207], v[74:77]
	v_mfma_f32_16x16x32_bf16 v[134:137], v[126:129], v[166:169], v[134:137]
	v_mfma_f32_16x16x32_bf16 v[130:133], v[142:145], v[166:169], v[130:133]
	v_mfma_f32_16x16x32_bf16 v[110:113], v[126:129], v[174:177], v[110:113]
	v_mfma_f32_16x16x32_bf16 v[106:109], v[142:145], v[174:177], v[106:109]
	v_mfma_f32_16x16x32_bf16 v[94:97], v[126:129], v[182:185], v[94:97]
	v_mfma_f32_16x16x32_bf16 v[90:93], v[142:145], v[182:185], v[90:93]
	v_mfma_f32_16x16x32_bf16 v[78:81], v[126:129], v[208:211], v[78:81]
	v_mfma_f32_16x16x32_bf16 v[74:77], v[142:145], v[208:211], v[74:77]
	v_mfma_f32_16x16x32_bf16 v[122:125], v[146:149], v[162:165], v[122:125]
	v_mfma_f32_16x16x32_bf16 v[118:121], v[154:157], v[162:165], v[118:121]
	v_mfma_f32_16x16x32_bf16 v[102:105], v[146:149], v[170:173], v[102:105]
	v_mfma_f32_16x16x32_bf16 v[98:101], v[154:157], v[170:173], v[98:101]
	v_mfma_f32_16x16x32_bf16 v[86:89], v[146:149], v[178:181], v[86:89]
	v_mfma_f32_16x16x32_bf16 v[82:85], v[154:157], v[178:181], v[82:85]
	v_mfma_f32_16x16x32_bf16 v[70:73], v[146:149], v[204:207], v[70:73]
	v_mfma_f32_16x16x32_bf16 v[66:69], v[154:157], v[204:207], v[66:69]
	v_mfma_f32_16x16x32_bf16 v[122:125], v[150:153], v[166:169], v[122:125]
	v_mfma_f32_16x16x32_bf16 v[118:121], v[158:161], v[166:169], v[118:121]
	v_mfma_f32_16x16x32_bf16 v[102:105], v[150:153], v[174:177], v[102:105]
	v_mfma_f32_16x16x32_bf16 v[98:101], v[158:161], v[174:177], v[98:101]
	v_mfma_f32_16x16x32_bf16 v[86:89], v[150:153], v[182:185], v[86:89]
	v_mfma_f32_16x16x32_bf16 v[82:85], v[158:161], v[182:185], v[82:85]
	v_mfma_f32_16x16x32_bf16 v[70:73], v[150:153], v[208:211], v[70:73]
	v_mfma_f32_16x16x32_bf16 v[66:69], v[158:161], v[208:211], v[66:69]
	s_barrier
	s_add_i32 s30, s47, 0x18000
	s_add_i32 m0, s30, 0xffffff80
	ds_read_b128 v[162:165], v235 offset:49152
	ds_read_b128 v[166:169], v235 offset:50176
	ds_read_b128 v[170:173], v235 offset:51200
	ds_read_b128 v[174:177], v235 offset:52224
	ds_read_b128 v[178:181], v235 offset:53248
	ds_read_b128 v[182:185], v235 offset:54272
	ds_read_b128 v[204:207], v235 offset:55296
	ds_read_b128 v[208:211], v235 offset:56320
	global_load_lds_dwordx4 v[190:191], off offset:128
	s_add_i32 m0, s30, 0x1f80
	s_add_i32 s30, s47, 0x1c000
	global_load_lds_dwordx4 v[192:193], off offset:128
	s_add_i32 m0, s30, 0xffffff80
	s_nop 0
	global_load_lds_dwordx4 v[212:213], off offset:128
	s_add_i32 m0, s30, 0x1f80
	s_nop 0
	global_load_lds_dwordx4 v[214:215], off offset:128
	s_add_i32 m0, s57, 0xffffff80
	s_nop 0
	global_load_lds_dwordx4 v194, s[44:45] offset:128
	s_add_i32 m0, s58, 0xffffff80
	s_nop 0
	global_load_lds_dwordx4 v196, s[44:45] offset:128
	s_waitcnt vmcnt(8) lgkmcnt(0)
	s_barrier
	v_mfma_f32_16x16x32_bf16 v[62:65], v[114:117], v[162:165], v[62:65]
	v_mfma_f32_16x16x32_bf16 v[58:61], v[138:141], v[162:165], v[58:61]
	v_mfma_f32_16x16x32_bf16 v[46:49], v[114:117], v[170:173], v[46:49]
	v_mfma_f32_16x16x32_bf16 v[42:45], v[138:141], v[170:173], v[42:45]
	v_mfma_f32_16x16x32_bf16 v[30:33], v[114:117], v[178:181], v[30:33]
	v_mfma_f32_16x16x32_bf16 v[26:29], v[138:141], v[178:181], v[26:29]
	v_mfma_f32_16x16x32_bf16 v[14:17], v[114:117], v[204:207], v[14:17]
	v_mfma_f32_16x16x32_bf16 v[10:13], v[138:141], v[204:207], v[10:13]
	v_mfma_f32_16x16x32_bf16 v[62:65], v[126:129], v[166:169], v[62:65]
	v_mfma_f32_16x16x32_bf16 v[58:61], v[142:145], v[166:169], v[58:61]
	v_mfma_f32_16x16x32_bf16 v[46:49], v[126:129], v[174:177], v[46:49]
	v_mfma_f32_16x16x32_bf16 v[42:45], v[142:145], v[174:177], v[42:45]
	v_mfma_f32_16x16x32_bf16 v[30:33], v[126:129], v[182:185], v[30:33]
	v_mfma_f32_16x16x32_bf16 v[26:29], v[142:145], v[182:185], v[26:29]
	v_mfma_f32_16x16x32_bf16 v[14:17], v[126:129], v[208:211], v[14:17]
	v_mfma_f32_16x16x32_bf16 v[10:13], v[142:145], v[208:211], v[10:13]
	v_mfma_f32_16x16x32_bf16 v[54:57], v[146:149], v[162:165], v[54:57]
	v_mfma_f32_16x16x32_bf16 v[50:53], v[154:157], v[162:165], v[50:53]
	v_mfma_f32_16x16x32_bf16 v[38:41], v[146:149], v[170:173], v[38:41]
	v_mfma_f32_16x16x32_bf16 v[34:37], v[154:157], v[170:173], v[34:37]
	v_mfma_f32_16x16x32_bf16 v[22:25], v[146:149], v[178:181], v[22:25]
	v_mfma_f32_16x16x32_bf16 v[18:21], v[154:157], v[178:181], v[18:21]
	v_mfma_f32_16x16x32_bf16 v[6:9], v[146:149], v[204:207], v[6:9]
	v_mfma_f32_16x16x32_bf16 v[2:5], v[154:157], v[204:207], v[2:5]
	v_mfma_f32_16x16x32_bf16 v[54:57], v[150:153], v[166:169], v[54:57]
	v_mfma_f32_16x16x32_bf16 v[50:53], v[158:161], v[166:169], v[50:53]
	v_mfma_f32_16x16x32_bf16 v[38:41], v[150:153], v[174:177], v[38:41]
	v_mfma_f32_16x16x32_bf16 v[34:37], v[158:161], v[174:177], v[34:37]
	v_mfma_f32_16x16x32_bf16 v[22:25], v[150:153], v[182:185], v[22:25]
	v_mfma_f32_16x16x32_bf16 v[18:21], v[158:161], v[182:185], v[18:21]
	v_mfma_f32_16x16x32_bf16 v[6:9], v[150:153], v[208:211], v[6:9]
	v_mfma_f32_16x16x32_bf16 v[2:5], v[158:161], v[208:211], v[2:5]
	s_barrier
	s_add_u32 s65, s65, 0x100
	s_addc_u32 s66, s66, 0
	s_cmp_ge_i32 s67, s56
	s_mov_b64 s[30:31], s[34:35]
	s_mov_b32 s44, s67
	s_cbranch_scc0 .LBB0_990
	s_movk_i32 s68, 0x4000
	s_movk_i32 s69, 0x6000
	s_mov_b32 s70, 0x18000
	s_mov_b32 s71, 0x3f317217
	v_readlane_b32 s67, v255, 30
	s_and_b64 vcc, exec, s[28:29]
	s_cbranch_vccz .LBB0_966

; #define PG8_STAGE(bufoff, gbase, voff) do { _Pragma("unroll") for (int _i = 0; _i < 2; ++_i) \
;         __builtin_amdgcn_global_load_lds((const unsigned*)((const char*)(gbase) + (voff)[_i]), (PG8_LAS unsigned*)(lds + (bufoff) + ldsw + _i * 8192), 16, 0, 0); } while (0)
; #define PG8_LDA(dst, b, h) do { _Pragma("unroll") for (int m = 0; m < 4; ++m) _Pragma("unroll") for (int k = 0; k < 2; ++k) dst[m][k] = *(const PG8_LAS bf16x8*)(lds + PG8_SA(b, h) + aoff + m * 2048 + k * 1024); } while (0)
; #define PG8_LDB(dst, b, h) do { _Pragma("unroll") for (int n = 0; n < 2; ++n) _Pragma("unroll") for (int k = 0; k < 2; ++k) dst[n][k] = *(const PG8_LAS bf16x8*)(lds + PG8_SB(b, h) + boff + n * 2048 + k * 1024); } while (0)
; #define PG8_MMA(ai, bj, At, Bt) do { __builtin_amdgcn_s_setprio(1); _Pragma("unroll") for (int m = 0; m < 4; ++m) _Pragma("unroll") for (int n = 0; n < 2; ++n) _Pragma("unroll") for (int k = 0; k < 2; ++k) \
;         acc[ai][bj][m][n] = __builtin_amdgcn_mfma_f32_16x16x32_bf16(Bt[n][k], At[m][k], acc[ai][bj][m][n], 0, 0, 0); __builtin_amdgcn_s_setprio(0); } while (0)
; #define PG8_WAIT_V(n) asm volatile("s_waitcnt vmcnt(" #n ")" ::: "memory")
; #define PG8_WAIT_L(n) asm volatile("s_waitcnt lgkmcnt(" #n ")" ::: "memory")
; template <class Epi, class Sched, bool ALIGN_EPI = false, bool SP2 = false>
; __device__ __forceinline__ void gemm_phase(PG8_LAS unsigned char* lds, const Gemm g, const Sched& S, const Epi& E, const int wv) {
;     ...
;             const bool last = (t == nt - 2);
;             const char* a1 = cA + (size_t)(t + 1) * kstep;
;             const char* a2 = last ? nA : cA + (size_t)(t + 2) * kstep; const char* b2 = last ? nB : cB + (size_t)(t + 2) * kstep;
;             const char* a3 = a2 + kstep; const char* b3 = b2 + kstep;
;             if (last && has_next) S.a_ready(nxt);
;             if constexpr (SP2) {
;             PG8_LDB(B0, 0, 0); PG8_LDB(B1, 0, 1); PG8_SCHED; PG8_LDA(At, 0, 0); PG8_STAGE(PG8_SA(1, 1), a1 + hstepA, voffA);
;             PG8_WAIT_V(8); PG8_WAIT_L(0); PG8_BAR; PG8_MMA(0, 0, At, B0); PG8_MMA(0, 1, At, B1); PG8_BAR; PG8_SCHED;
;             PG8_LDA(At, 0, 1); PG8_STAGE(PG8_SB(0, 0), b2, voffB); PG8_STAGE(PG8_SB(0, 1), b2 + hstepB, voffB); PG8_STAGE(PG8_SA(0, 0), a2, voffA);
;             PG8_WAIT_V(8); PG8_WAIT_L(0); PG8_BAR; PG8_MMA(1, 0, At, B0); PG8_MMA(1, 1, At, B1); PG8_BAR; PG8_SCHED;
.LBB0_1074:
	s_add_i32 s63, s30, 2
	s_add_u32 s64, s28, 0xfff80080
	s_addc_u32 s31, s29, -1
	s_cmp_eq_u32 s57, s30
	s_cselect_b32 s31, s17, s31
	s_cselect_b32 s30, s40, s64
	s_cselect_b32 s65, s19, s62
	s_cselect_b32 s64, s18, s41
	ds_read_b128 v[164:167], v147
	ds_read_b128 v[168:171], v147 offset:1024
	ds_read_b128 v[172:175], v147 offset:2048
	ds_read_b128 v[176:179], v147 offset:3072
	ds_read_b128 v[180:183], v149
	ds_read_b128 v[194:197], v149 offset:1024
	ds_read_b128 v[198:201], v149 offset:2048
	ds_read_b128 v[202:205], v149 offset:3072
	s_add_i32 m0, s47, 0xc000
	ds_read_b128 v[206:209], v163
	ds_read_b128 v[210:213], v163 offset:1024
	ds_read_b128 v[214:217], v163 offset:2048
	ds_read_b128 v[228:231], v163 offset:3072
	ds_read_b128 v[232:235], v163 offset:4096
	ds_read_b128 v[236:239], v163 offset:5120
	ds_read_b128 v[240:243], v163 offset:6144
	ds_read_b128 v[244:247], v163 offset:7168
	global_load_lds_dwordx4 v146, s[28:29]
	s_add_i32 m0, s47, 0xe000
	s_nop 0
	global_load_lds_dwordx4 v148, s[28:29]
	s_waitcnt vmcnt(8) lgkmcnt(0)
	s_barrier
	v_mfma_f32_16x16x32_bf16 v[130:133], v[164:167], v[206:209], v[130:133]
	v_mfma_f32_16x16x32_bf16 v[126:129], v[172:175], v[206:209], v[126:129]
	v_mfma_f32_16x16x32_bf16 v[114:117], v[164:167], v[214:217], v[114:117]
	v_mfma_f32_16x16x32_bf16 v[110:113], v[172:175], v[214:217], v[110:113]
	v_mfma_f32_16x16x32_bf16 v[98:101], v[164:167], v[232:235], v[98:101]
	v_mfma_f32_16x16x32_bf16 v[94:97], v[172:175], v[232:235], v[94:97]
	v_mfma_f32_16x16x32_bf16 v[82:85], v[164:167], v[240:243], v[82:85]
	v_mfma_f32_16x16x32_bf16 v[78:81], v[172:175], v[240:243], v[78:81]
	v_mfma_f32_16x16x32_bf16 v[130:133], v[168:171], v[210:213], v[130:133]
	v_mfma_f32_16x16x32_bf16 v[126:129], v[176:179], v[210:213], v[126:129]
	v_mfma_f32_16x16x32_bf16 v[114:117], v[168:171], v[228:231], v[114:117]
	v_mfma_f32_16x16x32_bf16 v[110:113], v[176:179], v[228:231], v[110:113]
	v_mfma_f32_16x16x32_bf16 v[98:101], v[168:171], v[236:239], v[98:101]
	v_mfma_f32_16x16x32_bf16 v[94:97], v[176:179], v[236:239], v[94:97]
	v_mfma_f32_16x16x32_bf16 v[82:85], v[168:171], v[244:247], v[82:85]
	v_mfma_f32_16x16x32_bf16 v[78:81], v[176:179], v[244:247], v[78:81]
	v_mfma_f32_16x16x32_bf16 v[122:125], v[180:183], v[206:209], v[122:125]
	v_mfma_f32_16x16x32_bf16 v[118:121], v[198:201], v[206:209], v[118:121]
	v_mfma_f32_16x16x32_bf16 v[106:109], v[180:183], v[214:217], v[106:109]
	v_mfma_f32_16x16x32_bf16 v[102:105], v[198:201], v[214:217], v[102:105]
	v_mfma_f32_16x16x32_bf16 v[90:93], v[180:183], v[232:235], v[90:93]
	v_mfma_f32_16x16x32_bf16 v[86:89], v[198:201], v[232:235], v[86:89]
	v_mfma_f32_16x16x32_bf16 v[74:77], v[180:183], v[240:243], v[74:77]
	v_mfma_f32_16x16x32_bf16 v[70:73], v[198:201], v[240:243], v[70:73]
	v_mfma_f32_16x16x32_bf16 v[122:125], v[194:197], v[210:213], v[122:125]
	v_mfma_f32_16x16x32_bf16 v[118:121], v[202:205], v[210:213], v[118:121]
	v_mfma_f32_16x16x32_bf16 v[106:109], v[194:197], v[228:231], v[106:109]
	v_mfma_f32_16x16x32_bf16 v[102:105], v[202:205], v[228:231], v[102:105]
	v_mfma_f32_16x16x32_bf16 v[90:93], v[194:197], v[236:239], v[90:93]
	v_mfma_f32_16x16x32_bf16 v[86:89], v[202:205], v[236:239], v[86:89]
	v_mfma_f32_16x16x32_bf16 v[74:77], v[194:197], v[244:247], v[74:77]
	v_mfma_f32_16x16x32_bf16 v[70:73], v[202:205], v[244:247], v[70:73]
	s_barrier
	s_add_i32 s66, s45, 0x10000
	v_lshl_add_u64 v[150:151], s[64:65], 0, v[138:139]
	s_mov_b32 m0, s66
	ds_read_b128 v[206:209], v163 offset:16384
	ds_read_b128 v[210:213], v163 offset:17408
	ds_read_b128 v[214:217], v163 offset:18432
	ds_read_b128 v[228:231], v163 offset:19456
	ds_read_b128 v[232:235], v163 offset:20480
	ds_read_b128 v[236:239], v163 offset:21504
	ds_read_b128 v[240:243], v163 offset:22528
	ds_read_b128 v[244:247], v163 offset:23552
	global_load_lds_dwordx4 v[150:151], off
	s_add_i32 m0, s66, 0x2000
	v_lshl_add_u64 v[184:185], s[64:65], 0, v[134:135]
	s_add_u32 s64, s64, s0
	s_addc_u32 s65, s65, s1
	s_add_i32 s66, s45, 0x14000
	global_load_lds_dwordx4 v[184:185], off
	s_mov_b32 m0, s66
	global_load_lds_dwordx4 v138, s[64:65]
	s_add_i32 m0, s66, 0x2000
	v_lshl_add_u64 v[218:219], s[30:31], 0, v[140:141]
	global_load_lds_dwordx4 v134, s[64:65]
	s_mov_b32 m0, s47
	v_lshl_add_u64 v[248:249], s[30:31], 0, v[136:137]
	global_load_lds_dwordx4 v[218:219], off
	s_mov_b32 m0, s48
	s_nop 0
	global_load_lds_dwordx4 v[248:249], off
	s_waitcnt vmcnt(8) lgkmcnt(0)
	s_barrier
	v_mfma_f32_16x16x32_bf16 v[66:69], v[164:167], v[206:209], v[66:69]
	v_mfma_f32_16x16x32_bf16 v[62:65], v[172:175], v[206:209], v[62:65]
	v_mfma_f32_16x16x32_bf16 v[50:53], v[164:167], v[214:217], v[50:53]
	v_mfma_f32_16x16x32_bf16 v[46:49], v[172:175], v[214:217], v[46:49]
	v_mfma_f32_16x16x32_bf16 v[34:37], v[164:167], v[232:235], v[34:37]
	v_mfma_f32_16x16x32_bf16 v[30:33], v[172:175], v[232:235], v[30:33]
	v_mfma_f32_16x16x32_bf16 v[18:21], v[164:167], v[240:243], v[18:21]
	v_mfma_f32_16x16x32_bf16 v[14:17], v[172:175], v[240:243], v[14:17]
	v_mfma_f32_16x16x32_bf16 v[66:69], v[168:171], v[210:213], v[66:69]
	v_mfma_f32_16x16x32_bf16 v[62:65], v[176:179], v[210:213], v[62:65]
	v_mfma_f32_16x16x32_bf16 v[50:53], v[168:171], v[228:231], v[50:53]
	v_mfma_f32_16x16x32_bf16 v[46:49], v[176:179], v[228:231], v[46:49]
	v_mfma_f32_16x16x32_bf16 v[34:37], v[168:171], v[236:239], v[34:37]
	v_mfma_f32_16x16x32_bf16 v[30:33], v[176:179], v[236:239], v[30:33]
	v_mfma_f32_16x16x32_bf16 v[18:21], v[168:171], v[244:247], v[18:21]
	v_mfma_f32_16x16x32_bf16 v[14:17], v[176:179], v[244:247], v[14:17]
	v_mfma_f32_16x16x32_bf16 v[58:61], v[180:183], v[206:209], v[58:61]
	v_mfma_f32_16x16x32_bf16 v[54:57], v[198:201], v[206:209], v[54:57]
	v_mfma_f32_16x16x32_bf16 v[42:45], v[180:183], v[214:217], v[42:45]
	v_mfma_f32_16x16x32_bf16 v[38:41], v[198:201], v[214:217], v[38:41]
	v_mfma_f32_16x16x32_bf16 v[26:29], v[180:183], v[232:235], v[26:29]
	v_mfma_f32_16x16x32_bf16 v[22:25], v[198:201], v[232:235], v[22:25]
	v_mfma_f32_16x16x32_bf16 v[10:13], v[180:183], v[240:243], v[10:13]
	v_mfma_f32_16x16x32_bf16 v[6:9], v[198:201], v[240:243], v[6:9]
	v_mfma_f32_16x16x32_bf16 v[58:61], v[194:197], v[210:213], v[58:61]
	v_mfma_f32_16x16x32_bf16 v[54:57], v[202:205], v[210:213], v[54:57]
	v_mfma_f32_16x16x32_bf16 v[42:45], v[194:197], v[228:231], v[42:45]
	v_mfma_f32_16x16x32_bf16 v[38:41], v[202:205], v[228:231], v[38:41]
	v_mfma_f32_16x16x32_bf16 v[26:29], v[194:197], v[236:239], v[26:29]
	v_mfma_f32_16x16x32_bf16 v[22:25], v[202:205], v[236:239], v[22:25]
	v_mfma_f32_16x16x32_bf16 v[10:13], v[194:197], v[244:247], v[10:13]
	v_mfma_f32_16x16x32_bf16 v[6:9], v[202:205], v[244:247], v[6:9]
	s_barrier
; #define PG8_STAGE(bufoff, gbase, voff) do { _Pragma("unroll") for (int _i = 0; _i < 2; ++_i) \
;         __builtin_amdgcn_global_load_lds((const unsigned*)((const char*)(gbase) + (voff)[_i]), (PG8_LAS unsigned*)(lds + (bufoff) + ldsw + _i * 8192), 16, 0, 0); } while (0)
; #define PG8_LDA(dst, b, h) do { _Pragma("unroll") for (int m = 0; m < 4; ++m) _Pragma("unroll") for (int k = 0; k < 2; ++k) dst[m][k] = *(const PG8_LAS bf16x8*)(lds + PG8_SA(b, h) + aoff + m * 2048 + k * 1024); } while (0)
; #define PG8_LDB(dst, b, h) do { _Pragma("unroll") for (int n = 0; n < 2; ++n) _Pragma("unroll") for (int k = 0; k < 2; ++k) dst[n][k] = *(const PG8_LAS bf16x8*)(lds + PG8_SB(b, h) + boff + n * 2048 + k * 1024); } while (0)
; #define PG8_MMA(ai, bj, At, Bt) do { __builtin_amdgcn_s_setprio(1); _Pragma("unroll") for (int m = 0; m < 4; ++m) _Pragma("unroll") for (int n = 0; n < 2; ++n) _Pragma("unroll") for (int k = 0; k < 2; ++k) \
;         acc[ai][bj][m][n] = __builtin_amdgcn_mfma_f32_16x16x32_bf16(Bt[n][k], At[m][k], acc[ai][bj][m][n], 0, 0, 0); __builtin_amdgcn_s_setprio(0); } while (0)
; #define PG8_WAIT_V(n) asm volatile("s_waitcnt vmcnt(" #n ")" ::: "memory")
; #define PG8_WAIT_L(n) asm volatile("s_waitcnt lgkmcnt(" #n ")" ::: "memory")
; #define PG8_BAR __builtin_amdgcn_s_barrier()
; #define PG8_SCHED __builtin_amdgcn_sched_barrier(0)
; template <class Epi, class Sched, bool ALIGN_EPI = false, bool SP2 = false>
; __device__ __forceinline__ void gemm_phase(PG8_LAS unsigned char* lds, const Gemm g, const Sched& S, const Epi& E, const int wv) {
;     ...
;             PG8_LDB(B0, 1, 0); PG8_LDB(B1, 1, 1); PG8_SCHED; PG8_LDA(At, 1, 0); PG8_STAGE(PG8_SA(0, 1), a2 + hstepA, voffA);
;             PG8_WAIT_V(8); PG8_WAIT_L(0); PG8_BAR; PG8_MMA(0, 0, At, B0); PG8_MMA(0, 1, At, B1); PG8_BAR; PG8_SCHED;
;             PG8_LDA(At, 1, 1); PG8_STAGE(PG8_SB(1, 0), b3, voffB); PG8_STAGE(PG8_SB(1, 1), b3 + hstepB, voffB); PG8_STAGE(PG8_SA(1, 0), a3, voffA);
;             PG8_WAIT_V(8); PG8_WAIT_L(0); PG8_BAR; PG8_MMA(1, 0, At, B0); PG8_MMA(1, 1, At, B1); PG8_BAR; PG8_SCHED;
	ds_read_b128 v[164:167], v152
	ds_read_b128 v[168:171], v152 offset:1024
	ds_read_b128 v[172:175], v152 offset:2048
	ds_read_b128 v[176:179], v152 offset:3072
	ds_read_b128 v[180:183], v154
	ds_read_b128 v[194:197], v154 offset:1024
	ds_read_b128 v[198:201], v154 offset:2048
	ds_read_b128 v[202:205], v154 offset:3072
	s_add_u32 s30, s30, 0x80000
	s_addc_u32 s31, s31, 0
	s_mov_b32 m0, s49
	ds_read_b128 v[206:209], v163 offset:32768
	ds_read_b128 v[210:213], v163 offset:33792
	ds_read_b128 v[214:217], v163 offset:34816
	ds_read_b128 v[228:231], v163 offset:35840
	ds_read_b128 v[232:235], v163 offset:36864
	ds_read_b128 v[236:239], v163 offset:37888
	ds_read_b128 v[240:243], v163 offset:38912
	ds_read_b128 v[244:247], v163 offset:39936
	global_load_lds_dwordx4 v140, s[30:31]
	s_mov_b32 m0, s50
	s_nop 0
	global_load_lds_dwordx4 v136, s[30:31]
	s_waitcnt vmcnt(8) lgkmcnt(0)
	s_barrier
	v_mfma_f32_16x16x32_bf16 v[130:133], v[164:167], v[206:209], v[130:133]
	v_mfma_f32_16x16x32_bf16 v[126:129], v[172:175], v[206:209], v[126:129]
	v_mfma_f32_16x16x32_bf16 v[114:117], v[164:167], v[214:217], v[114:117]
	v_mfma_f32_16x16x32_bf16 v[110:113], v[172:175], v[214:217], v[110:113]
	v_mfma_f32_16x16x32_bf16 v[98:101], v[164:167], v[232:235], v[98:101]
	v_mfma_f32_16x16x32_bf16 v[94:97], v[172:175], v[232:235], v[94:97]
	v_mfma_f32_16x16x32_bf16 v[82:85], v[164:167], v[240:243], v[82:85]
	v_mfma_f32_16x16x32_bf16 v[78:81], v[172:175], v[240:243], v[78:81]
	v_mfma_f32_16x16x32_bf16 v[130:133], v[168:171], v[210:213], v[130:133]
	v_mfma_f32_16x16x32_bf16 v[126:129], v[176:179], v[210:213], v[126:129]
	v_mfma_f32_16x16x32_bf16 v[114:117], v[168:171], v[228:231], v[114:117]
	v_mfma_f32_16x16x32_bf16 v[110:113], v[176:179], v[228:231], v[110:113]
	v_mfma_f32_16x16x32_bf16 v[98:101], v[168:171], v[236:239], v[98:101]
	v_mfma_f32_16x16x32_bf16 v[94:97], v[176:179], v[236:239], v[94:97]
	v_mfma_f32_16x16x32_bf16 v[82:85], v[168:171], v[244:247], v[82:85]
	v_mfma_f32_16x16x32_bf16 v[78:81], v[176:179], v[244:247], v[78:81]
	v_mfma_f32_16x16x32_bf16 v[122:125], v[180:183], v[206:209], v[122:125]
	v_mfma_f32_16x16x32_bf16 v[118:121], v[198:201], v[206:209], v[118:121]
	v_mfma_f32_16x16x32_bf16 v[106:109], v[180:183], v[214:217], v[106:109]
	v_mfma_f32_16x16x32_bf16 v[102:105], v[198:201], v[214:217], v[102:105]
	v_mfma_f32_16x16x32_bf16 v[90:93], v[180:183], v[232:235], v[90:93]
	v_mfma_f32_16x16x32_bf16 v[86:89], v[198:201], v[232:235], v[86:89]
	v_mfma_f32_16x16x32_bf16 v[74:77], v[180:183], v[240:243], v[74:77]
	v_mfma_f32_16x16x32_bf16 v[70:73], v[198:201], v[240:243], v[70:73]
	v_mfma_f32_16x16x32_bf16 v[122:125], v[194:197], v[210:213], v[122:125]
	v_mfma_f32_16x16x32_bf16 v[118:121], v[202:205], v[210:213], v[118:121]
	v_mfma_f32_16x16x32_bf16 v[106:109], v[194:197], v[228:231], v[106:109]
	v_mfma_f32_16x16x32_bf16 v[102:105], v[202:205], v[228:231], v[102:105]
	v_mfma_f32_16x16x32_bf16 v[90:93], v[194:197], v[236:239], v[90:93]
	v_mfma_f32_16x16x32_bf16 v[86:89], v[202:205], v[236:239], v[86:89]
	v_mfma_f32_16x16x32_bf16 v[74:77], v[194:197], v[244:247], v[74:77]
	v_mfma_f32_16x16x32_bf16 v[70:73], v[202:205], v[244:247], v[70:73]
	s_barrier
	s_add_i32 s30, s45, 0x18000
	s_add_i32 m0, s30, 0xffffff80
	ds_read_b128 v[206:209], v163 offset:49152
	ds_read_b128 v[210:213], v163 offset:50176
	ds_read_b128 v[214:217], v163 offset:51200
	ds_read_b128 v[228:231], v163 offset:52224
	ds_read_b128 v[232:235], v163 offset:53248
	ds_read_b128 v[236:239], v163 offset:54272
	ds_read_b128 v[240:243], v163 offset:55296
	ds_read_b128 v[244:247], v163 offset:56320
	global_load_lds_dwordx4 v[150:151], off offset:128
	s_add_i32 m0, s30, 0x1f80
	s_add_i32 s30, s45, 0x1c000
	global_load_lds_dwordx4 v[184:185], off offset:128
	s_add_i32 m0, s30, 0xffffff80
	s_nop 0
	global_load_lds_dwordx4 v138, s[64:65] offset:128
	s_add_i32 m0, s30, 0x1f80
	s_nop 0
	global_load_lds_dwordx4 v134, s[64:65] offset:128
	s_add_i32 m0, s53, 0xffffff80
	s_nop 0
	global_load_lds_dwordx4 v[218:219], off offset:128
	s_add_i32 m0, s54, 0xffffff80
	s_nop 0
	global_load_lds_dwordx4 v[248:249], off offset:128
	s_waitcnt vmcnt(8) lgkmcnt(0)
	s_barrier
	v_mfma_f32_16x16x32_bf16 v[66:69], v[164:167], v[206:209], v[66:69]
	v_mfma_f32_16x16x32_bf16 v[62:65], v[172:175], v[206:209], v[62:65]
	v_mfma_f32_16x16x32_bf16 v[50:53], v[164:167], v[214:217], v[50:53]
	v_mfma_f32_16x16x32_bf16 v[46:49], v[172:175], v[214:217], v[46:49]
	v_mfma_f32_16x16x32_bf16 v[34:37], v[164:167], v[232:235], v[34:37]
	v_mfma_f32_16x16x32_bf16 v[30:33], v[172:175], v[232:235], v[30:33]
	v_mfma_f32_16x16x32_bf16 v[18:21], v[164:167], v[240:243], v[18:21]
	v_mfma_f32_16x16x32_bf16 v[14:17], v[172:175], v[240:243], v[14:17]
	v_mfma_f32_16x16x32_bf16 v[66:69], v[168:171], v[210:213], v[66:69]
	v_mfma_f32_16x16x32_bf16 v[62:65], v[176:179], v[210:213], v[62:65]
	v_mfma_f32_16x16x32_bf16 v[50:53], v[168:171], v[228:231], v[50:53]
	v_mfma_f32_16x16x32_bf16 v[46:49], v[176:179], v[228:231], v[46:49]
	v_mfma_f32_16x16x32_bf16 v[34:37], v[168:171], v[236:239], v[34:37]
	v_mfma_f32_16x16x32_bf16 v[30:33], v[176:179], v[236:239], v[30:33]
	v_mfma_f32_16x16x32_bf16 v[18:21], v[168:171], v[244:247], v[18:21]
	v_mfma_f32_16x16x32_bf16 v[14:17], v[176:179], v[244:247], v[14:17]
	v_mfma_f32_16x16x32_bf16 v[58:61], v[180:183], v[206:209], v[58:61]
	v_mfma_f32_16x16x32_bf16 v[54:57], v[198:201], v[206:209], v[54:57]
	v_mfma_f32_16x16x32_bf16 v[42:45], v[180:183], v[214:217], v[42:45]
	v_mfma_f32_16x16x32_bf16 v[38:41], v[198:201], v[214:217], v[38:41]
	v_mfma_f32_16x16x32_bf16 v[26:29], v[180:183], v[232:235], v[26:29]
	v_mfma_f32_16x16x32_bf16 v[22:25], v[198:201], v[232:235], v[22:25]
	v_mfma_f32_16x16x32_bf16 v[10:13], v[180:183], v[240:243], v[10:13]
	v_mfma_f32_16x16x32_bf16 v[6:9], v[198:201], v[240:243], v[6:9]
	v_mfma_f32_16x16x32_bf16 v[58:61], v[194:197], v[210:213], v[58:61]
	v_mfma_f32_16x16x32_bf16 v[54:57], v[202:205], v[210:213], v[54:57]
	v_mfma_f32_16x16x32_bf16 v[42:45], v[194:197], v[228:231], v[42:45]
	v_mfma_f32_16x16x32_bf16 v[38:41], v[202:205], v[228:231], v[38:41]
	v_mfma_f32_16x16x32_bf16 v[26:29], v[194:197], v[236:239], v[26:29]
	v_mfma_f32_16x16x32_bf16 v[22:25], v[202:205], v[236:239], v[22:25]
	v_mfma_f32_16x16x32_bf16 v[10:13], v[194:197], v[244:247], v[10:13]
	v_mfma_f32_16x16x32_bf16 v[6:9], v[202:205], v[244:247], v[6:9]
	s_barrier
	s_add_u32 s28, s28, 0x100
	s_addc_u32 s29, s29, 0
	s_add_u32 s41, s41, 0x100
	s_addc_u32 s62, s62, 0
	s_cmp_ge_i32 s63, s55
	s_mov_b32 s30, s63
	s_cbranch_scc0 .LBB0_1074
	v_readlane_b32 s67, v255, 30

; #define PG8_STAGE(bufoff, gbase, voff) do { _Pragma("unroll") for (int _i = 0; _i < 2; ++_i) \
;         __builtin_amdgcn_global_load_lds((const unsigned*)((const char*)(gbase) + (voff)[_i]), (PG8_LAS unsigned*)(lds + (bufoff) + ldsw + _i * 8192), 16, 0, 0); } while (0)
; #define PG8_LDA(dst, b, h) do { _Pragma("unroll") for (int m = 0; m < 4; ++m) _Pragma("unroll") for (int k = 0; k < 2; ++k) dst[m][k] = *(const PG8_LAS bf16x8*)(lds + PG8_SA(b, h) + aoff + m * 2048 + k * 1024); } while (0)
; #define PG8_LDB(dst, b, h) do { _Pragma("unroll") for (int n = 0; n < 2; ++n) _Pragma("unroll") for (int k = 0; k < 2; ++k) dst[n][k] = *(const PG8_LAS bf16x8*)(lds + PG8_SB(b, h) + boff + n * 2048 + k * 1024); } while (0)
; #define PG8_MMA(ai, bj, At, Bt) do { __builtin_amdgcn_s_setprio(1); _Pragma("unroll") for (int m = 0; m < 4; ++m) _Pragma("unroll") for (int n = 0; n < 2; ++n) _Pragma("unroll") for (int k = 0; k < 2; ++k) \
;         acc[ai][bj][m][n] = __builtin_amdgcn_mfma_f32_16x16x32_bf16(Bt[n][k], At[m][k], acc[ai][bj][m][n], 0, 0, 0); __builtin_amdgcn_s_setprio(0); } while (0)
; #define PG8_WAIT_V(n) asm volatile("s_waitcnt vmcnt(" #n ")" ::: "memory")
; #define PG8_BAR __builtin_amdgcn_s_barrier()
; template <class Epi, class Sched, bool ALIGN_EPI = false, bool SP2 = false>
; __device__ __forceinline__ void gemm_phase(PG8_LAS unsigned char* lds, const Gemm g, const Sched& S, const Epi& E, const int wv) {
;     ...
;         for (int t = 0; t < nt; t += 2) {
;             const bool last = (t == nt - 2);
;             const char* a1 = cA + (size_t)(t + 1) * kstep;
;             const char* a2 = last ? nA : cA + (size_t)(t + 2) * kstep; const char* b2 = last ? nB : cB + (size_t)(t + 2) * kstep;
;             const char* a3 = a2 + kstep; const char* b3 = b2 + kstep;
;             if (last && has_next) S.a_ready(nxt);
;             if constexpr (SP2) {
;             PG8_LDB(B0, 0, 0); PG8_LDB(B1, 0, 1); PG8_SCHED; PG8_LDA(At, 0, 0); PG8_STAGE(PG8_SA(1, 1), a1 + hstepA, voffA);
;             PG8_WAIT_V(8); PG8_WAIT_L(0); PG8_BAR; PG8_MMA(0, 0, At, B0); PG8_MMA(0, 1, At, B1); PG8_BAR; PG8_SCHED;
;             PG8_LDA(At, 0, 1); PG8_STAGE(PG8_SB(0, 0), b2, voffB); PG8_STAGE(PG8_SB(0, 1), b2 + hstepB, voffB); PG8_STAGE(PG8_SA(0, 0), a2, voffA);
;             PG8_WAIT_V(8); PG8_WAIT_L(0); PG8_BAR; PG8_MMA(1, 0, At, B0); PG8_MMA(1, 1, At, B1); PG8_BAR; PG8_SCHED;
.LBB0_1385:
	s_add_i32 s70, s52, 2
	s_add_u32 s71, s44, 0xfffc0080
	s_addc_u32 s53, s45, -1
	s_cmp_eq_u32 s65, s52
	s_cselect_b32 s53, s13, s53
	s_cselect_b32 s52, s19, s71
	s_cselect_b32 s73, s15, s55
	s_cselect_b32 s72, s14, s54
	ds_read_b128 v[114:117], v201
	ds_read_b128 v[126:129], v201 offset:1024
	ds_read_b128 v[138:141], v201 offset:2048
	ds_read_b128 v[142:145], v201 offset:3072
	ds_read_b128 v[146:149], v203
	ds_read_b128 v[150:153], v203 offset:1024
	ds_read_b128 v[154:157], v203 offset:2048
	ds_read_b128 v[158:161], v203 offset:3072
	s_add_i32 m0, s51, 0xc000
	ds_read_b128 v[162:165], v235
	ds_read_b128 v[166:169], v235 offset:1024
	ds_read_b128 v[170:173], v235 offset:2048
	ds_read_b128 v[174:177], v235 offset:3072
	ds_read_b128 v[178:181], v235 offset:4096
	ds_read_b128 v[182:185], v235 offset:5120
	ds_read_b128 v[204:207], v235 offset:6144
	ds_read_b128 v[208:211], v235 offset:7168
	global_load_lds_dwordx4 v200, s[44:45]
	s_add_i32 m0, s51, 0xe000
	s_nop 0
	global_load_lds_dwordx4 v202, s[44:45]
	s_waitcnt vmcnt(8) lgkmcnt(0)
	s_barrier
	v_mfma_f32_16x16x32_bf16 v[134:137], v[114:117], v[162:165], v[134:137]
	v_mfma_f32_16x16x32_bf16 v[130:133], v[138:141], v[162:165], v[130:133]
	v_mfma_f32_16x16x32_bf16 v[110:113], v[114:117], v[170:173], v[110:113]
	v_mfma_f32_16x16x32_bf16 v[106:109], v[138:141], v[170:173], v[106:109]
	v_mfma_f32_16x16x32_bf16 v[94:97], v[114:117], v[178:181], v[94:97]
	v_mfma_f32_16x16x32_bf16 v[90:93], v[138:141], v[178:181], v[90:93]
	v_mfma_f32_16x16x32_bf16 v[78:81], v[114:117], v[204:207], v[78:81]
	v_mfma_f32_16x16x32_bf16 v[74:77], v[138:141], v[204:207], v[74:77]
	v_mfma_f32_16x16x32_bf16 v[134:137], v[126:129], v[166:169], v[134:137]
	v_mfma_f32_16x16x32_bf16 v[130:133], v[142:145], v[166:169], v[130:133]
	v_mfma_f32_16x16x32_bf16 v[110:113], v[126:129], v[174:177], v[110:113]
	v_mfma_f32_16x16x32_bf16 v[106:109], v[142:145], v[174:177], v[106:109]
	v_mfma_f32_16x16x32_bf16 v[94:97], v[126:129], v[182:185], v[94:97]
	v_mfma_f32_16x16x32_bf16 v[90:93], v[142:145], v[182:185], v[90:93]
	v_mfma_f32_16x16x32_bf16 v[78:81], v[126:129], v[208:211], v[78:81]
	v_mfma_f32_16x16x32_bf16 v[74:77], v[142:145], v[208:211], v[74:77]
	v_mfma_f32_16x16x32_bf16 v[122:125], v[146:149], v[162:165], v[122:125]
	v_mfma_f32_16x16x32_bf16 v[118:121], v[154:157], v[162:165], v[118:121]
	v_mfma_f32_16x16x32_bf16 v[102:105], v[146:149], v[170:173], v[102:105]
	v_mfma_f32_16x16x32_bf16 v[98:101], v[154:157], v[170:173], v[98:101]
	v_mfma_f32_16x16x32_bf16 v[86:89], v[146:149], v[178:181], v[86:89]
	v_mfma_f32_16x16x32_bf16 v[82:85], v[154:157], v[178:181], v[82:85]
	v_mfma_f32_16x16x32_bf16 v[70:73], v[146:149], v[204:207], v[70:73]
	v_mfma_f32_16x16x32_bf16 v[66:69], v[154:157], v[204:207], v[66:69]
	v_mfma_f32_16x16x32_bf16 v[122:125], v[150:153], v[166:169], v[122:125]
	v_mfma_f32_16x16x32_bf16 v[118:121], v[158:161], v[166:169], v[118:121]
	v_mfma_f32_16x16x32_bf16 v[102:105], v[150:153], v[174:177], v[102:105]
	v_mfma_f32_16x16x32_bf16 v[98:101], v[158:161], v[174:177], v[98:101]
	v_mfma_f32_16x16x32_bf16 v[86:89], v[150:153], v[182:185], v[86:89]
	v_mfma_f32_16x16x32_bf16 v[82:85], v[158:161], v[182:185], v[82:85]
	v_mfma_f32_16x16x32_bf16 v[70:73], v[150:153], v[208:211], v[70:73]
	v_mfma_f32_16x16x32_bf16 v[66:69], v[158:161], v[208:211], v[66:69]
	s_barrier
	s_add_i32 s74, s3, 0x10000
	v_lshl_add_u64 v[190:191], s[72:73], 0, v[0:1]
	s_mov_b32 m0, s74
	ds_read_b128 v[162:165], v235 offset:16384
	ds_read_b128 v[166:169], v235 offset:17408
	ds_read_b128 v[170:173], v235 offset:18432
	ds_read_b128 v[174:177], v235 offset:19456
	ds_read_b128 v[178:181], v235 offset:20480
	ds_read_b128 v[182:185], v235 offset:21504
	ds_read_b128 v[204:207], v235 offset:22528
	ds_read_b128 v[208:211], v235 offset:23552
	global_load_lds_dwordx4 v[190:191], off
	s_add_i32 m0, s74, 0x2000
	v_lshl_add_u64 v[192:193], s[72:73], 0, v[198:199]
	s_add_u32 s72, s72, s24
	s_addc_u32 s73, s73, s25
	s_add_i32 s71, s3, 0x14000
	global_load_lds_dwordx4 v[192:193], off
	s_mov_b32 m0, s71
	global_load_lds_dwordx4 v0, s[72:73]
	s_add_i32 m0, s71, 0x2000
	v_lshl_add_u64 v[216:217], s[52:53], 0, v[194:195]
	global_load_lds_dwordx4 v198, s[72:73]
	s_mov_b32 m0, s51
	v_lshl_add_u64 v[218:219], s[52:53], 0, v[196:197]
	global_load_lds_dwordx4 v[216:217], off
	s_mov_b32 m0, s59
	s_nop 0
	global_load_lds_dwordx4 v[218:219], off
	s_waitcnt vmcnt(8) lgkmcnt(0)
	s_barrier
	v_mfma_f32_16x16x32_bf16 v[62:65], v[114:117], v[162:165], v[62:65]
	v_mfma_f32_16x16x32_bf16 v[58:61], v[138:141], v[162:165], v[58:61]
	v_mfma_f32_16x16x32_bf16 v[46:49], v[114:117], v[170:173], v[46:49]
	v_mfma_f32_16x16x32_bf16 v[42:45], v[138:141], v[170:173], v[42:45]
	v_mfma_f32_16x16x32_bf16 v[30:33], v[114:117], v[178:181], v[30:33]
	v_mfma_f32_16x16x32_bf16 v[26:29], v[138:141], v[178:181], v[26:29]
	v_mfma_f32_16x16x32_bf16 v[14:17], v[114:117], v[204:207], v[14:17]
	v_mfma_f32_16x16x32_bf16 v[10:13], v[138:141], v[204:207], v[10:13]
	v_mfma_f32_16x16x32_bf16 v[62:65], v[126:129], v[166:169], v[62:65]
	v_mfma_f32_16x16x32_bf16 v[58:61], v[142:145], v[166:169], v[58:61]
	v_mfma_f32_16x16x32_bf16 v[46:49], v[126:129], v[174:177], v[46:49]
	v_mfma_f32_16x16x32_bf16 v[42:45], v[142:145], v[174:177], v[42:45]
	v_mfma_f32_16x16x32_bf16 v[30:33], v[126:129], v[182:185], v[30:33]
	v_mfma_f32_16x16x32_bf16 v[26:29], v[142:145], v[182:185], v[26:29]
	v_mfma_f32_16x16x32_bf16 v[14:17], v[126:129], v[208:211], v[14:17]
	v_mfma_f32_16x16x32_bf16 v[10:13], v[142:145], v[208:211], v[10:13]
	v_mfma_f32_16x16x32_bf16 v[54:57], v[146:149], v[162:165], v[54:57]
	v_mfma_f32_16x16x32_bf16 v[50:53], v[154:157], v[162:165], v[50:53]
	v_mfma_f32_16x16x32_bf16 v[38:41], v[146:149], v[170:173], v[38:41]
	v_mfma_f32_16x16x32_bf16 v[34:37], v[154:157], v[170:173], v[34:37]
	v_mfma_f32_16x16x32_bf16 v[22:25], v[146:149], v[178:181], v[22:25]
	v_mfma_f32_16x16x32_bf16 v[18:21], v[154:157], v[178:181], v[18:21]
	v_mfma_f32_16x16x32_bf16 v[6:9], v[146:149], v[204:207], v[6:9]
	v_mfma_f32_16x16x32_bf16 v[2:5], v[154:157], v[204:207], v[2:5]
	v_mfma_f32_16x16x32_bf16 v[54:57], v[150:153], v[166:169], v[54:57]
	v_mfma_f32_16x16x32_bf16 v[50:53], v[158:161], v[166:169], v[50:53]
	v_mfma_f32_16x16x32_bf16 v[38:41], v[150:153], v[174:177], v[38:41]
	v_mfma_f32_16x16x32_bf16 v[34:37], v[158:161], v[174:177], v[34:37]
	v_mfma_f32_16x16x32_bf16 v[22:25], v[150:153], v[182:185], v[22:25]
	v_mfma_f32_16x16x32_bf16 v[18:21], v[158:161], v[182:185], v[18:21]
	v_mfma_f32_16x16x32_bf16 v[6:9], v[150:153], v[208:211], v[6:9]
	v_mfma_f32_16x16x32_bf16 v[2:5], v[158:161], v[208:211], v[2:5]
	s_barrier
; #define PG8_STAGE(bufoff, gbase, voff) do { _Pragma("unroll") for (int _i = 0; _i < 2; ++_i) \
;         __builtin_amdgcn_global_load_lds((const unsigned*)((const char*)(gbase) + (voff)[_i]), (PG8_LAS unsigned*)(lds + (bufoff) + ldsw + _i * 8192), 16, 0, 0); } while (0)
; #define PG8_LDA(dst, b, h) do { _Pragma("unroll") for (int m = 0; m < 4; ++m) _Pragma("unroll") for (int k = 0; k < 2; ++k) dst[m][k] = *(const PG8_LAS bf16x8*)(lds + PG8_SA(b, h) + aoff + m * 2048 + k * 1024); } while (0)
; #define PG8_LDB(dst, b, h) do { _Pragma("unroll") for (int n = 0; n < 2; ++n) _Pragma("unroll") for (int k = 0; k < 2; ++k) dst[n][k] = *(const PG8_LAS bf16x8*)(lds + PG8_SB(b, h) + boff + n * 2048 + k * 1024); } while (0)
; #define PG8_MMA(ai, bj, At, Bt) do { __builtin_amdgcn_s_setprio(1); _Pragma("unroll") for (int m = 0; m < 4; ++m) _Pragma("unroll") for (int n = 0; n < 2; ++n) _Pragma("unroll") for (int k = 0; k < 2; ++k) \
;         acc[ai][bj][m][n] = __builtin_amdgcn_mfma_f32_16x16x32_bf16(Bt[n][k], At[m][k], acc[ai][bj][m][n], 0, 0, 0); __builtin_amdgcn_s_setprio(0); } while (0)
; #define PG8_WAIT_V(n) asm volatile("s_waitcnt vmcnt(" #n ")" ::: "memory")
; #define PG8_WAIT_L(n) asm volatile("s_waitcnt lgkmcnt(" #n ")" ::: "memory")
; #define PG8_BAR __builtin_amdgcn_s_barrier()
; template <class Epi, class Sched, bool ALIGN_EPI = false, bool SP2 = false>
; __device__ __forceinline__ void gemm_phase(PG8_LAS unsigned char* lds, const Gemm g, const Sched& S, const Epi& E, const int wv) {
;     ...
;         for (int t = 0; t < nt; t += 2) {
;             const bool last = (t == nt - 2);
;             const char* a1 = cA + (size_t)(t + 1) * kstep;
;             const char* a2 = last ? nA : cA + (size_t)(t + 2) * kstep; const char* b2 = last ? nB : cB + (size_t)(t + 2) * kstep;
;             const char* a3 = a2 + kstep; const char* b3 = b2 + kstep;
;     ...
;             PG8_LDB(B0, 1, 0); PG8_LDB(B1, 1, 1); PG8_SCHED; PG8_LDA(At, 1, 0); PG8_STAGE(PG8_SA(0, 1), a2 + hstepA, voffA);
;             PG8_WAIT_V(8); PG8_WAIT_L(0); PG8_BAR; PG8_MMA(0, 0, At, B0); PG8_MMA(0, 1, At, B1); PG8_BAR; PG8_SCHED;
;             PG8_LDA(At, 1, 1); PG8_STAGE(PG8_SB(1, 0), b3, voffB); PG8_STAGE(PG8_SB(1, 1), b3 + hstepB, voffB); PG8_STAGE(PG8_SA(1, 0), a3, voffA);
;             PG8_WAIT_V(8); PG8_WAIT_L(0); PG8_BAR; PG8_MMA(1, 0, At, B0); PG8_MMA(1, 1, At, B1); PG8_BAR; PG8_SCHED;
	ds_read_b128 v[114:117], v236
	ds_read_b128 v[126:129], v236 offset:1024
	ds_read_b128 v[138:141], v236 offset:2048
	ds_read_b128 v[142:145], v236 offset:3072
	ds_read_b128 v[146:149], v237
	ds_read_b128 v[150:153], v237 offset:1024
	ds_read_b128 v[154:157], v237 offset:2048
	ds_read_b128 v[158:161], v237 offset:3072
	s_add_u32 s52, s52, 0x40000
	s_addc_u32 s53, s53, 0
	s_mov_b32 m0, s60
	ds_read_b128 v[162:165], v235 offset:32768
	ds_read_b128 v[166:169], v235 offset:33792
	ds_read_b128 v[170:173], v235 offset:34816
	ds_read_b128 v[174:177], v235 offset:35840
	ds_read_b128 v[178:181], v235 offset:36864
	ds_read_b128 v[182:185], v235 offset:37888
	ds_read_b128 v[204:207], v235 offset:38912
	ds_read_b128 v[208:211], v235 offset:39936
	global_load_lds_dwordx4 v194, s[52:53]
	s_mov_b32 m0, s61
	s_nop 0
	global_load_lds_dwordx4 v196, s[52:53]
	s_waitcnt vmcnt(8) lgkmcnt(0)
	s_barrier
	v_mfma_f32_16x16x32_bf16 v[134:137], v[114:117], v[162:165], v[134:137]
	v_mfma_f32_16x16x32_bf16 v[130:133], v[138:141], v[162:165], v[130:133]
	v_mfma_f32_16x16x32_bf16 v[110:113], v[114:117], v[170:173], v[110:113]
	v_mfma_f32_16x16x32_bf16 v[106:109], v[138:141], v[170:173], v[106:109]
	v_mfma_f32_16x16x32_bf16 v[94:97], v[114:117], v[178:181], v[94:97]
	v_mfma_f32_16x16x32_bf16 v[90:93], v[138:141], v[178:181], v[90:93]
	v_mfma_f32_16x16x32_bf16 v[78:81], v[114:117], v[204:207], v[78:81]
	v_mfma_f32_16x16x32_bf16 v[74:77], v[138:141], v[204:207], v[74:77]
	v_mfma_f32_16x16x32_bf16 v[134:137], v[126:129], v[166:169], v[134:137]
	v_mfma_f32_16x16x32_bf16 v[130:133], v[142:145], v[166:169], v[130:133]
	v_mfma_f32_16x16x32_bf16 v[110:113], v[126:129], v[174:177], v[110:113]
	v_mfma_f32_16x16x32_bf16 v[106:109], v[142:145], v[174:177], v[106:109]
	v_mfma_f32_16x16x32_bf16 v[94:97], v[126:129], v[182:185], v[94:97]
	v_mfma_f32_16x16x32_bf16 v[90:93], v[142:145], v[182:185], v[90:93]
	v_mfma_f32_16x16x32_bf16 v[78:81], v[126:129], v[208:211], v[78:81]
	v_mfma_f32_16x16x32_bf16 v[74:77], v[142:145], v[208:211], v[74:77]
	v_mfma_f32_16x16x32_bf16 v[122:125], v[146:149], v[162:165], v[122:125]
	v_mfma_f32_16x16x32_bf16 v[118:121], v[154:157], v[162:165], v[118:121]
	v_mfma_f32_16x16x32_bf16 v[102:105], v[146:149], v[170:173], v[102:105]
	v_mfma_f32_16x16x32_bf16 v[98:101], v[154:157], v[170:173], v[98:101]
	v_mfma_f32_16x16x32_bf16 v[86:89], v[146:149], v[178:181], v[86:89]
	v_mfma_f32_16x16x32_bf16 v[82:85], v[154:157], v[178:181], v[82:85]
	v_mfma_f32_16x16x32_bf16 v[70:73], v[146:149], v[204:207], v[70:73]
	v_mfma_f32_16x16x32_bf16 v[66:69], v[154:157], v[204:207], v[66:69]
	v_mfma_f32_16x16x32_bf16 v[122:125], v[150:153], v[166:169], v[122:125]
	v_mfma_f32_16x16x32_bf16 v[118:121], v[158:161], v[166:169], v[118:121]
	v_mfma_f32_16x16x32_bf16 v[102:105], v[150:153], v[174:177], v[102:105]
	v_mfma_f32_16x16x32_bf16 v[98:101], v[158:161], v[174:177], v[98:101]
	v_mfma_f32_16x16x32_bf16 v[86:89], v[150:153], v[182:185], v[86:89]
	v_mfma_f32_16x16x32_bf16 v[82:85], v[158:161], v[182:185], v[82:85]
	v_mfma_f32_16x16x32_bf16 v[70:73], v[150:153], v[208:211], v[70:73]
	v_mfma_f32_16x16x32_bf16 v[66:69], v[158:161], v[208:211], v[66:69]
	s_barrier
	s_add_i32 s52, s3, 0x18000
	s_add_i32 m0, s52, 0xffffff80
	ds_read_b128 v[162:165], v235 offset:49152
	ds_read_b128 v[166:169], v235 offset:50176
	ds_read_b128 v[170:173], v235 offset:51200
	ds_read_b128 v[174:177], v235 offset:52224
	ds_read_b128 v[178:181], v235 offset:53248
	ds_read_b128 v[182:185], v235 offset:54272
	ds_read_b128 v[204:207], v235 offset:55296
	ds_read_b128 v[208:211], v235 offset:56320
	global_load_lds_dwordx4 v[190:191], off offset:128
	s_add_i32 m0, s52, 0x1f80
	s_add_i32 s52, s3, 0x1c000
	global_load_lds_dwordx4 v[192:193], off offset:128
	s_add_i32 m0, s52, 0xffffff80
	s_nop 0
	global_load_lds_dwordx4 v0, s[72:73] offset:128
	s_add_i32 m0, s52, 0x1f80
	s_nop 0
	global_load_lds_dwordx4 v198, s[72:73] offset:128
	s_add_i32 m0, s63, 0xffffff80
	s_nop 0
	global_load_lds_dwordx4 v[216:217], off offset:128
	s_add_i32 m0, s64, 0xffffff80
	s_nop 0
	global_load_lds_dwordx4 v[218:219], off offset:128
	s_waitcnt vmcnt(8) lgkmcnt(0)
	s_barrier
	v_mfma_f32_16x16x32_bf16 v[62:65], v[114:117], v[162:165], v[62:65]
	v_mfma_f32_16x16x32_bf16 v[58:61], v[138:141], v[162:165], v[58:61]
	v_mfma_f32_16x16x32_bf16 v[46:49], v[114:117], v[170:173], v[46:49]
	v_mfma_f32_16x16x32_bf16 v[42:45], v[138:141], v[170:173], v[42:45]
	v_mfma_f32_16x16x32_bf16 v[30:33], v[114:117], v[178:181], v[30:33]
	v_mfma_f32_16x16x32_bf16 v[26:29], v[138:141], v[178:181], v[26:29]
	v_mfma_f32_16x16x32_bf16 v[14:17], v[114:117], v[204:207], v[14:17]
	v_mfma_f32_16x16x32_bf16 v[10:13], v[138:141], v[204:207], v[10:13]
	v_mfma_f32_16x16x32_bf16 v[62:65], v[126:129], v[166:169], v[62:65]
	v_mfma_f32_16x16x32_bf16 v[58:61], v[142:145], v[166:169], v[58:61]
	v_mfma_f32_16x16x32_bf16 v[46:49], v[126:129], v[174:177], v[46:49]
	v_mfma_f32_16x16x32_bf16 v[42:45], v[142:145], v[174:177], v[42:45]
	v_mfma_f32_16x16x32_bf16 v[30:33], v[126:129], v[182:185], v[30:33]
	v_mfma_f32_16x16x32_bf16 v[26:29], v[142:145], v[182:185], v[26:29]
	v_mfma_f32_16x16x32_bf16 v[14:17], v[126:129], v[208:211], v[14:17]
	v_mfma_f32_16x16x32_bf16 v[10:13], v[142:145], v[208:211], v[10:13]
	v_mfma_f32_16x16x32_bf16 v[54:57], v[146:149], v[162:165], v[54:57]
	v_mfma_f32_16x16x32_bf16 v[50:53], v[154:157], v[162:165], v[50:53]
	v_mfma_f32_16x16x32_bf16 v[38:41], v[146:149], v[170:173], v[38:41]
	v_mfma_f32_16x16x32_bf16 v[34:37], v[154:157], v[170:173], v[34:37]
	v_mfma_f32_16x16x32_bf16 v[22:25], v[146:149], v[178:181], v[22:25]
	v_mfma_f32_16x16x32_bf16 v[18:21], v[154:157], v[178:181], v[18:21]
	v_mfma_f32_16x16x32_bf16 v[6:9], v[146:149], v[204:207], v[6:9]
	v_mfma_f32_16x16x32_bf16 v[2:5], v[154:157], v[204:207], v[2:5]
	v_mfma_f32_16x16x32_bf16 v[54:57], v[150:153], v[166:169], v[54:57]
	v_mfma_f32_16x16x32_bf16 v[50:53], v[158:161], v[166:169], v[50:53]
	v_mfma_f32_16x16x32_bf16 v[38:41], v[150:153], v[174:177], v[38:41]
	v_mfma_f32_16x16x32_bf16 v[34:37], v[158:161], v[174:177], v[34:37]
	v_mfma_f32_16x16x32_bf16 v[22:25], v[150:153], v[182:185], v[22:25]
	v_mfma_f32_16x16x32_bf16 v[18:21], v[158:161], v[182:185], v[18:21]
	v_mfma_f32_16x16x32_bf16 v[6:9], v[150:153], v[208:211], v[6:9]
	v_mfma_f32_16x16x32_bf16 v[2:5], v[158:161], v[208:211], v[2:5]
	s_barrier
	s_add_u32 s44, s44, 0x100
	s_addc_u32 s45, s45, 0
	s_add_u32 s54, s54, 0x100
	s_addc_u32 s55, s55, 0
	s_cmp_ge_i32 s70, s62
	s_mov_b32 s52, s70
	s_cbranch_scc0 .LBB0_1385
	s_mov_b32 s72, 0x10000
	s_mov_b32 s73, 0x12000
	s_mov_b32 s74, 0x14000
	s_mov_b32 s70, 0x18000
	s_mov_b32 s71, 0x3f317217
	s_and_b64 vcc, exec, s[46:47]
	s_cbranch_vccz .LBB0_1361

; #define PG8_STAGE(bufoff, gbase, voff) do { _Pragma("unroll") for (int _i = 0; _i < 2; ++_i) \
;         __builtin_amdgcn_global_load_lds((const unsigned*)((const char*)(gbase) + (voff)[_i]), (PG8_LAS unsigned*)(lds + (bufoff) + ldsw + _i * 8192), 16, 0, 0); } while (0)
; #define PG8_LDA(dst, b, h) do { _Pragma("unroll") for (int m = 0; m < 4; ++m) _Pragma("unroll") for (int k = 0; k < 2; ++k) dst[m][k] = *(const PG8_LAS bf16x8*)(lds + PG8_SA(b, h) + aoff + m * 2048 + k * 1024); } while (0)
; #define PG8_LDB(dst, b, h) do { _Pragma("unroll") for (int n = 0; n < 2; ++n) _Pragma("unroll") for (int k = 0; k < 2; ++k) dst[n][k] = *(const PG8_LAS bf16x8*)(lds + PG8_SB(b, h) + boff + n * 2048 + k * 1024); } while (0)
; #define PG8_MMA(ai, bj, At, Bt) do { __builtin_amdgcn_s_setprio(1); _Pragma("unroll") for (int m = 0; m < 4; ++m) _Pragma("unroll") for (int n = 0; n < 2; ++n) _Pragma("unroll") for (int k = 0; k < 2; ++k) \
;         acc[ai][bj][m][n] = __builtin_amdgcn_mfma_f32_16x16x32_bf16(Bt[n][k], At[m][k], acc[ai][bj][m][n], 0, 0, 0); __builtin_amdgcn_s_setprio(0); } while (0)
; #define PG8_WAIT_V(n) asm volatile("s_waitcnt vmcnt(" #n ")" ::: "memory")
; #define PG8_BAR __builtin_amdgcn_s_barrier()
; template <class Epi, class Sched, bool ALIGN_EPI = false, bool SP2 = false>
; __device__ __forceinline__ void gemm_phase(PG8_LAS unsigned char* lds, const Gemm g, const Sched& S, const Epi& E, const int wv) {
;     ...
;         for (int t = 0; t < nt; t += 2) {
;             const bool last = (t == nt - 2);
;             const char* a1 = cA + (size_t)(t + 1) * kstep;
;             const char* a2 = last ? nA : cA + (size_t)(t + 2) * kstep; const char* b2 = last ? nB : cB + (size_t)(t + 2) * kstep;
;             const char* a3 = a2 + kstep; const char* b3 = b2 + kstep;
;             if (last && has_next) S.a_ready(nxt);
;             if constexpr (SP2) {
;             PG8_LDB(B0, 0, 0); PG8_LDB(B1, 0, 1); PG8_SCHED; PG8_LDA(At, 0, 0); PG8_STAGE(PG8_SA(1, 1), a1 + hstepA, voffA);
;             PG8_WAIT_V(8); PG8_WAIT_L(0); PG8_BAR; PG8_MMA(0, 0, At, B0); PG8_MMA(0, 1, At, B1); PG8_BAR; PG8_SCHED;
;             PG8_LDA(At, 0, 1); PG8_STAGE(PG8_SB(0, 0), b2, voffB); PG8_STAGE(PG8_SB(0, 1), b2 + hstepB, voffB); PG8_STAGE(PG8_SA(0, 0), a2, voffA);
;             PG8_WAIT_V(8); PG8_WAIT_L(0); PG8_BAR; PG8_MMA(1, 0, At, B0); PG8_MMA(1, 1, At, B1); PG8_BAR; PG8_SCHED;
.LBB0_1495:
	s_add_i32 s52, s46, 2
	s_add_u32 s14, s48, 0x100
	s_addc_u32 s15, s49, 0
	s_cmp_eq_u32 s72, s46
	s_cselect_b32 s47, s11, s15
	s_cselect_b32 s46, s13, s14
	s_cselect_b32 s77, s87, s51
	s_cselect_b32 s76, s86, s35
	ds_read_b128 v[138:141], v192
	ds_read_b128 v[142:145], v192 offset:1024
	ds_read_b128 v[146:149], v192 offset:2048
	ds_read_b128 v[150:153], v192 offset:3072
	ds_read_b128 v[154:157], v193
	ds_read_b128 v[158:161], v193 offset:1024
	ds_read_b128 v[162:165], v193 offset:2048
	ds_read_b128 v[166:169], v193 offset:3072
	s_add_i32 m0, s64, 0xc000
	ds_read_b128 v[194:197], v211
	ds_read_b128 v[198:201], v211 offset:1024
	ds_read_b128 v[202:205], v211 offset:2048
	ds_read_b128 v[214:217], v211 offset:3072
	ds_read_b128 v[228:231], v211 offset:4096
	ds_read_b128 v[232:235], v211 offset:5120
	ds_read_b128 v[236:239], v211 offset:6144
	ds_read_b128 v[240:243], v211 offset:7168
	global_load_lds_dwordx4 v182, s[48:49]
	v_lshl_add_u64 v[190:191], s[48:49], 0, v[184:185]
	s_add_i32 m0, s64, 0xe000
	s_nop 0
	global_load_lds_dwordx4 v[190:191], off
	s_waitcnt vmcnt(8) lgkmcnt(0)
	s_barrier
	v_mfma_f32_16x16x32_bf16 v[118:121], v[138:141], v[194:197], v[118:121]
	v_mfma_f32_16x16x32_bf16 v[46:49], v[146:149], v[194:197], v[46:49]
	v_mfma_f32_16x16x32_bf16 v[110:113], v[138:141], v[202:205], v[110:113]
	v_mfma_f32_16x16x32_bf16 v[38:41], v[146:149], v[202:205], v[38:41]
	v_mfma_f32_16x16x32_bf16 v[134:137], v[138:141], v[228:231], v[134:137]
	v_mfma_f32_16x16x32_bf16 v[62:65], v[146:149], v[228:231], v[62:65]
	v_mfma_f32_16x16x32_bf16 v[130:133], v[138:141], v[236:239], v[130:133]
	v_mfma_f32_16x16x32_bf16 v[58:61], v[146:149], v[236:239], v[58:61]
	v_mfma_f32_16x16x32_bf16 v[118:121], v[142:145], v[198:201], v[118:121]
	v_mfma_f32_16x16x32_bf16 v[46:49], v[150:153], v[198:201], v[46:49]
	v_mfma_f32_16x16x32_bf16 v[110:113], v[142:145], v[214:217], v[110:113]
	v_mfma_f32_16x16x32_bf16 v[38:41], v[150:153], v[214:217], v[38:41]
	v_mfma_f32_16x16x32_bf16 v[134:137], v[142:145], v[232:235], v[134:137]
	v_mfma_f32_16x16x32_bf16 v[62:65], v[150:153], v[232:235], v[62:65]
	v_mfma_f32_16x16x32_bf16 v[130:133], v[142:145], v[240:243], v[130:133]
	v_mfma_f32_16x16x32_bf16 v[58:61], v[150:153], v[240:243], v[58:61]
	v_mfma_f32_16x16x32_bf16 v[114:117], v[154:157], v[194:197], v[114:117]
	v_mfma_f32_16x16x32_bf16 v[42:45], v[162:165], v[194:197], v[42:45]
	v_mfma_f32_16x16x32_bf16 v[106:109], v[154:157], v[202:205], v[106:109]
	v_mfma_f32_16x16x32_bf16 v[34:37], v[162:165], v[202:205], v[34:37]
	v_mfma_f32_16x16x32_bf16 v[126:129], v[154:157], v[228:231], v[126:129]
	v_mfma_f32_16x16x32_bf16 v[54:57], v[162:165], v[228:231], v[54:57]
	v_mfma_f32_16x16x32_bf16 v[122:125], v[154:157], v[236:239], v[122:125]
	v_mfma_f32_16x16x32_bf16 v[50:53], v[162:165], v[236:239], v[50:53]
	v_mfma_f32_16x16x32_bf16 v[114:117], v[158:161], v[198:201], v[114:117]
	v_mfma_f32_16x16x32_bf16 v[42:45], v[166:169], v[198:201], v[42:45]
	v_mfma_f32_16x16x32_bf16 v[106:109], v[158:161], v[214:217], v[106:109]
	v_mfma_f32_16x16x32_bf16 v[34:37], v[166:169], v[214:217], v[34:37]
	v_mfma_f32_16x16x32_bf16 v[126:129], v[158:161], v[232:235], v[126:129]
	v_mfma_f32_16x16x32_bf16 v[54:57], v[166:169], v[232:235], v[54:57]
	v_mfma_f32_16x16x32_bf16 v[122:125], v[158:161], v[240:243], v[122:125]
	v_mfma_f32_16x16x32_bf16 v[50:53], v[166:169], v[240:243], v[50:53]
	s_barrier
	s_add_i32 s48, s63, 0x10000
	s_mov_b32 m0, s48
	ds_read_b128 v[194:197], v211 offset:16384
	ds_read_b128 v[198:201], v211 offset:17408
	ds_read_b128 v[202:205], v211 offset:18432
	ds_read_b128 v[214:217], v211 offset:19456
	ds_read_b128 v[228:231], v211 offset:20480
	ds_read_b128 v[232:235], v211 offset:21504
	ds_read_b128 v[236:239], v211 offset:22528
	ds_read_b128 v[240:243], v211 offset:23552
	global_load_lds_dwordx4 v0, s[76:77]
	s_add_i32 m0, s48, 0x2000
	s_add_u32 s48, s76, s16
	s_addc_u32 s49, s77, s17
	s_add_i32 s53, s63, 0x14000
	global_load_lds_dwordx4 v174, s[76:77]
	s_mov_b32 m0, s53
	global_load_lds_dwordx4 v0, s[48:49]
	s_add_i32 m0, s53, 0x2000
	v_lshl_add_u64 v[246:247], s[46:47], 0, v[170:171]
	global_load_lds_dwordx4 v174, s[48:49]
	s_mov_b32 m0, s64
	v_lshl_add_u64 v[248:249], s[46:47], 0, v[172:173]
	global_load_lds_dwordx4 v[246:247], off
	s_mov_b32 m0, s65
	s_nop 0
	global_load_lds_dwordx4 v[248:249], off
	s_waitcnt vmcnt(8) lgkmcnt(0)
	s_barrier
	v_mfma_f32_16x16x32_bf16 v[86:89], v[138:141], v[194:197], v[86:89]
	v_mfma_f32_16x16x32_bf16 v[14:17], v[146:149], v[194:197], v[14:17]
	v_mfma_f32_16x16x32_bf16 v[70:73], v[138:141], v[202:205], v[70:73]
	v_mfma_f32_16x16x32_bf16 v[6:9], v[146:149], v[202:205], v[6:9]
	v_mfma_f32_16x16x32_bf16 v[102:105], v[138:141], v[228:231], v[102:105]
	v_mfma_f32_16x16x32_bf16 v[30:33], v[146:149], v[228:231], v[30:33]
	v_mfma_f32_16x16x32_bf16 v[98:101], v[138:141], v[236:239], v[98:101]
	v_mfma_f32_16x16x32_bf16 v[26:29], v[146:149], v[236:239], v[26:29]
	v_mfma_f32_16x16x32_bf16 v[86:89], v[142:145], v[198:201], v[86:89]
	v_mfma_f32_16x16x32_bf16 v[14:17], v[150:153], v[198:201], v[14:17]
	v_mfma_f32_16x16x32_bf16 v[70:73], v[142:145], v[214:217], v[70:73]
	v_mfma_f32_16x16x32_bf16 v[6:9], v[150:153], v[214:217], v[6:9]
	v_mfma_f32_16x16x32_bf16 v[102:105], v[142:145], v[232:235], v[102:105]
	v_mfma_f32_16x16x32_bf16 v[30:33], v[150:153], v[232:235], v[30:33]
	v_mfma_f32_16x16x32_bf16 v[98:101], v[142:145], v[240:243], v[98:101]
	v_mfma_f32_16x16x32_bf16 v[26:29], v[150:153], v[240:243], v[26:29]
	v_mfma_f32_16x16x32_bf16 v[82:85], v[154:157], v[194:197], v[82:85]
	v_mfma_f32_16x16x32_bf16 v[10:13], v[162:165], v[194:197], v[10:13]
	v_mfma_f32_16x16x32_bf16 v[66:69], v[154:157], v[202:205], v[66:69]
	v_mfma_f32_16x16x32_bf16 v[2:5], v[162:165], v[202:205], v[2:5]
	v_mfma_f32_16x16x32_bf16 v[94:97], v[154:157], v[228:231], v[94:97]
	v_mfma_f32_16x16x32_bf16 v[22:25], v[162:165], v[228:231], v[22:25]
	v_mfma_f32_16x16x32_bf16 v[90:93], v[154:157], v[236:239], v[90:93]
	v_mfma_f32_16x16x32_bf16 v[18:21], v[162:165], v[236:239], v[18:21]
	v_mfma_f32_16x16x32_bf16 v[82:85], v[158:161], v[198:201], v[82:85]
	v_mfma_f32_16x16x32_bf16 v[10:13], v[166:169], v[198:201], v[10:13]
	v_mfma_f32_16x16x32_bf16 v[66:69], v[158:161], v[214:217], v[66:69]
	v_mfma_f32_16x16x32_bf16 v[2:5], v[166:169], v[214:217], v[2:5]
	v_mfma_f32_16x16x32_bf16 v[94:97], v[158:161], v[232:235], v[94:97]
	v_mfma_f32_16x16x32_bf16 v[22:25], v[166:169], v[232:235], v[22:25]
	v_mfma_f32_16x16x32_bf16 v[90:93], v[158:161], v[240:243], v[90:93]
	v_mfma_f32_16x16x32_bf16 v[18:21], v[166:169], v[240:243], v[18:21]
	s_barrier
; #define PG8_STAGE(bufoff, gbase, voff) do { _Pragma("unroll") for (int _i = 0; _i < 2; ++_i) \
;         __builtin_amdgcn_global_load_lds((const unsigned*)((const char*)(gbase) + (voff)[_i]), (PG8_LAS unsigned*)(lds + (bufoff) + ldsw + _i * 8192), 16, 0, 0); } while (0)
; #define PG8_LDA(dst, b, h) do { _Pragma("unroll") for (int m = 0; m < 4; ++m) _Pragma("unroll") for (int k = 0; k < 2; ++k) dst[m][k] = *(const PG8_LAS bf16x8*)(lds + PG8_SA(b, h) + aoff + m * 2048 + k * 1024); } while (0)
; #define PG8_LDB(dst, b, h) do { _Pragma("unroll") for (int n = 0; n < 2; ++n) _Pragma("unroll") for (int k = 0; k < 2; ++k) dst[n][k] = *(const PG8_LAS bf16x8*)(lds + PG8_SB(b, h) + boff + n * 2048 + k * 1024); } while (0)
; #define PG8_MMA(ai, bj, At, Bt) do { __builtin_amdgcn_s_setprio(1); _Pragma("unroll") for (int m = 0; m < 4; ++m) _Pragma("unroll") for (int n = 0; n < 2; ++n) _Pragma("unroll") for (int k = 0; k < 2; ++k) \
;         acc[ai][bj][m][n] = __builtin_amdgcn_mfma_f32_16x16x32_bf16(Bt[n][k], At[m][k], acc[ai][bj][m][n], 0, 0, 0); __builtin_amdgcn_s_setprio(0); } while (0)
; #define PG8_WAIT_V(n) asm volatile("s_waitcnt vmcnt(" #n ")" ::: "memory")
; #define PG8_WAIT_L(n) asm volatile("s_waitcnt lgkmcnt(" #n ")" ::: "memory")
; #define PG8_BAR __builtin_amdgcn_s_barrier()
; template <class Epi, class Sched, bool ALIGN_EPI = false, bool SP2 = false>
; __device__ __forceinline__ void gemm_phase(PG8_LAS unsigned char* lds, const Gemm g, const Sched& S, const Epi& E, const int wv) {
;     ...
;         for (int t = 0; t < nt; t += 2) {
;             const bool last = (t == nt - 2);
;             const char* a1 = cA + (size_t)(t + 1) * kstep;
;             const char* a2 = last ? nA : cA + (size_t)(t + 2) * kstep; const char* b2 = last ? nB : cB + (size_t)(t + 2) * kstep;
;             const char* a3 = a2 + kstep; const char* b3 = b2 + kstep;
;     ...
;             PG8_LDB(B0, 1, 0); PG8_LDB(B1, 1, 1); PG8_SCHED; PG8_LDA(At, 1, 0); PG8_STAGE(PG8_SA(0, 1), a2 + hstepA, voffA);
;             PG8_WAIT_V(8); PG8_WAIT_L(0); PG8_BAR; PG8_MMA(0, 0, At, B0); PG8_MMA(0, 1, At, B1); PG8_BAR; PG8_SCHED;
;             PG8_LDA(At, 1, 1); PG8_STAGE(PG8_SB(1, 0), b3, voffB); PG8_STAGE(PG8_SB(1, 1), b3 + hstepB, voffB); PG8_STAGE(PG8_SA(1, 0), a3, voffA);
;             PG8_WAIT_V(8); PG8_WAIT_L(0); PG8_BAR; PG8_MMA(1, 0, At, B0); PG8_MMA(1, 1, At, B1); PG8_BAR; PG8_SCHED;
	ds_read_b128 v[138:141], v213
	ds_read_b128 v[142:145], v213 offset:1024
	ds_read_b128 v[146:149], v213 offset:2048
	ds_read_b128 v[150:153], v213 offset:3072
	ds_read_b128 v[154:157], v227
	ds_read_b128 v[158:161], v227 offset:1024
	ds_read_b128 v[162:165], v227 offset:2048
	ds_read_b128 v[166:169], v227 offset:3072
	s_add_u32 s46, s46, 0x80000
	s_addc_u32 s47, s47, 0
	s_mov_b32 m0, s66
	ds_read_b128 v[194:197], v211 offset:32768
	ds_read_b128 v[198:201], v211 offset:33792
	ds_read_b128 v[202:205], v211 offset:34816
	ds_read_b128 v[214:217], v211 offset:35840
	ds_read_b128 v[228:231], v211 offset:36864
	ds_read_b128 v[232:235], v211 offset:37888
	ds_read_b128 v[236:239], v211 offset:38912
	ds_read_b128 v[240:243], v211 offset:39936
	global_load_lds_dwordx4 v170, s[46:47]
	s_mov_b32 m0, s67
	s_nop 0
	global_load_lds_dwordx4 v172, s[46:47]
	s_waitcnt vmcnt(8) lgkmcnt(0)
	s_barrier
	v_mfma_f32_16x16x32_bf16 v[118:121], v[138:141], v[194:197], v[118:121]
	v_mfma_f32_16x16x32_bf16 v[46:49], v[146:149], v[194:197], v[46:49]
	v_mfma_f32_16x16x32_bf16 v[110:113], v[138:141], v[202:205], v[110:113]
	v_mfma_f32_16x16x32_bf16 v[38:41], v[146:149], v[202:205], v[38:41]
	v_mfma_f32_16x16x32_bf16 v[134:137], v[138:141], v[228:231], v[134:137]
	v_mfma_f32_16x16x32_bf16 v[62:65], v[146:149], v[228:231], v[62:65]
	v_mfma_f32_16x16x32_bf16 v[130:133], v[138:141], v[236:239], v[130:133]
	v_mfma_f32_16x16x32_bf16 v[58:61], v[146:149], v[236:239], v[58:61]
	v_mfma_f32_16x16x32_bf16 v[118:121], v[142:145], v[198:201], v[118:121]
	v_mfma_f32_16x16x32_bf16 v[46:49], v[150:153], v[198:201], v[46:49]
	v_mfma_f32_16x16x32_bf16 v[110:113], v[142:145], v[214:217], v[110:113]
	v_mfma_f32_16x16x32_bf16 v[38:41], v[150:153], v[214:217], v[38:41]
	v_mfma_f32_16x16x32_bf16 v[134:137], v[142:145], v[232:235], v[134:137]
	v_mfma_f32_16x16x32_bf16 v[62:65], v[150:153], v[232:235], v[62:65]
	v_mfma_f32_16x16x32_bf16 v[130:133], v[142:145], v[240:243], v[130:133]
	v_mfma_f32_16x16x32_bf16 v[58:61], v[150:153], v[240:243], v[58:61]
	v_mfma_f32_16x16x32_bf16 v[114:117], v[154:157], v[194:197], v[114:117]
	v_mfma_f32_16x16x32_bf16 v[42:45], v[162:165], v[194:197], v[42:45]
	v_mfma_f32_16x16x32_bf16 v[106:109], v[154:157], v[202:205], v[106:109]
	v_mfma_f32_16x16x32_bf16 v[34:37], v[162:165], v[202:205], v[34:37]
	v_mfma_f32_16x16x32_bf16 v[126:129], v[154:157], v[228:231], v[126:129]
	v_mfma_f32_16x16x32_bf16 v[54:57], v[162:165], v[228:231], v[54:57]
	v_mfma_f32_16x16x32_bf16 v[122:125], v[154:157], v[236:239], v[122:125]
	v_mfma_f32_16x16x32_bf16 v[50:53], v[162:165], v[236:239], v[50:53]
	v_mfma_f32_16x16x32_bf16 v[114:117], v[158:161], v[198:201], v[114:117]
	v_mfma_f32_16x16x32_bf16 v[42:45], v[166:169], v[198:201], v[42:45]
	v_mfma_f32_16x16x32_bf16 v[106:109], v[158:161], v[214:217], v[106:109]
	v_mfma_f32_16x16x32_bf16 v[34:37], v[166:169], v[214:217], v[34:37]
	v_mfma_f32_16x16x32_bf16 v[126:129], v[158:161], v[232:235], v[126:129]
	v_mfma_f32_16x16x32_bf16 v[54:57], v[166:169], v[232:235], v[54:57]
	v_mfma_f32_16x16x32_bf16 v[122:125], v[158:161], v[240:243], v[122:125]
	v_mfma_f32_16x16x32_bf16 v[50:53], v[166:169], v[240:243], v[50:53]
	s_barrier
	s_add_i32 s46, s63, 0x18000
	s_add_i32 m0, s46, 0xffffff80
	ds_read_b128 v[194:197], v211 offset:49152
	ds_read_b128 v[198:201], v211 offset:50176
	ds_read_b128 v[202:205], v211 offset:51200
	ds_read_b128 v[214:217], v211 offset:52224
	ds_read_b128 v[228:231], v211 offset:53248
	ds_read_b128 v[232:235], v211 offset:54272
	ds_read_b128 v[236:239], v211 offset:55296
	ds_read_b128 v[240:243], v211 offset:56320
	global_load_lds_dwordx4 v0, s[76:77] offset:128
	s_add_i32 m0, s46, 0x1f80
	s_add_i32 s46, s63, 0x1c000
	global_load_lds_dwordx4 v174, s[76:77] offset:128
	s_add_i32 m0, s46, 0xffffff80
	s_nop 0
	global_load_lds_dwordx4 v0, s[48:49] offset:128
	s_add_i32 m0, s46, 0x1f80
	s_nop 0
	global_load_lds_dwordx4 v174, s[48:49] offset:128
	s_add_i32 m0, s70, 0xffffff80
	s_nop 0
	global_load_lds_dwordx4 v[246:247], off offset:128
	s_add_i32 m0, s71, 0xffffff80
	s_nop 0
	global_load_lds_dwordx4 v[248:249], off offset:128
	s_waitcnt vmcnt(8) lgkmcnt(0)
	s_barrier
	v_mfma_f32_16x16x32_bf16 v[86:89], v[138:141], v[194:197], v[86:89]
	v_mfma_f32_16x16x32_bf16 v[14:17], v[146:149], v[194:197], v[14:17]
	v_mfma_f32_16x16x32_bf16 v[70:73], v[138:141], v[202:205], v[70:73]
	v_mfma_f32_16x16x32_bf16 v[6:9], v[146:149], v[202:205], v[6:9]
	v_mfma_f32_16x16x32_bf16 v[102:105], v[138:141], v[228:231], v[102:105]
	v_mfma_f32_16x16x32_bf16 v[30:33], v[146:149], v[228:231], v[30:33]
	v_mfma_f32_16x16x32_bf16 v[98:101], v[138:141], v[236:239], v[98:101]
	v_mfma_f32_16x16x32_bf16 v[26:29], v[146:149], v[236:239], v[26:29]
	v_mfma_f32_16x16x32_bf16 v[86:89], v[142:145], v[198:201], v[86:89]
	v_mfma_f32_16x16x32_bf16 v[14:17], v[150:153], v[198:201], v[14:17]
	v_mfma_f32_16x16x32_bf16 v[70:73], v[142:145], v[214:217], v[70:73]
	v_mfma_f32_16x16x32_bf16 v[6:9], v[150:153], v[214:217], v[6:9]
	v_mfma_f32_16x16x32_bf16 v[102:105], v[142:145], v[232:235], v[102:105]
	v_mfma_f32_16x16x32_bf16 v[30:33], v[150:153], v[232:235], v[30:33]
	v_mfma_f32_16x16x32_bf16 v[98:101], v[142:145], v[240:243], v[98:101]
	v_mfma_f32_16x16x32_bf16 v[26:29], v[150:153], v[240:243], v[26:29]
	v_mfma_f32_16x16x32_bf16 v[82:85], v[154:157], v[194:197], v[82:85]
	v_mfma_f32_16x16x32_bf16 v[10:13], v[162:165], v[194:197], v[10:13]
	v_mfma_f32_16x16x32_bf16 v[66:69], v[154:157], v[202:205], v[66:69]
	v_mfma_f32_16x16x32_bf16 v[2:5], v[162:165], v[202:205], v[2:5]
	v_mfma_f32_16x16x32_bf16 v[94:97], v[154:157], v[228:231], v[94:97]
	v_mfma_f32_16x16x32_bf16 v[22:25], v[162:165], v[228:231], v[22:25]
	v_mfma_f32_16x16x32_bf16 v[90:93], v[154:157], v[236:239], v[90:93]
	v_mfma_f32_16x16x32_bf16 v[18:21], v[162:165], v[236:239], v[18:21]
	v_mfma_f32_16x16x32_bf16 v[82:85], v[158:161], v[198:201], v[82:85]
	v_mfma_f32_16x16x32_bf16 v[10:13], v[166:169], v[198:201], v[10:13]
	v_mfma_f32_16x16x32_bf16 v[66:69], v[158:161], v[214:217], v[66:69]
	v_mfma_f32_16x16x32_bf16 v[2:5], v[166:169], v[214:217], v[2:5]
	v_mfma_f32_16x16x32_bf16 v[94:97], v[158:161], v[232:235], v[94:97]
	v_mfma_f32_16x16x32_bf16 v[22:25], v[166:169], v[232:235], v[22:25]
	v_mfma_f32_16x16x32_bf16 v[90:93], v[158:161], v[240:243], v[90:93]
	v_mfma_f32_16x16x32_bf16 v[18:21], v[166:169], v[240:243], v[18:21]
	s_barrier
	s_add_u32 s35, s35, 0x100
	s_addc_u32 s51, s51, 0
	s_cmp_ge_i32 s52, s68
	s_mov_b64 s[48:49], s[14:15]
	s_mov_b32 s46, s52
	s_cbranch_scc0 .LBB0_1495
	s_movk_i32 s78, 0x7ff
	s_movk_i32 s76, 0x3000
	s_and_b64 vcc, exec, s[30:31]
	s_cbranch_vccz .LBB0_1470

; #define PG8_STAGE(bufoff, gbase, voff) do { _Pragma("unroll") for (int _i = 0; _i < 2; ++_i) \
;         __builtin_amdgcn_global_load_lds((const unsigned*)((const char*)(gbase) + (voff)[_i]), (PG8_LAS unsigned*)(lds + (bufoff) + ldsw + _i * 8192), 16, 0, 0); } while (0)
; #define PG8_LDA(dst, b, h) do { _Pragma("unroll") for (int m = 0; m < 4; ++m) _Pragma("unroll") for (int k = 0; k < 2; ++k) dst[m][k] = *(const PG8_LAS bf16x8*)(lds + PG8_SA(b, h) + aoff + m * 2048 + k * 1024); } while (0)
; #define PG8_LDB(dst, b, h) do { _Pragma("unroll") for (int n = 0; n < 2; ++n) _Pragma("unroll") for (int k = 0; k < 2; ++k) dst[n][k] = *(const PG8_LAS bf16x8*)(lds + PG8_SB(b, h) + boff + n * 2048 + k * 1024); } while (0)
; #define PG8_MMA(ai, bj, At, Bt) do { __builtin_amdgcn_s_setprio(1); _Pragma("unroll") for (int m = 0; m < 4; ++m) _Pragma("unroll") for (int n = 0; n < 2; ++n) _Pragma("unroll") for (int k = 0; k < 2; ++k) \
;         acc[ai][bj][m][n] = __builtin_amdgcn_mfma_f32_16x16x32_bf16(Bt[n][k], At[m][k], acc[ai][bj][m][n], 0, 0, 0); __builtin_amdgcn_s_setprio(0); } while (0)
; #define PG8_WAIT_V(n) asm volatile("s_waitcnt vmcnt(" #n ")" ::: "memory")
; #define PG8_BAR __builtin_amdgcn_s_barrier()
; template <class Epi, class Sched, bool ALIGN_EPI = false, bool SP2 = false>
; __device__ __forceinline__ void gemm_phase(PG8_LAS unsigned char* lds, const Gemm g, const Sched& S, const Epi& E, const int wv) {
;     ...
;         for (int t = 0; t < nt; t += 2) {
;             const bool last = (t == nt - 2);
;             const char* a1 = cA + (size_t)(t + 1) * kstep;
;             const char* a2 = last ? nA : cA + (size_t)(t + 2) * kstep; const char* b2 = last ? nB : cB + (size_t)(t + 2) * kstep;
;             const char* a3 = a2 + kstep; const char* b3 = b2 + kstep;
;             if (last && has_next) S.a_ready(nxt);
;             if constexpr (SP2) {
;             PG8_LDB(B0, 0, 0); PG8_LDB(B1, 0, 1); PG8_SCHED; PG8_LDA(At, 0, 0); PG8_STAGE(PG8_SA(1, 1), a1 + hstepA, voffA);
;             PG8_WAIT_V(8); PG8_WAIT_L(0); PG8_BAR; PG8_MMA(0, 0, At, B0); PG8_MMA(0, 1, At, B1); PG8_BAR; PG8_SCHED;
;             PG8_LDA(At, 0, 1); PG8_STAGE(PG8_SB(0, 0), b2, voffB); PG8_STAGE(PG8_SB(0, 1), b2 + hstepB, voffB); PG8_STAGE(PG8_SA(0, 0), a2, voffA);
;             PG8_WAIT_V(8); PG8_WAIT_L(0); PG8_BAR; PG8_MMA(1, 0, At, B0); PG8_MMA(1, 1, At, B1); PG8_BAR; PG8_SCHED;
.LBB0_1676:
	s_add_i32 s67, s44, 2
	s_add_u32 s34, s30, 0x100
	s_addc_u32 s35, s31, 0
	s_cmp_eq_u32 s59, s44
	s_cselect_b32 s45, s13, s35
	s_cselect_b32 s44, s12, s34
	s_cselect_b32 s69, s15, s66
	s_cselect_b32 s68, s14, s65
	ds_read_b128 v[114:117], v197
	ds_read_b128 v[126:129], v197 offset:1024
	ds_read_b128 v[138:141], v197 offset:2048
	ds_read_b128 v[142:145], v197 offset:3072
	ds_read_b128 v[146:149], v201
	ds_read_b128 v[150:153], v201 offset:1024
	ds_read_b128 v[154:157], v201 offset:2048
	ds_read_b128 v[158:161], v201 offset:3072
	s_add_i32 m0, s52, 0xc000
	ds_read_b128 v[162:165], v235
	ds_read_b128 v[166:169], v235 offset:1024
	ds_read_b128 v[170:173], v235 offset:2048
	ds_read_b128 v[174:177], v235 offset:3072
	ds_read_b128 v[178:181], v235 offset:4096
	ds_read_b128 v[182:185], v235 offset:5120
	ds_read_b128 v[204:207], v235 offset:6144
	ds_read_b128 v[208:211], v235 offset:7168
	global_load_lds_dwordx4 v200, s[30:31]
	s_add_i32 m0, s52, 0xe000
	s_nop 0
	global_load_lds_dwordx4 v202, s[30:31]
	s_waitcnt vmcnt(8) lgkmcnt(0)
	s_barrier
	v_mfma_f32_16x16x32_bf16 v[134:137], v[114:117], v[162:165], v[134:137]
	v_mfma_f32_16x16x32_bf16 v[130:133], v[138:141], v[162:165], v[130:133]
	v_mfma_f32_16x16x32_bf16 v[110:113], v[114:117], v[170:173], v[110:113]
	v_mfma_f32_16x16x32_bf16 v[106:109], v[138:141], v[170:173], v[106:109]
	v_mfma_f32_16x16x32_bf16 v[94:97], v[114:117], v[178:181], v[94:97]
	v_mfma_f32_16x16x32_bf16 v[90:93], v[138:141], v[178:181], v[90:93]
	v_mfma_f32_16x16x32_bf16 v[78:81], v[114:117], v[204:207], v[78:81]
	v_mfma_f32_16x16x32_bf16 v[74:77], v[138:141], v[204:207], v[74:77]
	v_mfma_f32_16x16x32_bf16 v[134:137], v[126:129], v[166:169], v[134:137]
	v_mfma_f32_16x16x32_bf16 v[130:133], v[142:145], v[166:169], v[130:133]
	v_mfma_f32_16x16x32_bf16 v[110:113], v[126:129], v[174:177], v[110:113]
	v_mfma_f32_16x16x32_bf16 v[106:109], v[142:145], v[174:177], v[106:109]
	v_mfma_f32_16x16x32_bf16 v[94:97], v[126:129], v[182:185], v[94:97]
	v_mfma_f32_16x16x32_bf16 v[90:93], v[142:145], v[182:185], v[90:93]
	v_mfma_f32_16x16x32_bf16 v[78:81], v[126:129], v[208:211], v[78:81]
	v_mfma_f32_16x16x32_bf16 v[74:77], v[142:145], v[208:211], v[74:77]
	v_mfma_f32_16x16x32_bf16 v[122:125], v[146:149], v[162:165], v[122:125]
	v_mfma_f32_16x16x32_bf16 v[118:121], v[154:157], v[162:165], v[118:121]
	v_mfma_f32_16x16x32_bf16 v[102:105], v[146:149], v[170:173], v[102:105]
	v_mfma_f32_16x16x32_bf16 v[98:101], v[154:157], v[170:173], v[98:101]
	v_mfma_f32_16x16x32_bf16 v[86:89], v[146:149], v[178:181], v[86:89]
	v_mfma_f32_16x16x32_bf16 v[82:85], v[154:157], v[178:181], v[82:85]
	v_mfma_f32_16x16x32_bf16 v[70:73], v[146:149], v[204:207], v[70:73]
	v_mfma_f32_16x16x32_bf16 v[66:69], v[154:157], v[204:207], v[66:69]
	v_mfma_f32_16x16x32_bf16 v[122:125], v[150:153], v[166:169], v[122:125]
	v_mfma_f32_16x16x32_bf16 v[118:121], v[158:161], v[166:169], v[118:121]
	v_mfma_f32_16x16x32_bf16 v[102:105], v[150:153], v[174:177], v[102:105]
	v_mfma_f32_16x16x32_bf16 v[98:101], v[158:161], v[174:177], v[98:101]
	v_mfma_f32_16x16x32_bf16 v[86:89], v[150:153], v[182:185], v[86:89]
	v_mfma_f32_16x16x32_bf16 v[82:85], v[158:161], v[182:185], v[82:85]
	v_mfma_f32_16x16x32_bf16 v[70:73], v[150:153], v[208:211], v[70:73]
	v_mfma_f32_16x16x32_bf16 v[66:69], v[158:161], v[208:211], v[66:69]
	s_barrier
	s_add_i32 s30, s47, 0x10000
	v_lshl_add_u64 v[190:191], s[68:69], 0, v[0:1]
	s_mov_b32 m0, s30
	ds_read_b128 v[162:165], v235 offset:16384
	ds_read_b128 v[166:169], v235 offset:17408
	ds_read_b128 v[170:173], v235 offset:18432
	ds_read_b128 v[174:177], v235 offset:19456
	ds_read_b128 v[178:181], v235 offset:20480
	ds_read_b128 v[182:185], v235 offset:21504
	ds_read_b128 v[204:207], v235 offset:22528
	ds_read_b128 v[208:211], v235 offset:23552
	global_load_lds_dwordx4 v[190:191], off
	s_add_i32 m0, s30, 0x2000
	s_add_u32 s30, s68, s2
	v_lshl_add_u64 v[192:193], s[68:69], 0, v[198:199]
	s_addc_u32 s31, s69, s3
	s_add_i32 s68, s47, 0x14000
	global_load_lds_dwordx4 v[192:193], off
	v_lshl_add_u64 v[212:213], s[30:31], 0, v[0:1]
	s_mov_b32 m0, s68
	v_lshl_add_u64 v[214:215], s[30:31], 0, v[198:199]
	global_load_lds_dwordx4 v[212:213], off
	s_add_i32 m0, s68, 0x2000
	global_load_lds_dwordx4 v[214:215], off
	s_mov_b32 m0, s52
	global_load_lds_dwordx4 v194, s[44:45]
	s_mov_b32 m0, s53
	s_nop 0
	global_load_lds_dwordx4 v196, s[44:45]
	s_waitcnt vmcnt(8) lgkmcnt(0)
	s_barrier
	v_mfma_f32_16x16x32_bf16 v[62:65], v[114:117], v[162:165], v[62:65]
	v_mfma_f32_16x16x32_bf16 v[58:61], v[138:141], v[162:165], v[58:61]
	v_mfma_f32_16x16x32_bf16 v[46:49], v[114:117], v[170:173], v[46:49]
	v_mfma_f32_16x16x32_bf16 v[42:45], v[138:141], v[170:173], v[42:45]
	v_mfma_f32_16x16x32_bf16 v[30:33], v[114:117], v[178:181], v[30:33]
	v_mfma_f32_16x16x32_bf16 v[26:29], v[138:141], v[178:181], v[26:29]
	v_mfma_f32_16x16x32_bf16 v[14:17], v[114:117], v[204:207], v[14:17]
	v_mfma_f32_16x16x32_bf16 v[10:13], v[138:141], v[204:207], v[10:13]
	v_mfma_f32_16x16x32_bf16 v[62:65], v[126:129], v[166:169], v[62:65]
	v_mfma_f32_16x16x32_bf16 v[58:61], v[142:145], v[166:169], v[58:61]
	v_mfma_f32_16x16x32_bf16 v[46:49], v[126:129], v[174:177], v[46:49]
	v_mfma_f32_16x16x32_bf16 v[42:45], v[142:145], v[174:177], v[42:45]
	v_mfma_f32_16x16x32_bf16 v[30:33], v[126:129], v[182:185], v[30:33]
	v_mfma_f32_16x16x32_bf16 v[26:29], v[142:145], v[182:185], v[26:29]
	v_mfma_f32_16x16x32_bf16 v[14:17], v[126:129], v[208:211], v[14:17]
	v_mfma_f32_16x16x32_bf16 v[10:13], v[142:145], v[208:211], v[10:13]
	v_mfma_f32_16x16x32_bf16 v[54:57], v[146:149], v[162:165], v[54:57]
	v_mfma_f32_16x16x32_bf16 v[50:53], v[154:157], v[162:165], v[50:53]
	v_mfma_f32_16x16x32_bf16 v[38:41], v[146:149], v[170:173], v[38:41]
	v_mfma_f32_16x16x32_bf16 v[34:37], v[154:157], v[170:173], v[34:37]
	v_mfma_f32_16x16x32_bf16 v[22:25], v[146:149], v[178:181], v[22:25]
	v_mfma_f32_16x16x32_bf16 v[18:21], v[154:157], v[178:181], v[18:21]
	v_mfma_f32_16x16x32_bf16 v[6:9], v[146:149], v[204:207], v[6:9]
	v_mfma_f32_16x16x32_bf16 v[2:5], v[154:157], v[204:207], v[2:5]
	v_mfma_f32_16x16x32_bf16 v[54:57], v[150:153], v[166:169], v[54:57]
	v_mfma_f32_16x16x32_bf16 v[50:53], v[158:161], v[166:169], v[50:53]
	v_mfma_f32_16x16x32_bf16 v[38:41], v[150:153], v[174:177], v[38:41]
	v_mfma_f32_16x16x32_bf16 v[34:37], v[158:161], v[174:177], v[34:37]
	v_mfma_f32_16x16x32_bf16 v[22:25], v[150:153], v[182:185], v[22:25]
	v_mfma_f32_16x16x32_bf16 v[18:21], v[158:161], v[182:185], v[18:21]
	v_mfma_f32_16x16x32_bf16 v[6:9], v[150:153], v[208:211], v[6:9]
	v_mfma_f32_16x16x32_bf16 v[2:5], v[158:161], v[208:211], v[2:5]
	s_barrier
; #define PG8_STAGE(bufoff, gbase, voff) do { _Pragma("unroll") for (int _i = 0; _i < 2; ++_i) \
;         __builtin_amdgcn_global_load_lds((const unsigned*)((const char*)(gbase) + (voff)[_i]), (PG8_LAS unsigned*)(lds + (bufoff) + ldsw + _i * 8192), 16, 0, 0); } while (0)
; #define PG8_LDA(dst, b, h) do { _Pragma("unroll") for (int m = 0; m < 4; ++m) _Pragma("unroll") for (int k = 0; k < 2; ++k) dst[m][k] = *(const PG8_LAS bf16x8*)(lds + PG8_SA(b, h) + aoff + m * 2048 + k * 1024); } while (0)
; #define PG8_LDB(dst, b, h) do { _Pragma("unroll") for (int n = 0; n < 2; ++n) _Pragma("unroll") for (int k = 0; k < 2; ++k) dst[n][k] = *(const PG8_LAS bf16x8*)(lds + PG8_SB(b, h) + boff + n * 2048 + k * 1024); } while (0)
; #define PG8_MMA(ai, bj, At, Bt) do { __builtin_amdgcn_s_setprio(1); _Pragma("unroll") for (int m = 0; m < 4; ++m) _Pragma("unroll") for (int n = 0; n < 2; ++n) _Pragma("unroll") for (int k = 0; k < 2; ++k) \
;         acc[ai][bj][m][n] = __builtin_amdgcn_mfma_f32_16x16x32_bf16(Bt[n][k], At[m][k], acc[ai][bj][m][n], 0, 0, 0); __builtin_amdgcn_s_setprio(0); } while (0)
; #define PG8_WAIT_V(n) asm volatile("s_waitcnt vmcnt(" #n ")" ::: "memory")
; #define PG8_WAIT_L(n) asm volatile("s_waitcnt lgkmcnt(" #n ")" ::: "memory")
; #define PG8_BAR __builtin_amdgcn_s_barrier()
; template <class Epi, class Sched, bool ALIGN_EPI = false, bool SP2 = false>
; __device__ __forceinline__ void gemm_phase(PG8_LAS unsigned char* lds, const Gemm g, const Sched& S, const Epi& E, const int wv) {
;     ...
;         for (int t = 0; t < nt; t += 2) {
;             const bool last = (t == nt - 2);
;             const char* a1 = cA + (size_t)(t + 1) * kstep;
;             const char* a2 = last ? nA : cA + (size_t)(t + 2) * kstep; const char* b2 = last ? nB : cB + (size_t)(t + 2) * kstep;
;             const char* a3 = a2 + kstep; const char* b3 = b2 + kstep;
;     ...
;             PG8_LDB(B0, 1, 0); PG8_LDB(B1, 1, 1); PG8_SCHED; PG8_LDA(At, 1, 0); PG8_STAGE(PG8_SA(0, 1), a2 + hstepA, voffA);
;             PG8_WAIT_V(8); PG8_WAIT_L(0); PG8_BAR; PG8_MMA(0, 0, At, B0); PG8_MMA(0, 1, At, B1); PG8_BAR; PG8_SCHED;
;             PG8_LDA(At, 1, 1); PG8_STAGE(PG8_SB(1, 0), b3, voffB); PG8_STAGE(PG8_SB(1, 1), b3 + hstepB, voffB); PG8_STAGE(PG8_SA(1, 0), a3, voffA);
;             PG8_WAIT_V(8); PG8_WAIT_L(0); PG8_BAR; PG8_MMA(1, 0, At, B0); PG8_MMA(1, 1, At, B1); PG8_BAR; PG8_SCHED;
	ds_read_b128 v[114:117], v203
	ds_read_b128 v[126:129], v203 offset:1024
	ds_read_b128 v[138:141], v203 offset:2048
	ds_read_b128 v[142:145], v203 offset:3072
	ds_read_b128 v[146:149], v216
	ds_read_b128 v[150:153], v216 offset:1024
	ds_read_b128 v[154:157], v216 offset:2048
	ds_read_b128 v[158:161], v216 offset:3072
	s_add_u32 s30, s44, 0x180000
	s_addc_u32 s31, s45, 0
	s_mov_b32 m0, s54
	ds_read_b128 v[162:165], v235 offset:32768
	ds_read_b128 v[166:169], v235 offset:33792
	ds_read_b128 v[170:173], v235 offset:34816
	ds_read_b128 v[174:177], v235 offset:35840
	ds_read_b128 v[178:181], v235 offset:36864
	ds_read_b128 v[182:185], v235 offset:37888
	ds_read_b128 v[204:207], v235 offset:38912
	ds_read_b128 v[208:211], v235 offset:39936
	global_load_lds_dwordx4 v194, s[30:31]
	s_mov_b32 m0, s55
	s_nop 0
	global_load_lds_dwordx4 v196, s[30:31]
	s_waitcnt vmcnt(8) lgkmcnt(0)
	s_barrier
	v_mfma_f32_16x16x32_bf16 v[134:137], v[114:117], v[162:165], v[134:137]
	v_mfma_f32_16x16x32_bf16 v[130:133], v[138:141], v[162:165], v[130:133]
	v_mfma_f32_16x16x32_bf16 v[110:113], v[114:117], v[170:173], v[110:113]
	v_mfma_f32_16x16x32_bf16 v[106:109], v[138:141], v[170:173], v[106:109]
	v_mfma_f32_16x16x32_bf16 v[94:97], v[114:117], v[178:181], v[94:97]
	v_mfma_f32_16x16x32_bf16 v[90:93], v[138:141], v[178:181], v[90:93]
	v_mfma_f32_16x16x32_bf16 v[78:81], v[114:117], v[204:207], v[78:81]
	v_mfma_f32_16x16x32_bf16 v[74:77], v[138:141], v[204:207], v[74:77]
	v_mfma_f32_16x16x32_bf16 v[134:137], v[126:129], v[166:169], v[134:137]
	v_mfma_f32_16x16x32_bf16 v[130:133], v[142:145], v[166:169], v[130:133]
	v_mfma_f32_16x16x32_bf16 v[110:113], v[126:129], v[174:177], v[110:113]
	v_mfma_f32_16x16x32_bf16 v[106:109], v[142:145], v[174:177], v[106:109]
	v_mfma_f32_16x16x32_bf16 v[94:97], v[126:129], v[182:185], v[94:97]
	v_mfma_f32_16x16x32_bf16 v[90:93], v[142:145], v[182:185], v[90:93]
	v_mfma_f32_16x16x32_bf16 v[78:81], v[126:129], v[208:211], v[78:81]
	v_mfma_f32_16x16x32_bf16 v[74:77], v[142:145], v[208:211], v[74:77]
	v_mfma_f32_16x16x32_bf16 v[122:125], v[146:149], v[162:165], v[122:125]
	v_mfma_f32_16x16x32_bf16 v[118:121], v[154:157], v[162:165], v[118:121]
	v_mfma_f32_16x16x32_bf16 v[102:105], v[146:149], v[170:173], v[102:105]
	v_mfma_f32_16x16x32_bf16 v[98:101], v[154:157], v[170:173], v[98:101]
	v_mfma_f32_16x16x32_bf16 v[86:89], v[146:149], v[178:181], v[86:89]
	v_mfma_f32_16x16x32_bf16 v[82:85], v[154:157], v[178:181], v[82:85]
	v_mfma_f32_16x16x32_bf16 v[70:73], v[146:149], v[204:207], v[70:73]
	v_mfma_f32_16x16x32_bf16 v[66:69], v[154:157], v[204:207], v[66:69]
	v_mfma_f32_16x16x32_bf16 v[122:125], v[150:153], v[166:169], v[122:125]
	v_mfma_f32_16x16x32_bf16 v[118:121], v[158:161], v[166:169], v[118:121]
	v_mfma_f32_16x16x32_bf16 v[102:105], v[150:153], v[174:177], v[102:105]
	v_mfma_f32_16x16x32_bf16 v[98:101], v[158:161], v[174:177], v[98:101]
	v_mfma_f32_16x16x32_bf16 v[86:89], v[150:153], v[182:185], v[86:89]
	v_mfma_f32_16x16x32_bf16 v[82:85], v[158:161], v[182:185], v[82:85]
	v_mfma_f32_16x16x32_bf16 v[70:73], v[150:153], v[208:211], v[70:73]
	v_mfma_f32_16x16x32_bf16 v[66:69], v[158:161], v[208:211], v[66:69]
	s_barrier
	s_add_i32 s30, s47, 0x18000
	s_add_i32 m0, s30, 0xffffff80
	ds_read_b128 v[162:165], v235 offset:49152
	ds_read_b128 v[166:169], v235 offset:50176
	ds_read_b128 v[170:173], v235 offset:51200
	ds_read_b128 v[174:177], v235 offset:52224
	ds_read_b128 v[178:181], v235 offset:53248
	ds_read_b128 v[182:185], v235 offset:54272
	ds_read_b128 v[204:207], v235 offset:55296
	ds_read_b128 v[208:211], v235 offset:56320
	global_load_lds_dwordx4 v[190:191], off offset:128
	s_add_i32 m0, s30, 0x1f80
	s_add_i32 s30, s47, 0x1c000
	global_load_lds_dwordx4 v[192:193], off offset:128
	s_add_i32 m0, s30, 0xffffff80
	s_nop 0
	global_load_lds_dwordx4 v[212:213], off offset:128
	s_add_i32 m0, s30, 0x1f80
	s_nop 0
	global_load_lds_dwordx4 v[214:215], off offset:128
	s_add_i32 m0, s57, 0xffffff80
	s_nop 0
	global_load_lds_dwordx4 v194, s[44:45] offset:128
	s_add_i32 m0, s58, 0xffffff80
	s_nop 0
	global_load_lds_dwordx4 v196, s[44:45] offset:128
	s_waitcnt vmcnt(8) lgkmcnt(0)
	s_barrier
	v_mfma_f32_16x16x32_bf16 v[62:65], v[114:117], v[162:165], v[62:65]
	v_mfma_f32_16x16x32_bf16 v[58:61], v[138:141], v[162:165], v[58:61]
	v_mfma_f32_16x16x32_bf16 v[46:49], v[114:117], v[170:173], v[46:49]
	v_mfma_f32_16x16x32_bf16 v[42:45], v[138:141], v[170:173], v[42:45]
	v_mfma_f32_16x16x32_bf16 v[30:33], v[114:117], v[178:181], v[30:33]
	v_mfma_f32_16x16x32_bf16 v[26:29], v[138:141], v[178:181], v[26:29]
	v_mfma_f32_16x16x32_bf16 v[14:17], v[114:117], v[204:207], v[14:17]
	v_mfma_f32_16x16x32_bf16 v[10:13], v[138:141], v[204:207], v[10:13]
	v_mfma_f32_16x16x32_bf16 v[62:65], v[126:129], v[166:169], v[62:65]
	v_mfma_f32_16x16x32_bf16 v[58:61], v[142:145], v[166:169], v[58:61]
	v_mfma_f32_16x16x32_bf16 v[46:49], v[126:129], v[174:177], v[46:49]
	v_mfma_f32_16x16x32_bf16 v[42:45], v[142:145], v[174:177], v[42:45]
	v_mfma_f32_16x16x32_bf16 v[30:33], v[126:129], v[182:185], v[30:33]
	v_mfma_f32_16x16x32_bf16 v[26:29], v[142:145], v[182:185], v[26:29]
	v_mfma_f32_16x16x32_bf16 v[14:17], v[126:129], v[208:211], v[14:17]
	v_mfma_f32_16x16x32_bf16 v[10:13], v[142:145], v[208:211], v[10:13]
	v_mfma_f32_16x16x32_bf16 v[54:57], v[146:149], v[162:165], v[54:57]
	v_mfma_f32_16x16x32_bf16 v[50:53], v[154:157], v[162:165], v[50:53]
	v_mfma_f32_16x16x32_bf16 v[38:41], v[146:149], v[170:173], v[38:41]
	v_mfma_f32_16x16x32_bf16 v[34:37], v[154:157], v[170:173], v[34:37]
	v_mfma_f32_16x16x32_bf16 v[22:25], v[146:149], v[178:181], v[22:25]
	v_mfma_f32_16x16x32_bf16 v[18:21], v[154:157], v[178:181], v[18:21]
	v_mfma_f32_16x16x32_bf16 v[6:9], v[146:149], v[204:207], v[6:9]
	v_mfma_f32_16x16x32_bf16 v[2:5], v[154:157], v[204:207], v[2:5]
	v_mfma_f32_16x16x32_bf16 v[54:57], v[150:153], v[166:169], v[54:57]
	v_mfma_f32_16x16x32_bf16 v[50:53], v[158:161], v[166:169], v[50:53]
	v_mfma_f32_16x16x32_bf16 v[38:41], v[150:153], v[174:177], v[38:41]
	v_mfma_f32_16x16x32_bf16 v[34:37], v[158:161], v[174:177], v[34:37]
	v_mfma_f32_16x16x32_bf16 v[22:25], v[150:153], v[182:185], v[22:25]
	v_mfma_f32_16x16x32_bf16 v[18:21], v[158:161], v[182:185], v[18:21]
	v_mfma_f32_16x16x32_bf16 v[6:9], v[150:153], v[208:211], v[6:9]
	v_mfma_f32_16x16x32_bf16 v[2:5], v[158:161], v[208:211], v[2:5]
	s_barrier
	s_add_u32 s65, s65, 0x100
	s_addc_u32 s66, s66, 0
	s_cmp_ge_i32 s67, s56
	s_mov_b64 s[30:31], s[34:35]
	s_mov_b32 s44, s67
	s_cbranch_scc0 .LBB0_1676
	s_movk_i32 s68, 0x4000
	s_movk_i32 s69, 0x6000
	s_mov_b32 s70, 0x18000
	s_mov_b32 s71, 0x3f317217
	s_and_b64 vcc, exec, s[28:29]
	s_cbranch_vccz .LBB0_1652
